# GEMM main loops: M0 write moved before the address add of the second LDS-DMA load of each pair, s_nop 0 dropped (40 sites)
# speedup vs baseline: 1.0079x; 1.0035x over previous
; #define PG8_STAGE(bufoff, gbase, voff) do { _Pragma("unroll") for (int _i = 0; _i < 2; ++_i) \
;         __builtin_amdgcn_global_load_lds((const unsigned*)((const char*)(gbase) + (voff)[_i]), (LAS unsigned*)(lds + (bufoff) + ldsw + _i * 8192), 16, 0, 0); } while (0)
; #define PG8_LDA(dst, b, h) do { _Pragma("unroll") for (int m = 0; m < 4; ++m) _Pragma("unroll") for (int k = 0; k < 2; ++k) dst[m][k] = *(const LAS bf16x8*)(lds + PG8_SA(b, h) + aoff + m * 2048 + k * 1024); } while (0)
; #define PG8_LDB(dst, b, h) do { _Pragma("unroll") for (int n = 0; n < 2; ++n) _Pragma("unroll") for (int k = 0; k < 2; ++k) dst[n][k] = *(const LAS bf16x8*)(lds + PG8_SB(b, h) + boff + n * 2048 + k * 1024); } while (0)
; #define PG8_MMA(ai, bj, At, Bt) do { __builtin_amdgcn_s_setprio(1); _Pragma("unroll") for (int m = 0; m < 4; ++m) _Pragma("unroll") for (int n = 0; n < 2; ++n) _Pragma("unroll") for (int k = 0; k < 2; ++k) \
;         acc[ai][bj][m][n] = __builtin_amdgcn_mfma_f32_16x16x32_bf16(Bt[n][k], At[m][k], acc[ai][bj][m][n], 0, 0, 0); __builtin_amdgcn_s_setprio(0); } while (0)
; #define PG8_WAIT_L(n) asm volatile("s_waitcnt lgkmcnt(" #n ")" ::: "memory")
; #define PG8_BAR __builtin_amdgcn_s_barrier()
; #define PG8_SCHED __builtin_amdgcn_sched_barrier(0)
; template <class Epi>
; __device__ __forceinline__ void gemm_phase(const int TID, const int BID, LAS unsigned char* lds, const Gemm g, const StaticOrder& S, const Epi& E) {
;     ...
;         for (int t = 0; t < nt; t += 2) {
;             const bool last = (t == nt - 2);
;             const char* a1 = cA + (size_t)(t + 1) * kstep;
;             const char* a2 = last ? nA : cA + (size_t)(t + 2) * kstep; const char* b2 = last ? nB : cB + (size_t)(t + 2) * kstep;
;             const char* a3 = a2 + kstep; const char* b3 = b2 + kstep;
;             PG8_LDB(B0, 0, 0); PG8_SCHED; PG8_LDA(At, 0, 0); PG8_STAGE(PG8_SA(1, 1), a1 + hstepA, voffA);
;             PG8_WAIT_L(8); PG8_BAR; PG8_WAIT_L(0); PG8_MMA(0, 0, At, B0); PG8_BAR; PG8_SCHED;
;             PG8_LDB(B1, 0, 1); PG8_STAGE(PG8_SB(0, 0), b2, voffB);
;             PG8_BAR; PG8_WAIT_L(0); PG8_MMA(0, 1, At, B1); PG8_BAR;
;             PG8_LDA(At, 0, 1); PG8_STAGE(PG8_SA(0, 0), a2, voffA);
;             PG8_BAR; PG8_WAIT_L(0); PG8_MMA(1, 0, At, B0); PG8_BAR; PG8_SCHED;
.LBB0_799:
	v_add_u32_e32 v173, s23, v170
	ds_read_b128 v[138:141], v173
	ds_read_b128 v[142:145], v173 offset:1024
	ds_read_b128 v[174:177], v173 offset:2048
	ds_read_b128 v[178:181], v173 offset:3072
	s_add_u32 s26, s24, 0xfff80080
	s_addc_u32 s27, s25, -1
	s_cmp_eq_u32 s56, 28
	s_cselect_b32 s29, s17, s27
	s_cselect_b32 s28, s52, s26
	s_cselect_b32 s27, s15, s55
	s_cselect_b32 s26, s53, s54
	v_lshl_add_u64 v[200:201], s[24:25], 0, v[134:135]
	s_add_i32 m0, s35, 0xc000
	ds_read_b128 v[182:185], v172
	ds_read_b128 v[196:199], v172 offset:1024
	ds_read_b128 v[208:211], v172 offset:2048
	ds_read_b128 v[212:215], v172 offset:3072
	ds_read_b128 v[216:219], v172 offset:4096
	ds_read_b128 v[220:223], v172 offset:5120
	ds_read_b128 v[224:227], v172 offset:6144
	ds_read_b128 v[228:231], v172 offset:7168
	global_load_lds_dwordx4 v[200:201], off
	s_add_i32 m0, s35, 0xe000
	v_lshl_add_u64 v[200:201], s[24:25], 0, v[136:137]
	global_load_lds_dwordx4 v[200:201], off
	s_waitcnt lgkmcnt(8)
	s_barrier
	s_waitcnt lgkmcnt(0)
	s_setprio 1
	v_mfma_f32_16x16x32_bf16 v[124:127], v[138:141], v[182:185], v[124:127]
	v_mfma_f32_16x16x32_bf16 v[120:123], v[174:177], v[182:185], v[120:123]
	v_mfma_f32_16x16x32_bf16 v[108:111], v[138:141], v[208:211], v[108:111]
	v_mfma_f32_16x16x32_bf16 v[104:107], v[174:177], v[208:211], v[104:107]
	v_mfma_f32_16x16x32_bf16 v[92:95], v[138:141], v[216:219], v[92:95]
	v_mfma_f32_16x16x32_bf16 v[88:91], v[174:177], v[216:219], v[88:91]
	v_mfma_f32_16x16x32_bf16 v[76:79], v[138:141], v[224:227], v[76:79]
	v_mfma_f32_16x16x32_bf16 v[72:75], v[174:177], v[224:227], v[72:75]
	v_mfma_f32_16x16x32_bf16 v[124:127], v[142:145], v[196:199], v[124:127]
	v_mfma_f32_16x16x32_bf16 v[120:123], v[178:181], v[196:199], v[120:123]
	v_mfma_f32_16x16x32_bf16 v[108:111], v[142:145], v[212:215], v[108:111]
	v_mfma_f32_16x16x32_bf16 v[104:107], v[178:181], v[212:215], v[104:107]
	v_mfma_f32_16x16x32_bf16 v[92:95], v[142:145], v[220:223], v[92:95]
	v_mfma_f32_16x16x32_bf16 v[88:91], v[178:181], v[220:223], v[88:91]
	v_mfma_f32_16x16x32_bf16 v[76:79], v[142:145], v[228:231], v[76:79]
	v_mfma_f32_16x16x32_bf16 v[72:75], v[178:181], v[228:231], v[72:75]
	s_setprio 0
	s_barrier
	s_mov_b32 m0, s31
	v_add_u32_e32 v173, s37, v170
	v_lshl_add_u64 v[200:201], s[26:27], 0, v[160:161]
	ds_read_b128 v[232:235], v173
	ds_read_b128 v[236:239], v173 offset:1024
	ds_read_b128 v[240:243], v173 offset:2048
	ds_read_b128 v[244:247], v173 offset:3072
	global_load_lds_dwordx4 v[200:201], off
	s_mov_b32 m0, s34
	v_lshl_add_u64 v[248:249], s[26:27], 0, v[132:133]
	global_load_lds_dwordx4 v[248:249], off
	s_barrier
	s_waitcnt lgkmcnt(0)
	s_setprio 1
	v_mfma_f32_16x16x32_bf16 v[116:119], v[232:235], v[182:185], v[116:119]
	v_mfma_f32_16x16x32_bf16 v[112:115], v[240:243], v[182:185], v[112:115]
	v_mfma_f32_16x16x32_bf16 v[100:103], v[232:235], v[208:211], v[100:103]
	v_mfma_f32_16x16x32_bf16 v[96:99], v[240:243], v[208:211], v[96:99]
	v_mfma_f32_16x16x32_bf16 v[84:87], v[232:235], v[216:219], v[84:87]
	v_mfma_f32_16x16x32_bf16 v[80:83], v[240:243], v[216:219], v[80:83]
	v_mfma_f32_16x16x32_bf16 v[68:71], v[232:235], v[224:227], v[68:71]
	v_mfma_f32_16x16x32_bf16 v[64:67], v[240:243], v[224:227], v[64:67]
	v_mfma_f32_16x16x32_bf16 v[116:119], v[236:239], v[196:199], v[116:119]
	v_mfma_f32_16x16x32_bf16 v[112:115], v[244:247], v[196:199], v[112:115]
	v_mfma_f32_16x16x32_bf16 v[100:103], v[236:239], v[212:215], v[100:103]
	v_mfma_f32_16x16x32_bf16 v[96:99], v[244:247], v[212:215], v[96:99]
	v_mfma_f32_16x16x32_bf16 v[84:87], v[236:239], v[220:223], v[84:87]
	v_mfma_f32_16x16x32_bf16 v[80:83], v[244:247], v[220:223], v[80:83]
	v_mfma_f32_16x16x32_bf16 v[68:71], v[236:239], v[228:231], v[68:71]
	v_mfma_f32_16x16x32_bf16 v[64:67], v[244:247], v[228:231], v[64:67]
	s_setprio 0
	s_mov_b32 m0, s35
	v_lshl_add_u64 v[250:251], s[28:29], 0, v[128:129]
	s_barrier
	ds_read_b128 v[182:185], v172 offset:16384
	ds_read_b128 v[196:199], v172 offset:17408
	ds_read_b128 v[208:211], v172 offset:18432
	ds_read_b128 v[212:215], v172 offset:19456
	ds_read_b128 v[216:219], v172 offset:20480
	ds_read_b128 v[220:223], v172 offset:21504
	ds_read_b128 v[224:227], v172 offset:22528
	ds_read_b128 v[228:231], v172 offset:23552
	global_load_lds_dwordx4 v[250:251], off
	s_mov_b32 m0, s36
	v_lshl_add_u64 v[252:253], s[28:29], 0, v[130:131]
	global_load_lds_dwordx4 v[252:253], off
	s_barrier
	s_waitcnt lgkmcnt(0)
	s_setprio 1
	v_mfma_f32_16x16x32_bf16 v[60:63], v[138:141], v[182:185], v[60:63]
	v_mfma_f32_16x16x32_bf16 v[56:59], v[174:177], v[182:185], v[56:59]
	v_mfma_f32_16x16x32_bf16 v[44:47], v[138:141], v[208:211], v[44:47]
	v_mfma_f32_16x16x32_bf16 v[40:43], v[174:177], v[208:211], v[40:43]
	v_mfma_f32_16x16x32_bf16 v[28:31], v[138:141], v[216:219], v[28:31]
	v_mfma_f32_16x16x32_bf16 v[24:27], v[174:177], v[216:219], v[24:27]
	v_mfma_f32_16x16x32_bf16 v[12:15], v[138:141], v[224:227], v[12:15]
	v_mfma_f32_16x16x32_bf16 v[8:11], v[174:177], v[224:227], v[8:11]
	v_mfma_f32_16x16x32_bf16 v[60:63], v[142:145], v[196:199], v[60:63]
	v_mfma_f32_16x16x32_bf16 v[56:59], v[178:181], v[196:199], v[56:59]
	v_mfma_f32_16x16x32_bf16 v[44:47], v[142:145], v[212:215], v[44:47]
	v_mfma_f32_16x16x32_bf16 v[40:43], v[178:181], v[212:215], v[40:43]
	v_mfma_f32_16x16x32_bf16 v[28:31], v[142:145], v[220:223], v[28:31]
	v_mfma_f32_16x16x32_bf16 v[24:27], v[178:181], v[220:223], v[24:27]
	v_mfma_f32_16x16x32_bf16 v[12:15], v[142:145], v[228:231], v[12:15]
	v_mfma_f32_16x16x32_bf16 v[8:11], v[178:181], v[228:231], v[8:11]
	s_setprio 0
	s_barrier
; #define PG8_STAGE(bufoff, gbase, voff) do { _Pragma("unroll") for (int _i = 0; _i < 2; ++_i) \
;         __builtin_amdgcn_global_load_lds((const unsigned*)((const char*)(gbase) + (voff)[_i]), (LAS unsigned*)(lds + (bufoff) + ldsw + _i * 8192), 16, 0, 0); } while (0)
; #define PG8_LDA(dst, b, h) do { _Pragma("unroll") for (int m = 0; m < 4; ++m) _Pragma("unroll") for (int k = 0; k < 2; ++k) dst[m][k] = *(const LAS bf16x8*)(lds + PG8_SA(b, h) + aoff + m * 2048 + k * 1024); } while (0)
; #define PG8_LDB(dst, b, h) do { _Pragma("unroll") for (int n = 0; n < 2; ++n) _Pragma("unroll") for (int k = 0; k < 2; ++k) dst[n][k] = *(const LAS bf16x8*)(lds + PG8_SB(b, h) + boff + n * 2048 + k * 1024); } while (0)
; #define PG8_MMA(ai, bj, At, Bt) do { __builtin_amdgcn_s_setprio(1); _Pragma("unroll") for (int m = 0; m < 4; ++m) _Pragma("unroll") for (int n = 0; n < 2; ++n) _Pragma("unroll") for (int k = 0; k < 2; ++k) \
;         acc[ai][bj][m][n] = __builtin_amdgcn_mfma_f32_16x16x32_bf16(Bt[n][k], At[m][k], acc[ai][bj][m][n], 0, 0, 0); __builtin_amdgcn_s_setprio(0); } while (0)
; #define PG8_WAIT_V(n) asm volatile("s_waitcnt vmcnt(" #n ")" ::: "memory")
; #define PG8_WAIT_L(n) asm volatile("s_waitcnt lgkmcnt(" #n ")" ::: "memory")
; #define PG8_BAR __builtin_amdgcn_s_barrier()
; #define PG8_SCHED __builtin_amdgcn_sched_barrier(0)
; template <class Epi>
; __device__ __forceinline__ void gemm_phase(const int TID, const int BID, LAS unsigned char* lds, const Gemm g, const StaticOrder& S, const Epi& E) {
;     ...
;             PG8_STAGE(PG8_SB(0, 1), b2 + hstepB, voffB);
;             PG8_WAIT_V(6); PG8_BAR; PG8_MMA(1, 1, At, B1); PG8_BAR;
;             PG8_LDB(B0, 1, 0); PG8_SCHED; PG8_LDA(At, 1, 0); PG8_STAGE(PG8_SA(0, 1), a2 + hstepA, voffA);
;             PG8_WAIT_L(8); PG8_BAR; PG8_WAIT_L(0); PG8_MMA(0, 0, At, B0); PG8_BAR; PG8_SCHED;
;             PG8_LDB(B1, 1, 1); PG8_STAGE(PG8_SB(1, 0), b3, voffB);
;             PG8_BAR; PG8_WAIT_L(0); PG8_MMA(0, 1, At, B1); PG8_BAR;
	s_add_u32 s58, s26, 0x80000
	s_addc_u32 s59, s27, 0
	s_mov_b32 m0, s38
	v_lshl_add_u64 v[138:139], s[58:59], 0, v[160:161]
	global_load_lds_dwordx4 v[138:139], off
	s_mov_b32 m0, s39
	v_lshl_add_u64 v[138:139], s[58:59], 0, v[132:133]
	global_load_lds_dwordx4 v[138:139], off
	s_waitcnt vmcnt(6)
	s_barrier
	s_setprio 1
	v_mfma_f32_16x16x32_bf16 v[52:55], v[232:235], v[182:185], v[52:55]
	v_mfma_f32_16x16x32_bf16 v[48:51], v[240:243], v[182:185], v[48:51]
	v_mfma_f32_16x16x32_bf16 v[36:39], v[232:235], v[208:211], v[36:39]
	v_mfma_f32_16x16x32_bf16 v[32:35], v[240:243], v[208:211], v[32:35]
	v_mfma_f32_16x16x32_bf16 v[20:23], v[232:235], v[216:219], v[20:23]
	v_mfma_f32_16x16x32_bf16 v[16:19], v[240:243], v[216:219], v[16:19]
	v_mfma_f32_16x16x32_bf16 v[4:7], v[232:235], v[224:227], v[4:7]
	v_mfma_f32_16x16x32_bf16 v[0:3], v[240:243], v[224:227], v[0:3]
	v_mfma_f32_16x16x32_bf16 v[52:55], v[236:239], v[196:199], v[52:55]
	v_mfma_f32_16x16x32_bf16 v[48:51], v[244:247], v[196:199], v[48:51]
	v_mfma_f32_16x16x32_bf16 v[36:39], v[236:239], v[212:215], v[36:39]
	v_mfma_f32_16x16x32_bf16 v[32:35], v[244:247], v[212:215], v[32:35]
	v_mfma_f32_16x16x32_bf16 v[20:23], v[236:239], v[220:223], v[20:23]
	v_mfma_f32_16x16x32_bf16 v[16:19], v[244:247], v[220:223], v[16:19]
	v_mfma_f32_16x16x32_bf16 v[4:7], v[236:239], v[228:231], v[4:7]
	v_mfma_f32_16x16x32_bf16 v[0:3], v[244:247], v[228:231], v[0:3]
	s_setprio 0
	v_add_u32_e32 v173, s42, v170
	s_barrier
	ds_read_b128 v[138:141], v173
	ds_read_b128 v[142:145], v173 offset:1024
	ds_read_b128 v[174:177], v173 offset:2048
	ds_read_b128 v[178:181], v173 offset:3072
	s_add_u32 s28, s28, 0x80000
	s_addc_u32 s29, s29, 0
	s_mov_b32 m0, s40
	v_lshl_add_u64 v[232:233], s[28:29], 0, v[128:129]
	ds_read_b128 v[182:185], v172 offset:32768
	ds_read_b128 v[196:199], v172 offset:33792
	ds_read_b128 v[208:211], v172 offset:34816
	ds_read_b128 v[212:215], v172 offset:35840
	ds_read_b128 v[216:219], v172 offset:36864
	ds_read_b128 v[220:223], v172 offset:37888
	ds_read_b128 v[224:227], v172 offset:38912
	ds_read_b128 v[228:231], v172 offset:39936
	global_load_lds_dwordx4 v[232:233], off
	s_mov_b32 m0, s41
	v_lshl_add_u64 v[232:233], s[28:29], 0, v[130:131]
	global_load_lds_dwordx4 v[232:233], off
	s_waitcnt lgkmcnt(8)
	s_barrier
	s_waitcnt lgkmcnt(0)
	s_setprio 1
	v_mfma_f32_16x16x32_bf16 v[124:127], v[138:141], v[182:185], v[124:127]
	v_mfma_f32_16x16x32_bf16 v[120:123], v[174:177], v[182:185], v[120:123]
	v_mfma_f32_16x16x32_bf16 v[108:111], v[138:141], v[208:211], v[108:111]
	v_mfma_f32_16x16x32_bf16 v[104:107], v[174:177], v[208:211], v[104:107]
	v_mfma_f32_16x16x32_bf16 v[92:95], v[138:141], v[216:219], v[92:95]
	v_mfma_f32_16x16x32_bf16 v[88:91], v[174:177], v[216:219], v[88:91]
	v_mfma_f32_16x16x32_bf16 v[76:79], v[138:141], v[224:227], v[76:79]
	v_mfma_f32_16x16x32_bf16 v[72:75], v[174:177], v[224:227], v[72:75]
	v_mfma_f32_16x16x32_bf16 v[124:127], v[142:145], v[196:199], v[124:127]
	v_mfma_f32_16x16x32_bf16 v[120:123], v[178:181], v[196:199], v[120:123]
	v_mfma_f32_16x16x32_bf16 v[108:111], v[142:145], v[212:215], v[108:111]
	v_mfma_f32_16x16x32_bf16 v[104:107], v[178:181], v[212:215], v[104:107]
	v_mfma_f32_16x16x32_bf16 v[92:95], v[142:145], v[220:223], v[92:95]
	v_mfma_f32_16x16x32_bf16 v[88:91], v[178:181], v[220:223], v[88:91]
	v_mfma_f32_16x16x32_bf16 v[76:79], v[142:145], v[228:231], v[76:79]
	v_mfma_f32_16x16x32_bf16 v[72:75], v[178:181], v[228:231], v[72:75]
	s_setprio 0
	s_barrier
	s_mov_b32 m0, s43
	v_add_u32_e32 v173, s47, v170
	v_lshl_add_u64 v[200:201], v[200:201], 0, s[90:91]
	ds_read_b128 v[232:235], v173
	ds_read_b128 v[236:239], v173 offset:1024
	ds_read_b128 v[240:243], v173 offset:2048
	ds_read_b128 v[244:247], v173 offset:3072
	global_load_lds_dwordx4 v[200:201], off
	s_mov_b32 m0, s44
	v_lshl_add_u64 v[200:201], v[248:249], 0, s[90:91]
	global_load_lds_dwordx4 v[200:201], off
	s_barrier
	s_waitcnt lgkmcnt(0)
	s_setprio 1
	v_mfma_f32_16x16x32_bf16 v[116:119], v[232:235], v[182:185], v[116:119]
	v_mfma_f32_16x16x32_bf16 v[112:115], v[240:243], v[182:185], v[112:115]
	v_mfma_f32_16x16x32_bf16 v[100:103], v[232:235], v[208:211], v[100:103]
	v_mfma_f32_16x16x32_bf16 v[96:99], v[240:243], v[208:211], v[96:99]
	v_mfma_f32_16x16x32_bf16 v[84:87], v[232:235], v[216:219], v[84:87]
	v_mfma_f32_16x16x32_bf16 v[80:83], v[240:243], v[216:219], v[80:83]
	v_mfma_f32_16x16x32_bf16 v[68:71], v[232:235], v[224:227], v[68:71]
	v_mfma_f32_16x16x32_bf16 v[64:67], v[240:243], v[224:227], v[64:67]
	v_mfma_f32_16x16x32_bf16 v[116:119], v[236:239], v[196:199], v[116:119]
	v_mfma_f32_16x16x32_bf16 v[112:115], v[244:247], v[196:199], v[112:115]
	v_mfma_f32_16x16x32_bf16 v[100:103], v[236:239], v[212:215], v[100:103]
	v_mfma_f32_16x16x32_bf16 v[96:99], v[244:247], v[212:215], v[96:99]
	v_mfma_f32_16x16x32_bf16 v[84:87], v[236:239], v[220:223], v[84:87]
	v_mfma_f32_16x16x32_bf16 v[80:83], v[244:247], v[220:223], v[80:83]
	v_mfma_f32_16x16x32_bf16 v[68:71], v[236:239], v[228:231], v[68:71]
	v_mfma_f32_16x16x32_bf16 v[64:67], v[244:247], v[228:231], v[64:67]
	s_setprio 0
	s_mov_b32 m0, s45
	v_lshl_add_u64 v[200:201], v[250:251], 0, s[90:91]
	s_barrier
	ds_read_b128 v[182:185], v172 offset:49152
	ds_read_b128 v[196:199], v172 offset:50176
	ds_read_b128 v[208:211], v172 offset:51200
	ds_read_b128 v[212:215], v172 offset:52224
	ds_read_b128 v[216:219], v172 offset:53248
	ds_read_b128 v[220:223], v172 offset:54272
	ds_read_b128 v[224:227], v172 offset:55296
	ds_read_b128 v[228:231], v172 offset:56320
	global_load_lds_dwordx4 v[200:201], off
	s_mov_b32 m0, s46
	v_lshl_add_u64 v[200:201], v[252:253], 0, s[90:91]
	global_load_lds_dwordx4 v[200:201], off
	s_barrier
; __device__ __forceinline__ unsigned cvt_pk_bf16(float lo, float hi) { unsigned r; asm volatile("v_cvt_pk_bf16_f32 %0, %1, %2" : "=v"(r) : "v"(lo), "v"(hi)); return r; }
; __device__ __forceinline__ float rinv_st(stat_t s, float invn) { return rsqrtf((float)((double)s * (1.0 / 4294967296.0)) * invn + 1e-6f); }
; #define PG8_STAGE(bufoff, gbase, voff) do { _Pragma("unroll") for (int _i = 0; _i < 2; ++_i) \
;         __builtin_amdgcn_global_load_lds((const unsigned*)((const char*)(gbase) + (voff)[_i]), (LAS unsigned*)(lds + (bufoff) + ldsw + _i * 8192), 16, 0, 0); } while (0)
; #define PG8_LDA(dst, b, h) do { _Pragma("unroll") for (int m = 0; m < 4; ++m) _Pragma("unroll") for (int k = 0; k < 2; ++k) dst[m][k] = *(const LAS bf16x8*)(lds + PG8_SA(b, h) + aoff + m * 2048 + k * 1024); } while (0)
; #define PG8_WAIT_V(n) asm volatile("s_waitcnt vmcnt(" #n ")" ::: "memory")
; #define PG8_BAR __builtin_amdgcn_s_barrier()
; template <class Epi>
; __device__ __forceinline__ void gemm_phase(const int TID, const int BID, LAS unsigned char* lds, const Gemm g, const StaticOrder& S, const Epi& E) {
;     ...
;             PG8_BAR; PG8_WAIT_L(0); PG8_MMA(0, 1, At, B1); PG8_BAR;
;             PG8_LDA(At, 1, 1); PG8_STAGE(PG8_SA(1, 0), a3, voffA);
;             PG8_BAR; PG8_WAIT_L(0); PG8_MMA(1, 0, At, B0); PG8_BAR; PG8_SCHED;
;             PG8_STAGE(PG8_SB(1, 1), b3 + hstepB, voffB);
;             PG8_WAIT_V(6); PG8_BAR; PG8_MMA(1, 1, At, B1); PG8_BAR;
;     __device__ __forceinline__ void operator()(const f32x4 (&acc)[2][2][4][2], const Unit& u, int wr, int wc, int fr, int fq) const {
;         const int row0 = u.pm * BM + wr * 64 + fr, col0 = u.pn * BM + wc * 32 + 8 * fq;
; #pragma unroll
;         for (int ai = 0; ai < 2; ++ai)
; #pragma unroll
;             for (int m = 0; m < 4; ++m) {
;                 const int row = row0 + ai * HALF + m * 16; const float r = rinv_st(stats[row], 1.0f / 2048.0f);
;                 bf16_t* rowp = raw + (size_t)row * NINP + col0;
; #pragma unroll
;                 for (int bj = 0; bj < 2; ++bj) {
;                     const f32x4 v0 = acc[ai][bj][m][0] * r, v1 = acc[ai][bj][m][1] * r;
;                     u32x4 w; w.x = cvt_pk_bf16(v0[0], v0[1]); w.y = cvt_pk_bf16(v0[2], v0[3]); w.z = cvt_pk_bf16(v1[0], v1[1]); w.w = cvt_pk_bf16(v1[2], v1[3]);
;                     *(u32x4*)(rowp + bj * HALF) = w;
;                 }
	s_waitcnt lgkmcnt(0)
	s_setprio 1
	v_mfma_f32_16x16x32_bf16 v[60:63], v[138:141], v[182:185], v[60:63]
	v_mfma_f32_16x16x32_bf16 v[56:59], v[174:177], v[182:185], v[56:59]
	v_mfma_f32_16x16x32_bf16 v[44:47], v[138:141], v[208:211], v[44:47]
	v_mfma_f32_16x16x32_bf16 v[40:43], v[174:177], v[208:211], v[40:43]
	v_mfma_f32_16x16x32_bf16 v[28:31], v[138:141], v[216:219], v[28:31]
	v_mfma_f32_16x16x32_bf16 v[24:27], v[174:177], v[216:219], v[24:27]
	v_mfma_f32_16x16x32_bf16 v[12:15], v[138:141], v[224:227], v[12:15]
	v_mfma_f32_16x16x32_bf16 v[8:11], v[174:177], v[224:227], v[8:11]
	v_mfma_f32_16x16x32_bf16 v[60:63], v[142:145], v[196:199], v[60:63]
	v_mfma_f32_16x16x32_bf16 v[56:59], v[178:181], v[196:199], v[56:59]
	v_mfma_f32_16x16x32_bf16 v[44:47], v[142:145], v[212:215], v[44:47]
	v_mfma_f32_16x16x32_bf16 v[40:43], v[178:181], v[212:215], v[40:43]
	v_mfma_f32_16x16x32_bf16 v[28:31], v[142:145], v[220:223], v[28:31]
	v_mfma_f32_16x16x32_bf16 v[24:27], v[178:181], v[220:223], v[24:27]
	v_mfma_f32_16x16x32_bf16 v[12:15], v[142:145], v[228:231], v[12:15]
	v_mfma_f32_16x16x32_bf16 v[8:11], v[178:181], v[228:231], v[8:11]
	s_setprio 0
	s_barrier
	s_add_u32 s26, s26, 0x80080
	s_addc_u32 s27, s27, 0
	s_mov_b32 m0, s48
	v_lshl_add_u64 v[138:139], s[26:27], 0, v[160:161]
	global_load_lds_dwordx4 v[138:139], off
	s_mov_b32 m0, s49
	v_lshl_add_u64 v[138:139], s[26:27], 0, v[132:133]
	global_load_lds_dwordx4 v[138:139], off
	s_waitcnt vmcnt(6)
	s_barrier
	s_setprio 1
	v_mfma_f32_16x16x32_bf16 v[52:55], v[232:235], v[182:185], v[52:55]
	v_mfma_f32_16x16x32_bf16 v[48:51], v[240:243], v[182:185], v[48:51]
	v_mfma_f32_16x16x32_bf16 v[36:39], v[232:235], v[208:211], v[36:39]
	v_mfma_f32_16x16x32_bf16 v[32:35], v[240:243], v[208:211], v[32:35]
	v_mfma_f32_16x16x32_bf16 v[20:23], v[232:235], v[216:219], v[20:23]
	v_mfma_f32_16x16x32_bf16 v[16:19], v[240:243], v[216:219], v[16:19]
	v_mfma_f32_16x16x32_bf16 v[4:7], v[232:235], v[224:227], v[4:7]
	v_mfma_f32_16x16x32_bf16 v[0:3], v[240:243], v[224:227], v[0:3]
	v_mfma_f32_16x16x32_bf16 v[52:55], v[236:239], v[196:199], v[52:55]
	v_mfma_f32_16x16x32_bf16 v[48:51], v[244:247], v[196:199], v[48:51]
	v_mfma_f32_16x16x32_bf16 v[36:39], v[236:239], v[212:215], v[36:39]
	v_mfma_f32_16x16x32_bf16 v[32:35], v[244:247], v[212:215], v[32:35]
	v_mfma_f32_16x16x32_bf16 v[20:23], v[236:239], v[220:223], v[20:23]
	v_mfma_f32_16x16x32_bf16 v[16:19], v[244:247], v[220:223], v[16:19]
	v_mfma_f32_16x16x32_bf16 v[4:7], v[236:239], v[228:231], v[4:7]
	v_mfma_f32_16x16x32_bf16 v[0:3], v[244:247], v[228:231], v[0:3]
	s_setprio 0
	s_add_i32 s56, s56, 2
	s_add_u32 s24, s24, 0x100
	s_addc_u32 s25, s25, 0
	s_add_u32 s54, s54, 0x100
	s_addc_u32 s55, s55, 0
	s_cmp_gt_u32 s56, 29
	s_barrier
	s_cbranch_scc0 .LBB0_799
	v_lshl_add_u32 v138, s22, 8, v169
	v_ashrrev_i32_e32 v139, 31, v138
	v_lshl_add_u64 v[140:141], v[138:139], 3, s[10:11]
	global_load_dwordx2 v[142:143], v[140:141], off
	global_load_dwordx2 v[208:209], v[140:141], off offset:128
	global_load_dwordx2 v[210:211], v[140:141], off offset:256
	global_load_dwordx2 v[212:213], v[140:141], off offset:384
	global_load_dwordx2 v[214:215], v[140:141], off offset:1024
	global_load_dwordx2 v[216:217], v[140:141], off offset:1152
	global_load_dwordx2 v[218:219], v[140:141], off offset:1280
	global_load_dwordx2 v[220:221], v[140:141], off offset:1408
	v_lshl_or_b32 v144, s51, 8, v171
	v_ashrrev_i32_e32 v145, 31, v144
	s_movk_i32 s15, 0x2200
	v_lshlrev_b64 v[144:145], 1, v[144:145]
	s_mov_b32 s51, s14
	s_mov_b32 s22, s16
	s_mov_b64 s[26:27], s[20:21]
	s_waitcnt vmcnt(0)
	v_cvt_f64_u32_e32 v[174:175], v143
	v_ldexp_f64 v[174:175], v[174:175], 32
	v_cvt_f64_u32_e32 v[142:143], v142
	v_add_f64 v[142:143], v[174:175], v[142:143]
	v_ldexp_f64 v[142:143], v[142:143], s93
	v_cvt_f32_f64_e32 v139, v[142:143]
	v_fmamk_f32 v139, v139, 0x3a000000, v189
	v_cmp_gt_f32_e32 vcc, s78, v139
	v_mul_f32_e32 v142, 0x4b800000, v139
	s_nop 0
	v_cndmask_b32_e32 v139, v139, v142, vcc
	v_rsq_f32_e32 v139, v139
	s_nop 0
	v_mul_f32_e32 v142, 0x45800000, v139
	v_cndmask_b32_e32 v174, v139, v142, vcc
	v_mov_b64_e32 v[142:143], s[12:13]
	v_mad_i64_i32 v[176:177], s[24:25], v138, s15, v[142:143]
	v_lshl_add_u64 v[176:177], v[176:177], 0, v[144:145]
	v_pk_mul_f32 v[126:127], v[126:127], v[174:175] op_sel_hi:[1,0]
	v_pk_mul_f32 v[124:125], v[124:125], v[174:175] op_sel_hi:[1,0]
	v_pk_mul_f32 v[178:179], v[122:123], v[174:175] op_sel_hi:[1,0]
	v_pk_mul_f32 v[122:123], v[120:121], v[174:175] op_sel_hi:[1,0]
	v_cvt_pk_bf16_f32 v120, v124, v125
	v_cvt_pk_bf16_f32 v121, v126, v127
	v_pk_mul_f32 v[116:117], v[116:117], v[174:175] op_sel_hi:[1,0]
	v_cvt_pk_bf16_f32 v122, v122, v123
	v_cvt_pk_bf16_f32 v123, v178, v179
	global_store_dwordx4 v[176:177], v[120:123], off
	v_pk_mul_f32 v[118:119], v[118:119], v[174:175] op_sel_hi:[1,0]
	s_nop 0
	v_pk_mul_f32 v[120:121], v[114:115], v[174:175] op_sel_hi:[1,0]
	v_pk_mul_f32 v[114:115], v[112:113], v[174:175] op_sel_hi:[1,0]
	v_cvt_pk_bf16_f32 v112, v116, v117
	v_cvt_pk_bf16_f32 v113, v118, v119
	s_nop 0
	v_cvt_pk_bf16_f32 v114, v114, v115
	v_cvt_pk_bf16_f32 v115, v120, v121
	global_store_dwordx4 v[176:177], v[112:115], off offset:256
	s_nop 1
	v_or_b32_e32 v112, 16, v138
	v_ashrrev_i32_e32 v113, 31, v112
	v_lshl_add_u64 v[114:115], v[112:113], 3, s[10:11]
	s_nop 1
	v_mov_b64_e32 v[114:115], v[208:209]
	v_cvt_f64_u32_e32 v[116:117], v115
	v_ldexp_f64 v[116:117], v[116:117], 32
	v_cvt_f64_u32_e32 v[114:115], v114
	v_add_f64 v[114:115], v[116:117], v[114:115]
	v_ldexp_f64 v[114:115], v[114:115], s93
	v_cvt_f32_f64_e32 v113, v[114:115]
	v_fmamk_f32 v113, v113, 0x3a000000, v189
; __device__ __forceinline__ unsigned cvt_pk_bf16(float lo, float hi) { unsigned r; asm volatile("v_cvt_pk_bf16_f32 %0, %1, %2" : "=v"(r) : "v"(lo), "v"(hi)); return r; }
; __device__ __forceinline__ float rinv_st(stat_t s, float invn) { return rsqrtf((float)((double)s * (1.0 / 4294967296.0)) * invn + 1e-6f); }
;     __device__ __forceinline__ void operator()(const f32x4 (&acc)[2][2][4][2], const Unit& u, int wr, int wc, int fr, int fq) const {
;     ...
;         for (int ai = 0; ai < 2; ++ai)
; #pragma unroll
;             for (int m = 0; m < 4; ++m) {
;                 const int row = row0 + ai * HALF + m * 16; const float r = rinv_st(stats[row], 1.0f / 2048.0f);
;                 bf16_t* rowp = raw + (size_t)row * NINP + col0;
; #pragma unroll
;                 for (int bj = 0; bj < 2; ++bj) {
;                     const f32x4 v0 = acc[ai][bj][m][0] * r, v1 = acc[ai][bj][m][1] * r;
;                     u32x4 w; w.x = cvt_pk_bf16(v0[0], v0[1]); w.y = cvt_pk_bf16(v0[2], v0[3]); w.z = cvt_pk_bf16(v1[0], v1[1]); w.w = cvt_pk_bf16(v1[2], v1[3]);
;                     *(u32x4*)(rowp + bj * HALF) = w;
;                 }
;             }
	v_cmp_gt_f32_e32 vcc, s78, v113
	v_mul_f32_e32 v114, 0x4b800000, v113
	s_nop 0
	v_cndmask_b32_e32 v113, v113, v114, vcc
	v_rsq_f32_e32 v113, v113
	s_nop 0
	v_mul_f32_e32 v114, 0x45800000, v113
	v_cndmask_b32_e32 v114, v113, v114, vcc
	v_mad_i64_i32 v[112:113], s[24:25], v112, s15, v[142:143]
	v_lshl_add_u64 v[112:113], v[112:113], 0, v[144:145]
	v_pk_mul_f32 v[110:111], v[110:111], v[114:115] op_sel_hi:[1,0]
	v_pk_mul_f32 v[108:109], v[108:109], v[114:115] op_sel_hi:[1,0]
	v_pk_mul_f32 v[116:117], v[106:107], v[114:115] op_sel_hi:[1,0]
	v_pk_mul_f32 v[106:107], v[104:105], v[114:115] op_sel_hi:[1,0]
	v_cvt_pk_bf16_f32 v104, v108, v109
	v_cvt_pk_bf16_f32 v105, v110, v111
	v_pk_mul_f32 v[100:101], v[100:101], v[114:115] op_sel_hi:[1,0]
	v_cvt_pk_bf16_f32 v106, v106, v107
	v_cvt_pk_bf16_f32 v107, v116, v117
	global_store_dwordx4 v[112:113], v[104:107], off
	v_pk_mul_f32 v[102:103], v[102:103], v[114:115] op_sel_hi:[1,0]
	s_nop 0
	v_pk_mul_f32 v[104:105], v[98:99], v[114:115] op_sel_hi:[1,0]
	v_pk_mul_f32 v[98:99], v[96:97], v[114:115] op_sel_hi:[1,0]
	v_cvt_pk_bf16_f32 v96, v100, v101
	v_cvt_pk_bf16_f32 v97, v102, v103
	s_nop 0
	v_cvt_pk_bf16_f32 v98, v98, v99
	v_cvt_pk_bf16_f32 v99, v104, v105
	global_store_dwordx4 v[112:113], v[96:99], off offset:256
	s_nop 1
	v_or_b32_e32 v96, 32, v138
	v_ashrrev_i32_e32 v97, 31, v96
	v_lshl_add_u64 v[98:99], v[96:97], 3, s[10:11]
	s_nop 1
	v_mov_b64_e32 v[98:99], v[210:211]
	v_cvt_f64_u32_e32 v[100:101], v99
	v_ldexp_f64 v[100:101], v[100:101], 32
	v_cvt_f64_u32_e32 v[98:99], v98
	v_add_f64 v[98:99], v[100:101], v[98:99]
	v_ldexp_f64 v[98:99], v[98:99], s93
	v_cvt_f32_f64_e32 v97, v[98:99]
	v_fmamk_f32 v97, v97, 0x3a000000, v189
	v_cmp_gt_f32_e32 vcc, s78, v97
	v_mul_f32_e32 v98, 0x4b800000, v97
	s_nop 0
	v_cndmask_b32_e32 v97, v97, v98, vcc
	v_rsq_f32_e32 v97, v97
	s_nop 0
	v_mul_f32_e32 v98, 0x45800000, v97
	v_cndmask_b32_e32 v98, v97, v98, vcc
	v_mad_i64_i32 v[96:97], s[24:25], v96, s15, v[142:143]
	v_lshl_add_u64 v[96:97], v[96:97], 0, v[144:145]
	v_pk_mul_f32 v[94:95], v[94:95], v[98:99] op_sel_hi:[1,0]
	v_pk_mul_f32 v[92:93], v[92:93], v[98:99] op_sel_hi:[1,0]
	v_pk_mul_f32 v[100:101], v[90:91], v[98:99] op_sel_hi:[1,0]
	v_pk_mul_f32 v[90:91], v[88:89], v[98:99] op_sel_hi:[1,0]
	v_cvt_pk_bf16_f32 v88, v92, v93
	v_cvt_pk_bf16_f32 v89, v94, v95
	v_pk_mul_f32 v[84:85], v[84:85], v[98:99] op_sel_hi:[1,0]
	v_cvt_pk_bf16_f32 v90, v90, v91
	v_cvt_pk_bf16_f32 v91, v100, v101
	global_store_dwordx4 v[96:97], v[88:91], off
	v_pk_mul_f32 v[86:87], v[86:87], v[98:99] op_sel_hi:[1,0]
	s_nop 0
	v_pk_mul_f32 v[88:89], v[82:83], v[98:99] op_sel_hi:[1,0]
	v_pk_mul_f32 v[82:83], v[80:81], v[98:99] op_sel_hi:[1,0]
	v_cvt_pk_bf16_f32 v80, v84, v85
	v_cvt_pk_bf16_f32 v81, v86, v87
	s_nop 0
	v_cvt_pk_bf16_f32 v82, v82, v83
	v_cvt_pk_bf16_f32 v83, v88, v89
	global_store_dwordx4 v[96:97], v[80:83], off offset:256
	s_nop 1
	v_or_b32_e32 v80, 48, v138
	v_ashrrev_i32_e32 v81, 31, v80
	v_lshl_add_u64 v[82:83], v[80:81], 3, s[10:11]
	s_nop 1
	v_mov_b64_e32 v[82:83], v[212:213]
	v_cvt_f64_u32_e32 v[84:85], v83
	v_ldexp_f64 v[84:85], v[84:85], 32
	v_cvt_f64_u32_e32 v[82:83], v82
	v_add_f64 v[82:83], v[84:85], v[82:83]
	v_ldexp_f64 v[82:83], v[82:83], s93
	v_cvt_f32_f64_e32 v81, v[82:83]
	v_fmamk_f32 v81, v81, 0x3a000000, v189
	v_cmp_gt_f32_e32 vcc, s78, v81
	v_mul_f32_e32 v82, 0x4b800000, v81
	s_nop 0
	v_cndmask_b32_e32 v81, v81, v82, vcc
	v_rsq_f32_e32 v81, v81
	s_nop 0
	v_mul_f32_e32 v82, 0x45800000, v81
	v_cndmask_b32_e32 v82, v81, v82, vcc
	v_mad_i64_i32 v[80:81], s[24:25], v80, s15, v[142:143]
	v_lshl_add_u64 v[80:81], v[80:81], 0, v[144:145]
	v_pk_mul_f32 v[78:79], v[78:79], v[82:83] op_sel_hi:[1,0]
	v_pk_mul_f32 v[76:77], v[76:77], v[82:83] op_sel_hi:[1,0]
	v_pk_mul_f32 v[84:85], v[74:75], v[82:83] op_sel_hi:[1,0]
	v_pk_mul_f32 v[74:75], v[72:73], v[82:83] op_sel_hi:[1,0]
	v_cvt_pk_bf16_f32 v72, v76, v77
	v_cvt_pk_bf16_f32 v73, v78, v79
	v_pk_mul_f32 v[70:71], v[70:71], v[82:83] op_sel_hi:[1,0]
	v_cvt_pk_bf16_f32 v74, v74, v75
	v_cvt_pk_bf16_f32 v75, v84, v85
	global_store_dwordx4 v[80:81], v[72:75], off
	v_pk_mul_f32 v[68:69], v[68:69], v[82:83] op_sel_hi:[1,0]
	s_nop 0
	v_pk_mul_f32 v[72:73], v[66:67], v[82:83] op_sel_hi:[1,0]
	v_pk_mul_f32 v[66:67], v[64:65], v[82:83] op_sel_hi:[1,0]
	v_cvt_pk_bf16_f32 v64, v68, v69
	v_cvt_pk_bf16_f32 v65, v70, v71
	v_add_u32_e32 v68, 0x80, v138
	v_cvt_pk_bf16_f32 v66, v66, v67
	v_cvt_pk_bf16_f32 v67, v72, v73
	global_store_dwordx4 v[80:81], v[64:67], off offset:256
	s_nop 1
	v_mov_b64_e32 v[64:65], v[214:215]
	v_cvt_f64_u32_e32 v[66:67], v65
	v_ldexp_f64 v[66:67], v[66:67], 32
	v_cvt_f64_u32_e32 v[64:65], v64
	v_add_f64 v[64:65], v[66:67], v[64:65]
	v_ldexp_f64 v[64:65], v[64:65], s93
	v_cvt_f32_f64_e32 v64, v[64:65]
	v_fmamk_f32 v64, v64, 0x3a000000, v189
	v_cmp_gt_f32_e32 vcc, s78, v64
	v_mul_f32_e32 v65, 0x4b800000, v64
	v_mad_i64_i32 v[66:67], s[24:25], v68, s15, v[142:143]
	v_cndmask_b32_e32 v64, v64, v65, vcc
	v_rsq_f32_e32 v64, v64
	v_lshl_add_u64 v[66:67], v[66:67], 0, v[144:145]
	v_mul_f32_e32 v65, 0x45800000, v64
	v_cndmask_b32_e32 v64, v64, v65, vcc
	v_pk_mul_f32 v[62:63], v[62:63], v[64:65] op_sel_hi:[1,0]
	v_pk_mul_f32 v[60:61], v[60:61], v[64:65] op_sel_hi:[1,0]
	v_pk_mul_f32 v[68:69], v[58:59], v[64:65] op_sel_hi:[1,0]
; __device__ __forceinline__ unsigned cvt_pk_bf16(float lo, float hi) { unsigned r; asm volatile("v_cvt_pk_bf16_f32 %0, %1, %2" : "=v"(r) : "v"(lo), "v"(hi)); return r; }
; __device__ __forceinline__ float rinv_st(stat_t s, float invn) { return rsqrtf((float)((double)s * (1.0 / 4294967296.0)) * invn + 1e-6f); }
; #define PG8_WAIT_V(n) asm volatile("s_waitcnt vmcnt(" #n ")" ::: "memory")
; #define PG8_BAR __builtin_amdgcn_s_barrier()
; template <class Epi>
; __device__ __forceinline__ void gemm_phase(const int TID, const int BID, LAS unsigned char* lds, const Gemm g, const StaticOrder& S, const Epi& E) {
;     ...
;     PG8_WAIT_V(0);
;     if (wr == 0) PG8_BAR;
;     PG8_BAR;
;     __device__ __forceinline__ void operator()(const f32x4 (&acc)[2][2][4][2], const Unit& u, int wr, int wc, int fr, int fq) const {
;     ...
;         for (int ai = 0; ai < 2; ++ai)
; #pragma unroll
;             for (int m = 0; m < 4; ++m) {
;                 const int row = row0 + ai * HALF + m * 16; const float r = rinv_st(stats[row], 1.0f / 2048.0f);
;                 bf16_t* rowp = raw + (size_t)row * NINP + col0;
; #pragma unroll
;                 for (int bj = 0; bj < 2; ++bj) {
;                     const f32x4 v0 = acc[ai][bj][m][0] * r, v1 = acc[ai][bj][m][1] * r;
;                     u32x4 w; w.x = cvt_pk_bf16(v0[0], v0[1]); w.y = cvt_pk_bf16(v0[2], v0[3]); w.z = cvt_pk_bf16(v1[0], v1[1]); w.w = cvt_pk_bf16(v1[2], v1[3]);
;                     *(u32x4*)(rowp + bj * HALF) = w;
;                 }
;             }
	v_pk_mul_f32 v[58:59], v[56:57], v[64:65] op_sel_hi:[1,0]
	v_cvt_pk_bf16_f32 v56, v60, v61
	v_cvt_pk_bf16_f32 v57, v62, v63
	v_pk_mul_f32 v[54:55], v[54:55], v[64:65] op_sel_hi:[1,0]
	v_cvt_pk_bf16_f32 v58, v58, v59
	v_cvt_pk_bf16_f32 v59, v68, v69
	global_store_dwordx4 v[66:67], v[56:59], off
	v_pk_mul_f32 v[52:53], v[52:53], v[64:65] op_sel_hi:[1,0]
	s_nop 0
	v_pk_mul_f32 v[56:57], v[50:51], v[64:65] op_sel_hi:[1,0]
	v_pk_mul_f32 v[50:51], v[48:49], v[64:65] op_sel_hi:[1,0]
	v_cvt_pk_bf16_f32 v48, v52, v53
	v_cvt_pk_bf16_f32 v49, v54, v55
	v_add_u32_e32 v52, 0x90, v138
	v_cvt_pk_bf16_f32 v50, v50, v51
	v_cvt_pk_bf16_f32 v51, v56, v57
	global_store_dwordx4 v[66:67], v[48:51], off offset:256
	s_nop 1
	v_mov_b64_e32 v[48:49], v[216:217]
	v_cvt_f64_u32_e32 v[50:51], v49
	v_ldexp_f64 v[50:51], v[50:51], 32
	v_cvt_f64_u32_e32 v[48:49], v48
	v_add_f64 v[48:49], v[50:51], v[48:49]
	v_ldexp_f64 v[48:49], v[48:49], s93
	v_cvt_f32_f64_e32 v48, v[48:49]
	v_fmamk_f32 v48, v48, 0x3a000000, v189
	v_cmp_gt_f32_e32 vcc, s78, v48
	v_mul_f32_e32 v49, 0x4b800000, v48
	v_mad_i64_i32 v[50:51], s[24:25], v52, s15, v[142:143]
	v_cndmask_b32_e32 v48, v48, v49, vcc
	v_rsq_f32_e32 v48, v48
	v_lshl_add_u64 v[50:51], v[50:51], 0, v[144:145]
	v_mul_f32_e32 v49, 0x45800000, v48
	v_cndmask_b32_e32 v48, v48, v49, vcc
	v_pk_mul_f32 v[46:47], v[46:47], v[48:49] op_sel_hi:[1,0]
	v_pk_mul_f32 v[44:45], v[44:45], v[48:49] op_sel_hi:[1,0]
	v_pk_mul_f32 v[52:53], v[42:43], v[48:49] op_sel_hi:[1,0]
	v_pk_mul_f32 v[42:43], v[40:41], v[48:49] op_sel_hi:[1,0]
	v_cvt_pk_bf16_f32 v40, v44, v45
	v_cvt_pk_bf16_f32 v41, v46, v47
	v_pk_mul_f32 v[38:39], v[38:39], v[48:49] op_sel_hi:[1,0]
	v_cvt_pk_bf16_f32 v42, v42, v43
	v_cvt_pk_bf16_f32 v43, v52, v53
	global_store_dwordx4 v[50:51], v[40:43], off
	v_pk_mul_f32 v[36:37], v[36:37], v[48:49] op_sel_hi:[1,0]
	s_nop 0
	v_pk_mul_f32 v[40:41], v[34:35], v[48:49] op_sel_hi:[1,0]
	v_pk_mul_f32 v[34:35], v[32:33], v[48:49] op_sel_hi:[1,0]
	v_cvt_pk_bf16_f32 v32, v36, v37
	v_cvt_pk_bf16_f32 v33, v38, v39
	v_add_u32_e32 v36, 0xa0, v138
	v_cvt_pk_bf16_f32 v34, v34, v35
	v_cvt_pk_bf16_f32 v35, v40, v41
	global_store_dwordx4 v[50:51], v[32:35], off offset:256
	s_nop 1
	v_mov_b64_e32 v[32:33], v[218:219]
	v_cvt_f64_u32_e32 v[34:35], v33
	v_ldexp_f64 v[34:35], v[34:35], 32
	v_cvt_f64_u32_e32 v[32:33], v32
	v_add_f64 v[32:33], v[34:35], v[32:33]
	v_ldexp_f64 v[32:33], v[32:33], s93
	v_cvt_f32_f64_e32 v32, v[32:33]
	v_fmamk_f32 v32, v32, 0x3a000000, v189
	v_cmp_gt_f32_e32 vcc, s78, v32
	v_mul_f32_e32 v33, 0x4b800000, v32
	v_mad_i64_i32 v[34:35], s[24:25], v36, s15, v[142:143]
	v_cndmask_b32_e32 v32, v32, v33, vcc
	v_rsq_f32_e32 v32, v32
	v_lshl_add_u64 v[34:35], v[34:35], 0, v[144:145]
	v_mul_f32_e32 v33, 0x45800000, v32
	v_cndmask_b32_e32 v32, v32, v33, vcc
	v_pk_mul_f32 v[30:31], v[30:31], v[32:33] op_sel_hi:[1,0]
	v_pk_mul_f32 v[28:29], v[28:29], v[32:33] op_sel_hi:[1,0]
	v_pk_mul_f32 v[36:37], v[26:27], v[32:33] op_sel_hi:[1,0]
	v_pk_mul_f32 v[26:27], v[24:25], v[32:33] op_sel_hi:[1,0]
	v_cvt_pk_bf16_f32 v24, v28, v29
	v_cvt_pk_bf16_f32 v25, v30, v31
	v_pk_mul_f32 v[22:23], v[22:23], v[32:33] op_sel_hi:[1,0]
	v_cvt_pk_bf16_f32 v26, v26, v27
	v_cvt_pk_bf16_f32 v27, v36, v37
	global_store_dwordx4 v[34:35], v[24:27], off
	v_pk_mul_f32 v[20:21], v[20:21], v[32:33] op_sel_hi:[1,0]
	s_nop 0
	v_pk_mul_f32 v[24:25], v[18:19], v[32:33] op_sel_hi:[1,0]
	v_pk_mul_f32 v[18:19], v[16:17], v[32:33] op_sel_hi:[1,0]
	v_cvt_pk_bf16_f32 v16, v20, v21
	v_cvt_pk_bf16_f32 v17, v22, v23
	v_add_u32_e32 v20, 0xb0, v138
	v_cvt_pk_bf16_f32 v18, v18, v19
	v_cvt_pk_bf16_f32 v19, v24, v25
	global_store_dwordx4 v[34:35], v[16:19], off offset:256
	s_nop 1
	v_mov_b64_e32 v[16:17], v[220:221]
	v_cvt_f64_u32_e32 v[18:19], v17
	v_ldexp_f64 v[18:19], v[18:19], 32
	v_cvt_f64_u32_e32 v[16:17], v16
	v_add_f64 v[16:17], v[18:19], v[16:17]
	v_ldexp_f64 v[16:17], v[16:17], s93
	v_cvt_f32_f64_e32 v16, v[16:17]
	v_fmamk_f32 v16, v16, 0x3a000000, v189
	v_cmp_gt_f32_e32 vcc, s78, v16
	v_mul_f32_e32 v17, 0x4b800000, v16
	v_mad_i64_i32 v[18:19], s[24:25], v20, s15, v[142:143]
	v_cndmask_b32_e32 v16, v16, v17, vcc
	v_rsq_f32_e32 v16, v16
	v_lshl_add_u64 v[18:19], v[18:19], 0, v[144:145]
	s_mov_b64 s[24:25], s[18:19]
	v_mul_f32_e32 v17, 0x45800000, v16
	v_cndmask_b32_e32 v16, v16, v17, vcc
	v_pk_mul_f32 v[14:15], v[14:15], v[16:17] op_sel_hi:[1,0]
	v_pk_mul_f32 v[12:13], v[12:13], v[16:17] op_sel_hi:[1,0]
	v_pk_mul_f32 v[20:21], v[10:11], v[16:17] op_sel_hi:[1,0]
	v_pk_mul_f32 v[10:11], v[8:9], v[16:17] op_sel_hi:[1,0]
	v_cvt_pk_bf16_f32 v8, v12, v13
	v_cvt_pk_bf16_f32 v9, v14, v15
	s_and_b64 vcc, exec, s[8:9]
	v_cvt_pk_bf16_f32 v10, v10, v11
	v_cvt_pk_bf16_f32 v11, v20, v21
	global_store_dwordx4 v[18:19], v[8:11], off
	v_pk_mul_f32 v[6:7], v[6:7], v[16:17] op_sel_hi:[1,0]
	v_pk_mul_f32 v[4:5], v[4:5], v[16:17] op_sel_hi:[1,0]
	v_pk_mul_f32 v[8:9], v[2:3], v[16:17] op_sel_hi:[1,0]
	v_pk_mul_f32 v[2:3], v[0:1], v[16:17] op_sel_hi:[1,0]
	v_cvt_pk_bf16_f32 v0, v4, v5
	v_cvt_pk_bf16_f32 v1, v6, v7
	s_nop 0
	v_cvt_pk_bf16_f32 v2, v2, v3
	v_cvt_pk_bf16_f32 v3, v8, v9
	global_store_dwordx4 v[18:19], v[0:3], off offset:256
	s_cbranch_vccz .LBB0_792
	s_waitcnt vmcnt(0)
	s_cmpk_gt_u32 s0, 0xff
	s_cbranch_scc1 .LBB0_803
	s_barrier

; #define PG8_STAGE(bufoff, gbase, voff) do { _Pragma("unroll") for (int _i = 0; _i < 2; ++_i) \
;         __builtin_amdgcn_global_load_lds((const unsigned*)((const char*)(gbase) + (voff)[_i]), (LAS unsigned*)(lds + (bufoff) + ldsw + _i * 8192), 16, 0, 0); } while (0)
; #define PG8_LDA(dst, b, h) do { _Pragma("unroll") for (int m = 0; m < 4; ++m) _Pragma("unroll") for (int k = 0; k < 2; ++k) dst[m][k] = *(const LAS bf16x8*)(lds + PG8_SA(b, h) + aoff + m * 2048 + k * 1024); } while (0)
; #define PG8_LDB(dst, b, h) do { _Pragma("unroll") for (int n = 0; n < 2; ++n) _Pragma("unroll") for (int k = 0; k < 2; ++k) dst[n][k] = *(const LAS bf16x8*)(lds + PG8_SB(b, h) + boff + n * 2048 + k * 1024); } while (0)
; #define PG8_MMA(ai, bj, At, Bt) do { __builtin_amdgcn_s_setprio(1); _Pragma("unroll") for (int m = 0; m < 4; ++m) _Pragma("unroll") for (int n = 0; n < 2; ++n) _Pragma("unroll") for (int k = 0; k < 2; ++k) \
;         acc[ai][bj][m][n] = __builtin_amdgcn_mfma_f32_16x16x32_bf16(Bt[n][k], At[m][k], acc[ai][bj][m][n], 0, 0, 0); __builtin_amdgcn_s_setprio(0); } while (0)
; #define PG8_WAIT_L(n) asm volatile("s_waitcnt lgkmcnt(" #n ")" ::: "memory")
; #define PG8_BAR __builtin_amdgcn_s_barrier()
; #define PG8_SCHED __builtin_amdgcn_sched_barrier(0)
; template <class Epi>
; __device__ __forceinline__ void gemm_phase(const int TID, const int BID, LAS unsigned char* lds, const Gemm g, const StaticOrder& S, const Epi& E) {
;     ...
;         for (int t = 0; t < nt; t += 2) {
;             const bool last = (t == nt - 2);
;             const char* a1 = cA + (size_t)(t + 1) * kstep;
;             const char* a2 = last ? nA : cA + (size_t)(t + 2) * kstep; const char* b2 = last ? nB : cB + (size_t)(t + 2) * kstep;
;             const char* a3 = a2 + kstep; const char* b3 = b2 + kstep;
;             PG8_LDB(B0, 0, 0); PG8_SCHED; PG8_LDA(At, 0, 0); PG8_STAGE(PG8_SA(1, 1), a1 + hstepA, voffA);
;             PG8_WAIT_L(8); PG8_BAR; PG8_WAIT_L(0); PG8_MMA(0, 0, At, B0); PG8_BAR; PG8_SCHED;
;             PG8_LDB(B1, 0, 1); PG8_STAGE(PG8_SB(0, 0), b2, voffB);
;             PG8_BAR; PG8_WAIT_L(0); PG8_MMA(0, 1, At, B1); PG8_BAR;
;             PG8_LDA(At, 0, 1); PG8_STAGE(PG8_SA(0, 0), a2, voffA);
;             PG8_BAR; PG8_WAIT_L(0); PG8_MMA(1, 0, At, B0); PG8_BAR; PG8_SCHED;
.LBB0_822:
	v_add_u32_e32 v154, s36, v147
	ds_read_b128 v[134:137], v154
	ds_read_b128 v[138:141], v154 offset:1024
	ds_read_b128 v[150:153], v154 offset:2048
	ds_read_b128 v[154:157], v154 offset:3072
	s_add_u32 s28, s26, 0xfff80080
	s_addc_u32 s29, s27, -1
	s_cmp_eq_u32 s66, 4
	s_cselect_b32 s31, s17, s29
	s_cselect_b32 s30, s61, s28
	s_cselect_b32 s29, s15, s64
	s_cselect_b32 s28, s62, s63
	v_lshl_add_u64 v[158:159], s[26:27], 0, v[130:131]
	s_add_i32 m0, s47, 0xc000
	ds_read_b128 v[166:169], v149
	ds_read_b128 v[170:173], v149 offset:1024
	ds_read_b128 v[174:177], v149 offset:2048
	ds_read_b128 v[178:181], v149 offset:3072
	ds_read_b128 v[182:185], v149 offset:4096
	ds_read_b128 v[196:199], v149 offset:5120
	ds_read_b128 v[208:211], v149 offset:6144
	ds_read_b128 v[212:215], v149 offset:7168
	global_load_lds_dwordx4 v[158:159], off
	s_add_i32 m0, s47, 0xe000
	v_lshl_add_u64 v[158:159], s[26:27], 0, v[132:133]
	global_load_lds_dwordx4 v[158:159], off
	s_waitcnt lgkmcnt(8)
	s_barrier
	s_waitcnt lgkmcnt(0)
	s_setprio 1
	v_mfma_f32_16x16x32_bf16 v[124:127], v[134:137], v[166:169], v[124:127]
	v_mfma_f32_16x16x32_bf16 v[120:123], v[150:153], v[166:169], v[120:123]
	v_mfma_f32_16x16x32_bf16 v[108:111], v[134:137], v[174:177], v[108:111]
	v_mfma_f32_16x16x32_bf16 v[104:107], v[150:153], v[174:177], v[104:107]
	v_mfma_f32_16x16x32_bf16 v[92:95], v[134:137], v[182:185], v[92:95]
	v_mfma_f32_16x16x32_bf16 v[88:91], v[150:153], v[182:185], v[88:91]
	v_mfma_f32_16x16x32_bf16 v[76:79], v[134:137], v[208:211], v[76:79]
	v_mfma_f32_16x16x32_bf16 v[72:75], v[150:153], v[208:211], v[72:75]
	v_mfma_f32_16x16x32_bf16 v[124:127], v[138:141], v[170:173], v[124:127]
	v_mfma_f32_16x16x32_bf16 v[120:123], v[154:157], v[170:173], v[120:123]
	v_mfma_f32_16x16x32_bf16 v[108:111], v[138:141], v[178:181], v[108:111]
	v_mfma_f32_16x16x32_bf16 v[104:107], v[154:157], v[178:181], v[104:107]
	v_mfma_f32_16x16x32_bf16 v[92:95], v[138:141], v[196:199], v[92:95]
	v_mfma_f32_16x16x32_bf16 v[88:91], v[154:157], v[196:199], v[88:91]
	v_mfma_f32_16x16x32_bf16 v[76:79], v[138:141], v[212:215], v[76:79]
	v_mfma_f32_16x16x32_bf16 v[72:75], v[154:157], v[212:215], v[72:75]
	s_setprio 0
	s_barrier
	v_add_u32_e32 v158, s37, v147
	s_mov_b32 m0, s25
	ds_read_b128 v[216:219], v158
	ds_read_b128 v[220:223], v158 offset:1024
	ds_read_b128 v[224:227], v158 offset:2048
	ds_read_b128 v[228:231], v158 offset:3072
	v_lshl_add_u64 v[158:159], s[28:29], 0, v[160:161]
	global_load_lds_dwordx4 v[158:159], off
	s_mov_b32 m0, s46
	v_lshl_add_u64 v[200:201], s[28:29], 0, v[128:129]
	global_load_lds_dwordx4 v[200:201], off
	s_barrier
	s_waitcnt lgkmcnt(0)
	s_setprio 1
	v_mfma_f32_16x16x32_bf16 v[116:119], v[216:219], v[166:169], v[116:119]
	v_mfma_f32_16x16x32_bf16 v[112:115], v[224:227], v[166:169], v[112:115]
	v_mfma_f32_16x16x32_bf16 v[100:103], v[216:219], v[174:177], v[100:103]
	v_mfma_f32_16x16x32_bf16 v[96:99], v[224:227], v[174:177], v[96:99]
	v_mfma_f32_16x16x32_bf16 v[84:87], v[216:219], v[182:185], v[84:87]
	v_mfma_f32_16x16x32_bf16 v[80:83], v[224:227], v[182:185], v[80:83]
	v_mfma_f32_16x16x32_bf16 v[68:71], v[216:219], v[208:211], v[68:71]
	v_mfma_f32_16x16x32_bf16 v[64:67], v[224:227], v[208:211], v[64:67]
	v_mfma_f32_16x16x32_bf16 v[116:119], v[220:223], v[170:173], v[116:119]
	v_mfma_f32_16x16x32_bf16 v[112:115], v[228:231], v[170:173], v[112:115]
	v_mfma_f32_16x16x32_bf16 v[100:103], v[220:223], v[178:181], v[100:103]
	v_mfma_f32_16x16x32_bf16 v[96:99], v[228:231], v[178:181], v[96:99]
	v_mfma_f32_16x16x32_bf16 v[84:87], v[220:223], v[196:199], v[84:87]
	v_mfma_f32_16x16x32_bf16 v[80:83], v[228:231], v[196:199], v[80:83]
	v_mfma_f32_16x16x32_bf16 v[68:71], v[220:223], v[212:215], v[68:71]
	v_mfma_f32_16x16x32_bf16 v[64:67], v[228:231], v[212:215], v[64:67]
	s_setprio 0
	s_mov_b32 m0, s47
	v_lshl_add_u64 v[232:233], s[30:31], 0, v[160:161]
	s_barrier
	ds_read_b128 v[166:169], v149 offset:16384
	ds_read_b128 v[170:173], v149 offset:17408
	ds_read_b128 v[174:177], v149 offset:18432
	ds_read_b128 v[178:181], v149 offset:19456
	ds_read_b128 v[182:185], v149 offset:20480
	ds_read_b128 v[196:199], v149 offset:21504
	ds_read_b128 v[208:211], v149 offset:22528
	ds_read_b128 v[212:215], v149 offset:23552
	global_load_lds_dwordx4 v[232:233], off
	s_mov_b32 m0, s48
	v_lshl_add_u64 v[234:235], s[30:31], 0, v[128:129]
	global_load_lds_dwordx4 v[234:235], off
	s_barrier
	s_waitcnt lgkmcnt(0)
	s_setprio 1
	v_mfma_f32_16x16x32_bf16 v[60:63], v[134:137], v[166:169], v[60:63]
	v_mfma_f32_16x16x32_bf16 v[56:59], v[150:153], v[166:169], v[56:59]
	v_mfma_f32_16x16x32_bf16 v[44:47], v[134:137], v[174:177], v[44:47]
	v_mfma_f32_16x16x32_bf16 v[40:43], v[150:153], v[174:177], v[40:43]
	v_mfma_f32_16x16x32_bf16 v[28:31], v[134:137], v[182:185], v[28:31]
	v_mfma_f32_16x16x32_bf16 v[24:27], v[150:153], v[182:185], v[24:27]
	v_mfma_f32_16x16x32_bf16 v[12:15], v[134:137], v[208:211], v[12:15]
	v_mfma_f32_16x16x32_bf16 v[8:11], v[150:153], v[208:211], v[8:11]
	v_mfma_f32_16x16x32_bf16 v[60:63], v[138:141], v[170:173], v[60:63]
	v_mfma_f32_16x16x32_bf16 v[56:59], v[154:157], v[170:173], v[56:59]
	v_mfma_f32_16x16x32_bf16 v[44:47], v[138:141], v[178:181], v[44:47]
	v_mfma_f32_16x16x32_bf16 v[40:43], v[154:157], v[178:181], v[40:43]
	v_mfma_f32_16x16x32_bf16 v[28:31], v[138:141], v[196:199], v[28:31]
	v_mfma_f32_16x16x32_bf16 v[24:27], v[154:157], v[196:199], v[24:27]
	v_mfma_f32_16x16x32_bf16 v[12:15], v[138:141], v[212:215], v[12:15]
	v_mfma_f32_16x16x32_bf16 v[8:11], v[154:157], v[212:215], v[8:11]
	s_setprio 0
	s_barrier
; #define PG8_STAGE(bufoff, gbase, voff) do { _Pragma("unroll") for (int _i = 0; _i < 2; ++_i) \
;         __builtin_amdgcn_global_load_lds((const unsigned*)((const char*)(gbase) + (voff)[_i]), (LAS unsigned*)(lds + (bufoff) + ldsw + _i * 8192), 16, 0, 0); } while (0)
; #define PG8_LDA(dst, b, h) do { _Pragma("unroll") for (int m = 0; m < 4; ++m) _Pragma("unroll") for (int k = 0; k < 2; ++k) dst[m][k] = *(const LAS bf16x8*)(lds + PG8_SA(b, h) + aoff + m * 2048 + k * 1024); } while (0)
; #define PG8_LDB(dst, b, h) do { _Pragma("unroll") for (int n = 0; n < 2; ++n) _Pragma("unroll") for (int k = 0; k < 2; ++k) dst[n][k] = *(const LAS bf16x8*)(lds + PG8_SB(b, h) + boff + n * 2048 + k * 1024); } while (0)
; #define PG8_MMA(ai, bj, At, Bt) do { __builtin_amdgcn_s_setprio(1); _Pragma("unroll") for (int m = 0; m < 4; ++m) _Pragma("unroll") for (int n = 0; n < 2; ++n) _Pragma("unroll") for (int k = 0; k < 2; ++k) \
;         acc[ai][bj][m][n] = __builtin_amdgcn_mfma_f32_16x16x32_bf16(Bt[n][k], At[m][k], acc[ai][bj][m][n], 0, 0, 0); __builtin_amdgcn_s_setprio(0); } while (0)
; #define PG8_WAIT_V(n) asm volatile("s_waitcnt vmcnt(" #n ")" ::: "memory")
; #define PG8_WAIT_L(n) asm volatile("s_waitcnt lgkmcnt(" #n ")" ::: "memory")
; #define PG8_BAR __builtin_amdgcn_s_barrier()
; #define PG8_SCHED __builtin_amdgcn_sched_barrier(0)
; template <class Epi>
; __device__ __forceinline__ void gemm_phase(const int TID, const int BID, LAS unsigned char* lds, const Gemm g, const StaticOrder& S, const Epi& E) {
;     ...
;             PG8_STAGE(PG8_SB(0, 1), b2 + hstepB, voffB);
;             PG8_WAIT_V(6); PG8_BAR; PG8_MMA(1, 1, At, B1); PG8_BAR;
;             PG8_LDB(B0, 1, 0); PG8_SCHED; PG8_LDA(At, 1, 0); PG8_STAGE(PG8_SA(0, 1), a2 + hstepA, voffA);
;             PG8_WAIT_L(8); PG8_BAR; PG8_WAIT_L(0); PG8_MMA(0, 0, At, B0); PG8_BAR; PG8_SCHED;
;             PG8_LDB(B1, 1, 1); PG8_STAGE(PG8_SB(1, 0), b3, voffB);
;             PG8_BAR; PG8_WAIT_L(0); PG8_MMA(0, 1, At, B1); PG8_BAR;
	s_add_u32 s74, s28, 0x80000
	s_addc_u32 s75, s29, 0
	s_mov_b32 m0, s49
	v_lshl_add_u64 v[134:135], s[74:75], 0, v[160:161]
	global_load_lds_dwordx4 v[134:135], off
	s_mov_b32 m0, s50
	v_lshl_add_u64 v[134:135], s[74:75], 0, v[128:129]
	global_load_lds_dwordx4 v[134:135], off
	s_waitcnt vmcnt(6)
	s_barrier
	s_setprio 1
	v_mfma_f32_16x16x32_bf16 v[52:55], v[216:219], v[166:169], v[52:55]
	v_mfma_f32_16x16x32_bf16 v[48:51], v[224:227], v[166:169], v[48:51]
	v_mfma_f32_16x16x32_bf16 v[36:39], v[216:219], v[174:177], v[36:39]
	v_mfma_f32_16x16x32_bf16 v[32:35], v[224:227], v[174:177], v[32:35]
	v_mfma_f32_16x16x32_bf16 v[20:23], v[216:219], v[182:185], v[20:23]
	v_mfma_f32_16x16x32_bf16 v[16:19], v[224:227], v[182:185], v[16:19]
	v_mfma_f32_16x16x32_bf16 v[4:7], v[216:219], v[208:211], v[4:7]
	v_mfma_f32_16x16x32_bf16 v[0:3], v[224:227], v[208:211], v[0:3]
	v_mfma_f32_16x16x32_bf16 v[52:55], v[220:223], v[170:173], v[52:55]
	v_mfma_f32_16x16x32_bf16 v[48:51], v[228:231], v[170:173], v[48:51]
	v_mfma_f32_16x16x32_bf16 v[36:39], v[220:223], v[178:181], v[36:39]
	v_mfma_f32_16x16x32_bf16 v[32:35], v[228:231], v[178:181], v[32:35]
	v_mfma_f32_16x16x32_bf16 v[20:23], v[220:223], v[196:199], v[20:23]
	v_mfma_f32_16x16x32_bf16 v[16:19], v[228:231], v[196:199], v[16:19]
	v_mfma_f32_16x16x32_bf16 v[4:7], v[220:223], v[212:215], v[4:7]
	v_mfma_f32_16x16x32_bf16 v[0:3], v[228:231], v[212:215], v[0:3]
	s_setprio 0
	v_add_u32_e32 v154, s38, v147
	s_barrier
	ds_read_b128 v[134:137], v154
	ds_read_b128 v[138:141], v154 offset:1024
	ds_read_b128 v[150:153], v154 offset:2048
	ds_read_b128 v[154:157], v154 offset:3072
	s_add_u32 s30, s30, 0x80000
	s_addc_u32 s31, s31, 0
	s_mov_b32 m0, s51
	v_lshl_add_u64 v[216:217], s[30:31], 0, v[160:161]
	ds_read_b128 v[166:169], v149 offset:32768
	ds_read_b128 v[170:173], v149 offset:33792
	ds_read_b128 v[174:177], v149 offset:34816
	ds_read_b128 v[178:181], v149 offset:35840
	ds_read_b128 v[182:185], v149 offset:36864
	ds_read_b128 v[196:199], v149 offset:37888
	ds_read_b128 v[208:211], v149 offset:38912
	ds_read_b128 v[212:215], v149 offset:39936
	global_load_lds_dwordx4 v[216:217], off
	s_mov_b32 m0, s52
	v_lshl_add_u64 v[216:217], s[30:31], 0, v[128:129]
	global_load_lds_dwordx4 v[216:217], off
	s_waitcnt lgkmcnt(8)
	s_barrier
	s_waitcnt lgkmcnt(0)
	s_setprio 1
	v_mfma_f32_16x16x32_bf16 v[124:127], v[134:137], v[166:169], v[124:127]
	v_mfma_f32_16x16x32_bf16 v[120:123], v[150:153], v[166:169], v[120:123]
	v_mfma_f32_16x16x32_bf16 v[108:111], v[134:137], v[174:177], v[108:111]
	v_mfma_f32_16x16x32_bf16 v[104:107], v[150:153], v[174:177], v[104:107]
	v_mfma_f32_16x16x32_bf16 v[92:95], v[134:137], v[182:185], v[92:95]
	v_mfma_f32_16x16x32_bf16 v[88:91], v[150:153], v[182:185], v[88:91]
	v_mfma_f32_16x16x32_bf16 v[76:79], v[134:137], v[208:211], v[76:79]
	v_mfma_f32_16x16x32_bf16 v[72:75], v[150:153], v[208:211], v[72:75]
	v_mfma_f32_16x16x32_bf16 v[124:127], v[138:141], v[170:173], v[124:127]
	v_mfma_f32_16x16x32_bf16 v[120:123], v[154:157], v[170:173], v[120:123]
	v_mfma_f32_16x16x32_bf16 v[108:111], v[138:141], v[178:181], v[108:111]
	v_mfma_f32_16x16x32_bf16 v[104:107], v[154:157], v[178:181], v[104:107]
	v_mfma_f32_16x16x32_bf16 v[92:95], v[138:141], v[196:199], v[92:95]
	v_mfma_f32_16x16x32_bf16 v[88:91], v[154:157], v[196:199], v[88:91]
	v_mfma_f32_16x16x32_bf16 v[76:79], v[138:141], v[212:215], v[76:79]
	v_mfma_f32_16x16x32_bf16 v[72:75], v[154:157], v[212:215], v[72:75]
	s_setprio 0
	s_barrier
	s_mov_b32 m0, s53
	v_add_u32_e32 v228, s39, v147
	v_lshl_add_u64 v[158:159], v[158:159], 0, s[90:91]
	ds_read_b128 v[216:219], v228
	ds_read_b128 v[220:223], v228 offset:1024
	ds_read_b128 v[224:227], v228 offset:2048
	ds_read_b128 v[228:231], v228 offset:3072
	global_load_lds_dwordx4 v[158:159], off
	s_mov_b32 m0, s54
	v_lshl_add_u64 v[158:159], v[200:201], 0, s[90:91]
	global_load_lds_dwordx4 v[158:159], off
	s_barrier
	s_waitcnt lgkmcnt(0)
	s_setprio 1
	v_mfma_f32_16x16x32_bf16 v[116:119], v[216:219], v[166:169], v[116:119]
	v_mfma_f32_16x16x32_bf16 v[112:115], v[224:227], v[166:169], v[112:115]
	v_mfma_f32_16x16x32_bf16 v[100:103], v[216:219], v[174:177], v[100:103]
	v_mfma_f32_16x16x32_bf16 v[96:99], v[224:227], v[174:177], v[96:99]
	v_mfma_f32_16x16x32_bf16 v[84:87], v[216:219], v[182:185], v[84:87]
	v_mfma_f32_16x16x32_bf16 v[80:83], v[224:227], v[182:185], v[80:83]
	v_mfma_f32_16x16x32_bf16 v[68:71], v[216:219], v[208:211], v[68:71]
	v_mfma_f32_16x16x32_bf16 v[64:67], v[224:227], v[208:211], v[64:67]
	v_mfma_f32_16x16x32_bf16 v[116:119], v[220:223], v[170:173], v[116:119]
	v_mfma_f32_16x16x32_bf16 v[112:115], v[228:231], v[170:173], v[112:115]
	v_mfma_f32_16x16x32_bf16 v[100:103], v[220:223], v[178:181], v[100:103]
	v_mfma_f32_16x16x32_bf16 v[96:99], v[228:231], v[178:181], v[96:99]
	v_mfma_f32_16x16x32_bf16 v[84:87], v[220:223], v[196:199], v[84:87]
	v_mfma_f32_16x16x32_bf16 v[80:83], v[228:231], v[196:199], v[80:83]
	v_mfma_f32_16x16x32_bf16 v[68:71], v[220:223], v[212:215], v[68:71]
	v_mfma_f32_16x16x32_bf16 v[64:67], v[228:231], v[212:215], v[64:67]
	s_setprio 0
	s_mov_b32 m0, s55
	v_lshl_add_u64 v[158:159], v[232:233], 0, s[90:91]
	s_barrier
	ds_read_b128 v[166:169], v149 offset:49152
	ds_read_b128 v[170:173], v149 offset:50176
	ds_read_b128 v[174:177], v149 offset:51200
	ds_read_b128 v[178:181], v149 offset:52224
	ds_read_b128 v[182:185], v149 offset:53248
	ds_read_b128 v[196:199], v149 offset:54272
	ds_read_b128 v[208:211], v149 offset:55296
	ds_read_b128 v[212:215], v149 offset:56320
	global_load_lds_dwordx4 v[158:159], off
	s_mov_b32 m0, s56
	v_lshl_add_u64 v[158:159], v[234:235], 0, s[90:91]
	global_load_lds_dwordx4 v[158:159], off
	s_barrier
; __device__ __forceinline__ float rinv_st(stat_t s, float invn) { return rsqrtf((float)((double)s * (1.0 / 4294967296.0)) * invn + 1e-6f); }
; #define PG8_STAGE(bufoff, gbase, voff) do { _Pragma("unroll") for (int _i = 0; _i < 2; ++_i) \
;         __builtin_amdgcn_global_load_lds((const unsigned*)((const char*)(gbase) + (voff)[_i]), (LAS unsigned*)(lds + (bufoff) + ldsw + _i * 8192), 16, 0, 0); } while (0)
; #define PG8_LDA(dst, b, h) do { _Pragma("unroll") for (int m = 0; m < 4; ++m) _Pragma("unroll") for (int k = 0; k < 2; ++k) dst[m][k] = *(const LAS bf16x8*)(lds + PG8_SA(b, h) + aoff + m * 2048 + k * 1024); } while (0)
; #define PG8_MMA(ai, bj, At, Bt) do { __builtin_amdgcn_s_setprio(1); _Pragma("unroll") for (int m = 0; m < 4; ++m) _Pragma("unroll") for (int n = 0; n < 2; ++n) _Pragma("unroll") for (int k = 0; k < 2; ++k) \
;         acc[ai][bj][m][n] = __builtin_amdgcn_mfma_f32_16x16x32_bf16(Bt[n][k], At[m][k], acc[ai][bj][m][n], 0, 0, 0); __builtin_amdgcn_s_setprio(0); } while (0)
; #define PG8_WAIT_V(n) asm volatile("s_waitcnt vmcnt(" #n ")" ::: "memory")
; #define PG8_BAR __builtin_amdgcn_s_barrier()
; template <class Epi>
; __device__ __forceinline__ void gemm_phase(const int TID, const int BID, LAS unsigned char* lds, const Gemm g, const StaticOrder& S, const Epi& E) {
;     ...
;             PG8_BAR; PG8_WAIT_L(0); PG8_MMA(0, 1, At, B1); PG8_BAR;
;             PG8_LDA(At, 1, 1); PG8_STAGE(PG8_SA(1, 0), a3, voffA);
;             PG8_BAR; PG8_WAIT_L(0); PG8_MMA(1, 0, At, B0); PG8_BAR; PG8_SCHED;
;             PG8_STAGE(PG8_SB(1, 1), b3 + hstepB, voffB);
;             PG8_WAIT_V(6); PG8_BAR; PG8_MMA(1, 1, At, B1); PG8_BAR;
;     __device__ __forceinline__ void operator()(const f32x4 (&acc)[2][2][4][2], const Unit& u, int wr, int wc, int fr, int fq) const {
;         const int row0 = u.pm * BM + wr * 64 + fr, col0 = u.pn * BM + wc * 32 + 4 * fq;
; #pragma unroll
;         for (int ai = 0; ai < 2; ++ai)
; #pragma unroll
;             for (int m = 0; m < 4; ++m) {
;                 const int row = row0 + ai * HALF + m * 16; const float r = rinv_st(stats[row], 1.0f / 2048.0f);
;                 float* rowp = raw + (size_t)row * 256 + col0;
; #pragma unroll
;                 for (int bj = 0; bj < 2; ++bj)
; #pragma unroll
;                     for (int n = 0; n < 2; ++n) *(f32x4*)(rowp + bj * HALF + n * 16) = acc[ai][bj][m][n] * r;
	s_waitcnt lgkmcnt(0)
	s_setprio 1
	v_mfma_f32_16x16x32_bf16 v[60:63], v[134:137], v[166:169], v[60:63]
	v_mfma_f32_16x16x32_bf16 v[56:59], v[150:153], v[166:169], v[56:59]
	v_mfma_f32_16x16x32_bf16 v[44:47], v[134:137], v[174:177], v[44:47]
	v_mfma_f32_16x16x32_bf16 v[40:43], v[150:153], v[174:177], v[40:43]
	v_mfma_f32_16x16x32_bf16 v[28:31], v[134:137], v[182:185], v[28:31]
	v_mfma_f32_16x16x32_bf16 v[24:27], v[150:153], v[182:185], v[24:27]
	v_mfma_f32_16x16x32_bf16 v[12:15], v[134:137], v[208:211], v[12:15]
	v_mfma_f32_16x16x32_bf16 v[8:11], v[150:153], v[208:211], v[8:11]
	v_mfma_f32_16x16x32_bf16 v[60:63], v[138:141], v[170:173], v[60:63]
	v_mfma_f32_16x16x32_bf16 v[56:59], v[154:157], v[170:173], v[56:59]
	v_mfma_f32_16x16x32_bf16 v[44:47], v[138:141], v[178:181], v[44:47]
	v_mfma_f32_16x16x32_bf16 v[40:43], v[154:157], v[178:181], v[40:43]
	v_mfma_f32_16x16x32_bf16 v[28:31], v[138:141], v[196:199], v[28:31]
	v_mfma_f32_16x16x32_bf16 v[24:27], v[154:157], v[196:199], v[24:27]
	v_mfma_f32_16x16x32_bf16 v[12:15], v[138:141], v[212:215], v[12:15]
	v_mfma_f32_16x16x32_bf16 v[8:11], v[154:157], v[212:215], v[8:11]
	s_setprio 0
	s_barrier
	s_add_u32 s28, s28, 0x80080
	s_addc_u32 s29, s29, 0
	s_mov_b32 m0, s57
	v_lshl_add_u64 v[134:135], s[28:29], 0, v[160:161]
	global_load_lds_dwordx4 v[134:135], off
	s_mov_b32 m0, s58
	v_lshl_add_u64 v[134:135], s[28:29], 0, v[128:129]
	global_load_lds_dwordx4 v[134:135], off
	s_waitcnt vmcnt(6)
	s_barrier
	s_setprio 1
	v_mfma_f32_16x16x32_bf16 v[52:55], v[216:219], v[166:169], v[52:55]
	v_mfma_f32_16x16x32_bf16 v[48:51], v[224:227], v[166:169], v[48:51]
	v_mfma_f32_16x16x32_bf16 v[36:39], v[216:219], v[174:177], v[36:39]
	v_mfma_f32_16x16x32_bf16 v[32:35], v[224:227], v[174:177], v[32:35]
	v_mfma_f32_16x16x32_bf16 v[20:23], v[216:219], v[182:185], v[20:23]
	v_mfma_f32_16x16x32_bf16 v[16:19], v[224:227], v[182:185], v[16:19]
	v_mfma_f32_16x16x32_bf16 v[4:7], v[216:219], v[208:211], v[4:7]
	v_mfma_f32_16x16x32_bf16 v[0:3], v[224:227], v[208:211], v[0:3]
	v_mfma_f32_16x16x32_bf16 v[52:55], v[220:223], v[170:173], v[52:55]
	v_mfma_f32_16x16x32_bf16 v[48:51], v[228:231], v[170:173], v[48:51]
	v_mfma_f32_16x16x32_bf16 v[36:39], v[220:223], v[178:181], v[36:39]
	v_mfma_f32_16x16x32_bf16 v[32:35], v[228:231], v[178:181], v[32:35]
	v_mfma_f32_16x16x32_bf16 v[20:23], v[220:223], v[196:199], v[20:23]
	v_mfma_f32_16x16x32_bf16 v[16:19], v[228:231], v[196:199], v[16:19]
	v_mfma_f32_16x16x32_bf16 v[4:7], v[220:223], v[212:215], v[4:7]
	v_mfma_f32_16x16x32_bf16 v[0:3], v[228:231], v[212:215], v[0:3]
	s_setprio 0
	s_add_i32 s66, s66, 2
	s_add_u32 s26, s26, 0x100
	s_addc_u32 s27, s27, 0
	s_add_u32 s63, s63, 0x100
	s_addc_u32 s64, s64, 0
	s_cmp_gt_u32 s66, 5
	s_barrier
	s_cbranch_scc0 .LBB0_822
	v_lshl_add_u32 v140, s24, 8, v145
	v_ashrrev_i32_e32 v141, 31, v140
	v_lshl_add_u64 v[136:137], v[140:141], 3, s[10:11]
	global_load_dwordx2 v[138:139], v[136:137], off
	global_load_dwordx2 v[208:209], v[136:137], off offset:128
	global_load_dwordx2 v[210:211], v[136:137], off offset:256
	global_load_dwordx2 v[212:213], v[136:137], off offset:384
	global_load_dwordx2 v[214:215], v[136:137], off offset:1024
	global_load_dwordx2 v[216:217], v[136:137], off offset:1152
	global_load_dwordx2 v[218:219], v[136:137], off offset:1280
	global_load_dwordx2 v[220:221], v[136:137], off offset:1408
	v_lshl_or_b32 v134, s60, 8, v148
	v_ashrrev_i32_e32 v135, 31, v134
	s_mov_b32 s15, 0x20000
	s_mov_b64 s[26:27], 0x20000
	s_mov_b32 s60, s14
	s_mov_b32 s24, s16
	s_mov_b64 s[28:29], s[22:23]
	s_waitcnt vmcnt(0)
	v_cvt_f64_u32_e32 v[150:151], v139
	v_ldexp_f64 v[150:151], v[150:151], 32
	v_cvt_f64_u32_e32 v[138:139], v138
	v_add_f64 v[138:139], v[150:151], v[138:139]
	v_ldexp_f64 v[138:139], v[138:139], s93
	v_cvt_f32_f64_e32 v138, v[138:139]
	v_fmamk_f32 v138, v138, 0x3a000000, v189
	v_cmp_gt_f32_e32 vcc, s78, v138
	v_mul_f32_e32 v139, 0x4b800000, v138
	s_nop 0
	v_cndmask_b32_e32 v138, v138, v139, vcc
	v_rsq_f32_e32 v138, v138
	s_nop 0
	v_mul_f32_e32 v139, 0x45800000, v138
	v_cndmask_b32_e32 v150, v138, v139, vcc
	v_lshlrev_b64 v[138:139], 10, v[140:141]
	v_lshl_add_u64 v[152:153], s[12:13], 0, v[138:139]
	v_lshlrev_b64 v[138:139], 2, v[134:135]
	v_lshl_add_u64 v[134:135], v[152:153], 0, v[138:139]
	v_pk_mul_f32 v[114:115], v[114:115], v[150:151] op_sel_hi:[1,0]
	v_pk_mul_f32 v[112:113], v[112:113], v[150:151] op_sel_hi:[1,0]
	global_store_dwordx4 v[134:135], v[112:115], off offset:576
	v_pk_mul_f32 v[126:127], v[126:127], v[150:151] op_sel_hi:[1,0]
	v_pk_mul_f32 v[124:125], v[124:125], v[150:151] op_sel_hi:[1,0]
	v_or_b32_e32 v112, 16, v140
	v_pk_mul_f32 v[122:123], v[122:123], v[150:151] op_sel_hi:[1,0]
	v_pk_mul_f32 v[120:121], v[120:121], v[150:151] op_sel_hi:[1,0]
	v_pk_mul_f32 v[118:119], v[118:119], v[150:151] op_sel_hi:[1,0]
	v_pk_mul_f32 v[116:117], v[116:117], v[150:151] op_sel_hi:[1,0]
	v_ashrrev_i32_e32 v113, 31, v112
	global_store_dwordx4 v[134:135], v[124:127], off
	global_store_dwordx4 v[134:135], v[120:123], off offset:64
	global_store_dwordx4 v[134:135], v[116:119], off offset:512
	v_lshl_add_u64 v[114:115], v[112:113], 3, s[10:11]
	s_nop 1
	v_mov_b64_e32 v[114:115], v[208:209]
	v_lshlrev_b64 v[112:113], 10, v[112:113]
	v_lshl_add_u64 v[112:113], s[12:13], 0, v[112:113]
	v_lshl_add_u64 v[112:113], v[112:113], 0, v[138:139]
	v_cvt_f64_u32_e32 v[116:117], v115
	v_ldexp_f64 v[116:117], v[116:117], 32
	v_cvt_f64_u32_e32 v[114:115], v114
	v_add_f64 v[114:115], v[116:117], v[114:115]
	v_ldexp_f64 v[114:115], v[114:115], s93
	v_cvt_f32_f64_e32 v114, v[114:115]
	v_fmamk_f32 v114, v114, 0x3a000000, v189
	v_cmp_gt_f32_e32 vcc, s78, v114
; __device__ __forceinline__ float rinv_st(stat_t s, float invn) { return rsqrtf((float)((double)s * (1.0 / 4294967296.0)) * invn + 1e-6f); }
;     __device__ __forceinline__ void operator()(const f32x4 (&acc)[2][2][4][2], const Unit& u, int wr, int wc, int fr, int fq) const {
;         const int row0 = u.pm * BM + wr * 64 + fr, col0 = u.pn * BM + wc * 32 + 4 * fq;
; #pragma unroll
;         for (int ai = 0; ai < 2; ++ai)
; #pragma unroll
;             for (int m = 0; m < 4; ++m) {
;                 const int row = row0 + ai * HALF + m * 16; const float r = rinv_st(stats[row], 1.0f / 2048.0f);
;                 float* rowp = raw + (size_t)row * 256 + col0;
; #pragma unroll
;                 for (int bj = 0; bj < 2; ++bj)
; #pragma unroll
;                     for (int n = 0; n < 2; ++n) *(f32x4*)(rowp + bj * HALF + n * 16) = acc[ai][bj][m][n] * r;
	v_mul_f32_e32 v115, 0x4b800000, v114
	s_nop 0
	v_cndmask_b32_e32 v114, v114, v115, vcc
	v_rsq_f32_e32 v114, v114
	s_nop 0
	v_mul_f32_e32 v115, 0x45800000, v114
	v_cndmask_b32_e32 v114, v114, v115, vcc
	v_pk_mul_f32 v[98:99], v[98:99], v[114:115] op_sel_hi:[1,0]
	v_pk_mul_f32 v[96:97], v[96:97], v[114:115] op_sel_hi:[1,0]
	global_store_dwordx4 v[112:113], v[96:99], off offset:576
	v_pk_mul_f32 v[110:111], v[110:111], v[114:115] op_sel_hi:[1,0]
	v_pk_mul_f32 v[108:109], v[108:109], v[114:115] op_sel_hi:[1,0]
	v_or_b32_e32 v96, 32, v140
	v_pk_mul_f32 v[106:107], v[106:107], v[114:115] op_sel_hi:[1,0]
	v_pk_mul_f32 v[104:105], v[104:105], v[114:115] op_sel_hi:[1,0]
	v_pk_mul_f32 v[102:103], v[102:103], v[114:115] op_sel_hi:[1,0]
	v_pk_mul_f32 v[100:101], v[100:101], v[114:115] op_sel_hi:[1,0]
	v_ashrrev_i32_e32 v97, 31, v96
	global_store_dwordx4 v[112:113], v[108:111], off
	global_store_dwordx4 v[112:113], v[104:107], off offset:64
	global_store_dwordx4 v[112:113], v[100:103], off offset:512
	v_lshl_add_u64 v[98:99], v[96:97], 3, s[10:11]
	s_nop 1
	v_mov_b64_e32 v[98:99], v[210:211]
	v_lshlrev_b64 v[96:97], 10, v[96:97]
	v_lshl_add_u64 v[96:97], s[12:13], 0, v[96:97]
	v_lshl_add_u64 v[96:97], v[96:97], 0, v[138:139]
	v_cvt_f64_u32_e32 v[100:101], v99
	v_ldexp_f64 v[100:101], v[100:101], 32
	v_cvt_f64_u32_e32 v[98:99], v98
	v_add_f64 v[98:99], v[100:101], v[98:99]
	v_ldexp_f64 v[98:99], v[98:99], s93
	v_cvt_f32_f64_e32 v98, v[98:99]
	v_fmamk_f32 v98, v98, 0x3a000000, v189
	v_cmp_gt_f32_e32 vcc, s78, v98
	v_mul_f32_e32 v99, 0x4b800000, v98
	s_nop 0
	v_cndmask_b32_e32 v98, v98, v99, vcc
	v_rsq_f32_e32 v98, v98
	s_nop 0
	v_mul_f32_e32 v99, 0x45800000, v98
	v_cndmask_b32_e32 v98, v98, v99, vcc
	v_pk_mul_f32 v[82:83], v[82:83], v[98:99] op_sel_hi:[1,0]
	v_pk_mul_f32 v[80:81], v[80:81], v[98:99] op_sel_hi:[1,0]
	global_store_dwordx4 v[96:97], v[80:83], off offset:576
	v_pk_mul_f32 v[94:95], v[94:95], v[98:99] op_sel_hi:[1,0]
	v_pk_mul_f32 v[92:93], v[92:93], v[98:99] op_sel_hi:[1,0]
	v_or_b32_e32 v80, 48, v140
	v_pk_mul_f32 v[90:91], v[90:91], v[98:99] op_sel_hi:[1,0]
	v_pk_mul_f32 v[88:89], v[88:89], v[98:99] op_sel_hi:[1,0]
	v_pk_mul_f32 v[86:87], v[86:87], v[98:99] op_sel_hi:[1,0]
	v_pk_mul_f32 v[84:85], v[84:85], v[98:99] op_sel_hi:[1,0]
	v_ashrrev_i32_e32 v81, 31, v80
	global_store_dwordx4 v[96:97], v[92:95], off
	global_store_dwordx4 v[96:97], v[88:91], off offset:64
	global_store_dwordx4 v[96:97], v[84:87], off offset:512
	v_lshl_add_u64 v[82:83], v[80:81], 3, s[10:11]
	s_nop 1
	v_mov_b64_e32 v[82:83], v[212:213]
	v_lshlrev_b64 v[80:81], 10, v[80:81]
	v_lshl_add_u64 v[80:81], s[12:13], 0, v[80:81]
	v_lshl_add_u64 v[80:81], v[80:81], 0, v[138:139]
	v_cvt_f64_u32_e32 v[84:85], v83
	v_ldexp_f64 v[84:85], v[84:85], 32
	v_cvt_f64_u32_e32 v[82:83], v82
	v_add_f64 v[82:83], v[84:85], v[82:83]
	v_ldexp_f64 v[82:83], v[82:83], s93
	v_cvt_f32_f64_e32 v82, v[82:83]
	v_fmamk_f32 v82, v82, 0x3a000000, v189
	v_cmp_gt_f32_e32 vcc, s78, v82
	v_mul_f32_e32 v83, 0x4b800000, v82
	s_nop 0
	v_cndmask_b32_e32 v82, v82, v83, vcc
	v_rsq_f32_e32 v82, v82
	s_nop 0
	v_mul_f32_e32 v83, 0x45800000, v82
	v_cndmask_b32_e32 v82, v82, v83, vcc
	v_pk_mul_f32 v[78:79], v[78:79], v[82:83] op_sel_hi:[1,0]
	v_pk_mul_f32 v[76:77], v[76:77], v[82:83] op_sel_hi:[1,0]
	v_pk_mul_f32 v[74:75], v[74:75], v[82:83] op_sel_hi:[1,0]
	v_pk_mul_f32 v[72:73], v[72:73], v[82:83] op_sel_hi:[1,0]
	v_pk_mul_f32 v[70:71], v[70:71], v[82:83] op_sel_hi:[1,0]
	v_pk_mul_f32 v[68:69], v[68:69], v[82:83] op_sel_hi:[1,0]
	v_pk_mul_f32 v[66:67], v[66:67], v[82:83] op_sel_hi:[1,0]
	v_pk_mul_f32 v[64:65], v[64:65], v[82:83] op_sel_hi:[1,0]
	global_store_dwordx4 v[80:81], v[76:79], off
	global_store_dwordx4 v[80:81], v[72:75], off offset:64
	global_store_dwordx4 v[80:81], v[68:71], off offset:512
	global_store_dwordx4 v[80:81], v[64:67], off offset:576
	s_nop 1
	v_mov_b64_e32 v[64:65], v[214:215]
	v_cvt_f64_u32_e32 v[66:67], v65
	v_ldexp_f64 v[66:67], v[66:67], 32
	v_cvt_f64_u32_e32 v[64:65], v64
	v_add_f64 v[64:65], v[66:67], v[64:65]
	v_ldexp_f64 v[64:65], v[64:65], s93
	v_cvt_f32_f64_e32 v64, v[64:65]
	v_fmamk_f32 v64, v64, 0x3a000000, v189
	v_cmp_gt_f32_e32 vcc, s78, v64
	v_mul_f32_e32 v65, 0x4b800000, v64
	v_lshl_add_u64 v[66:67], v[134:135], 0, s[26:27]
	v_cndmask_b32_e32 v64, v64, v65, vcc
	v_rsq_f32_e32 v64, v64
	s_mov_b64 s[26:27], 0x24000
	v_mul_f32_e32 v65, 0x45800000, v64
	v_cndmask_b32_e32 v64, v64, v65, vcc
	v_add_co_u32_e32 v68, vcc, s15, v134
	v_pk_mul_f32 v[62:63], v[62:63], v[64:65] op_sel_hi:[1,0]
	v_pk_mul_f32 v[60:61], v[60:61], v[64:65] op_sel_hi:[1,0]
	v_addc_co_u32_e32 v69, vcc, 0, v135, vcc
	v_pk_mul_f32 v[58:59], v[58:59], v[64:65] op_sel_hi:[1,0]
	v_pk_mul_f32 v[56:57], v[56:57], v[64:65] op_sel_hi:[1,0]
; __device__ __forceinline__ float rinv_st(stat_t s, float invn) { return rsqrtf((float)((double)s * (1.0 / 4294967296.0)) * invn + 1e-6f); }
; #define PG8_WAIT_V(n) asm volatile("s_waitcnt vmcnt(" #n ")" ::: "memory")
; #define PG8_BAR __builtin_amdgcn_s_barrier()
; template <class Epi>
; __device__ __forceinline__ void gemm_phase(const int TID, const int BID, LAS unsigned char* lds, const Gemm g, const StaticOrder& S, const Epi& E) {
;     ...
;     PG8_WAIT_V(0);
;     if (wr == 0) PG8_BAR;
;     PG8_BAR;
;     __device__ __forceinline__ void operator()(const f32x4 (&acc)[2][2][4][2], const Unit& u, int wr, int wc, int fr, int fq) const {
;         const int row0 = u.pm * BM + wr * 64 + fr, col0 = u.pn * BM + wc * 32 + 4 * fq;
; #pragma unroll
;         for (int ai = 0; ai < 2; ++ai)
; #pragma unroll
;             for (int m = 0; m < 4; ++m) {
;                 const int row = row0 + ai * HALF + m * 16; const float r = rinv_st(stats[row], 1.0f / 2048.0f);
;                 float* rowp = raw + (size_t)row * 256 + col0;
; #pragma unroll
;                 for (int bj = 0; bj < 2; ++bj)
; #pragma unroll
;                     for (int n = 0; n < 2; ++n) *(f32x4*)(rowp + bj * HALF + n * 16) = acc[ai][bj][m][n] * r;
	v_pk_mul_f32 v[54:55], v[54:55], v[64:65] op_sel_hi:[1,0]
	v_pk_mul_f32 v[52:53], v[52:53], v[64:65] op_sel_hi:[1,0]
	v_pk_mul_f32 v[50:51], v[50:51], v[64:65] op_sel_hi:[1,0]
	v_pk_mul_f32 v[48:49], v[48:49], v[64:65] op_sel_hi:[1,0]
	global_store_dwordx4 v[68:69], v[60:63], off
	global_store_dwordx4 v[66:67], v[56:59], off offset:64
	global_store_dwordx4 v[66:67], v[52:55], off offset:512
	global_store_dwordx4 v[66:67], v[48:51], off offset:576
	s_nop 1
	v_mov_b64_e32 v[48:49], v[216:217]
	s_mov_b32 s15, 0x24000
	v_cvt_f64_u32_e32 v[50:51], v49
	v_ldexp_f64 v[50:51], v[50:51], 32
	v_cvt_f64_u32_e32 v[48:49], v48
	v_add_f64 v[48:49], v[50:51], v[48:49]
	v_ldexp_f64 v[48:49], v[48:49], s93
	v_cvt_f32_f64_e32 v48, v[48:49]
	v_fmamk_f32 v48, v48, 0x3a000000, v189
	v_cmp_gt_f32_e32 vcc, s78, v48
	v_mul_f32_e32 v49, 0x4b800000, v48
	v_lshl_add_u64 v[50:51], v[134:135], 0, s[26:27]
	v_cndmask_b32_e32 v48, v48, v49, vcc
	v_rsq_f32_e32 v48, v48
	s_mov_b64 s[26:27], 0x28000
	v_mul_f32_e32 v49, 0x45800000, v48
	v_cndmask_b32_e32 v48, v48, v49, vcc
	v_add_co_u32_e32 v52, vcc, s15, v134
	v_pk_mul_f32 v[46:47], v[46:47], v[48:49] op_sel_hi:[1,0]
	v_pk_mul_f32 v[44:45], v[44:45], v[48:49] op_sel_hi:[1,0]
	v_addc_co_u32_e32 v53, vcc, 0, v135, vcc
	v_pk_mul_f32 v[42:43], v[42:43], v[48:49] op_sel_hi:[1,0]
	v_pk_mul_f32 v[40:41], v[40:41], v[48:49] op_sel_hi:[1,0]
	v_pk_mul_f32 v[38:39], v[38:39], v[48:49] op_sel_hi:[1,0]
	v_pk_mul_f32 v[36:37], v[36:37], v[48:49] op_sel_hi:[1,0]
	v_pk_mul_f32 v[34:35], v[34:35], v[48:49] op_sel_hi:[1,0]
	v_pk_mul_f32 v[32:33], v[32:33], v[48:49] op_sel_hi:[1,0]
	global_store_dwordx4 v[52:53], v[44:47], off
	global_store_dwordx4 v[50:51], v[40:43], off offset:64
	global_store_dwordx4 v[50:51], v[36:39], off offset:512
	global_store_dwordx4 v[50:51], v[32:35], off offset:576
	s_nop 1
	v_mov_b64_e32 v[32:33], v[218:219]
	s_mov_b32 s15, 0x28000
	v_cvt_f64_u32_e32 v[34:35], v33
	v_ldexp_f64 v[34:35], v[34:35], 32
	v_cvt_f64_u32_e32 v[32:33], v32
	v_add_f64 v[32:33], v[34:35], v[32:33]
	v_ldexp_f64 v[32:33], v[32:33], s93
	v_cvt_f32_f64_e32 v32, v[32:33]
	v_fmamk_f32 v32, v32, 0x3a000000, v189
	v_cmp_gt_f32_e32 vcc, s78, v32
	v_mul_f32_e32 v33, 0x4b800000, v32
	v_lshl_add_u64 v[34:35], v[134:135], 0, s[26:27]
	v_cndmask_b32_e32 v32, v32, v33, vcc
	v_rsq_f32_e32 v32, v32
	s_mov_b64 s[26:27], 0x2c000
	v_mul_f32_e32 v33, 0x45800000, v32
	v_cndmask_b32_e32 v32, v32, v33, vcc
	v_add_co_u32_e32 v36, vcc, s15, v134
	v_pk_mul_f32 v[30:31], v[30:31], v[32:33] op_sel_hi:[1,0]
	v_pk_mul_f32 v[28:29], v[28:29], v[32:33] op_sel_hi:[1,0]
	v_addc_co_u32_e32 v37, vcc, 0, v135, vcc
	v_pk_mul_f32 v[26:27], v[26:27], v[32:33] op_sel_hi:[1,0]
	v_pk_mul_f32 v[24:25], v[24:25], v[32:33] op_sel_hi:[1,0]
	v_pk_mul_f32 v[22:23], v[22:23], v[32:33] op_sel_hi:[1,0]
	v_pk_mul_f32 v[20:21], v[20:21], v[32:33] op_sel_hi:[1,0]
	v_pk_mul_f32 v[18:19], v[18:19], v[32:33] op_sel_hi:[1,0]
	v_pk_mul_f32 v[16:17], v[16:17], v[32:33] op_sel_hi:[1,0]
	global_store_dwordx4 v[36:37], v[28:31], off
	global_store_dwordx4 v[34:35], v[24:27], off offset:64
	global_store_dwordx4 v[34:35], v[20:23], off offset:512
	global_store_dwordx4 v[34:35], v[16:19], off offset:576
	s_nop 1
	v_mov_b64_e32 v[16:17], v[220:221]
	s_mov_b32 s15, 0x2c000
	v_cvt_f64_u32_e32 v[18:19], v17
	v_ldexp_f64 v[18:19], v[18:19], 32
	v_cvt_f64_u32_e32 v[16:17], v16
	v_add_f64 v[16:17], v[18:19], v[16:17]
	v_ldexp_f64 v[16:17], v[16:17], s93
	v_cvt_f32_f64_e32 v16, v[16:17]
	v_fmamk_f32 v16, v16, 0x3a000000, v189
	v_cmp_gt_f32_e32 vcc, s78, v16
	v_mul_f32_e32 v17, 0x4b800000, v16
	v_lshl_add_u64 v[18:19], v[134:135], 0, s[26:27]
	v_cndmask_b32_e32 v16, v16, v17, vcc
	v_rsq_f32_e32 v16, v16
	s_mov_b64 s[26:27], s[20:21]
	v_mul_f32_e32 v17, 0x45800000, v16
	v_cndmask_b32_e32 v16, v16, v17, vcc
	v_add_co_u32_e32 v20, vcc, s15, v134
	v_pk_mul_f32 v[14:15], v[14:15], v[16:17] op_sel_hi:[1,0]
	s_nop 0
	v_addc_co_u32_e32 v21, vcc, 0, v135, vcc
	v_pk_mul_f32 v[12:13], v[12:13], v[16:17] op_sel_hi:[1,0]
	v_pk_mul_f32 v[10:11], v[10:11], v[16:17] op_sel_hi:[1,0]
	v_pk_mul_f32 v[8:9], v[8:9], v[16:17] op_sel_hi:[1,0]
	v_pk_mul_f32 v[6:7], v[6:7], v[16:17] op_sel_hi:[1,0]
	v_pk_mul_f32 v[4:5], v[4:5], v[16:17] op_sel_hi:[1,0]
	v_pk_mul_f32 v[2:3], v[2:3], v[16:17] op_sel_hi:[1,0]
	v_pk_mul_f32 v[0:1], v[0:1], v[16:17] op_sel_hi:[1,0]
	s_and_b64 vcc, exec, s[18:19]
	global_store_dwordx4 v[20:21], v[12:15], off
	global_store_dwordx4 v[18:19], v[8:11], off offset:64
	global_store_dwordx4 v[18:19], v[4:7], off offset:512
	global_store_dwordx4 v[18:19], v[0:3], off offset:576
	s_cbranch_vccz .LBB0_815
	s_waitcnt vmcnt(0)
	s_cmpk_gt_u32 s42, 0xff
	s_cbranch_scc1 .LBB0_805
	s_barrier
	s_branch .LBB0_805

; #define PG8_STAGE(bufoff, gbase, voff) do { _Pragma("unroll") for (int _i = 0; _i < 2; ++_i) \
;         __builtin_amdgcn_global_load_lds((const unsigned*)((const char*)(gbase) + (voff)[_i]), (LAS unsigned*)(lds + (bufoff) + ldsw + _i * 8192), 16, 0, 0); } while (0)
; #define PG8_LDA(dst, b, h) do { _Pragma("unroll") for (int m = 0; m < 4; ++m) _Pragma("unroll") for (int k = 0; k < 2; ++k) dst[m][k] = *(const LAS bf16x8*)(lds + PG8_SA(b, h) + aoff + m * 2048 + k * 1024); } while (0)
; #define PG8_LDB(dst, b, h) do { _Pragma("unroll") for (int n = 0; n < 2; ++n) _Pragma("unroll") for (int k = 0; k < 2; ++k) dst[n][k] = *(const LAS bf16x8*)(lds + PG8_SB(b, h) + boff + n * 2048 + k * 1024); } while (0)
; #define PG8_MMA(ai, bj, At, Bt) do { __builtin_amdgcn_s_setprio(1); _Pragma("unroll") for (int m = 0; m < 4; ++m) _Pragma("unroll") for (int n = 0; n < 2; ++n) _Pragma("unroll") for (int k = 0; k < 2; ++k) \
;         acc[ai][bj][m][n] = __builtin_amdgcn_mfma_f32_16x16x32_bf16(Bt[n][k], At[m][k], acc[ai][bj][m][n], 0, 0, 0); __builtin_amdgcn_s_setprio(0); } while (0)
; #define PG8_WAIT_L(n) asm volatile("s_waitcnt lgkmcnt(" #n ")" ::: "memory")
; #define PG8_BAR __builtin_amdgcn_s_barrier()
; #define PG8_SCHED __builtin_amdgcn_sched_barrier(0)
; template <class Epi>
; __device__ __forceinline__ void gemm_phase(const int TID, const int BID, LAS unsigned char* lds, const Gemm g, const StaticOrder& S, const Epi& E) {
;     ...
;         for (int t = 0; t < nt; t += 2) {
;             const bool last = (t == nt - 2);
;             const char* a1 = cA + (size_t)(t + 1) * kstep;
;             const char* a2 = last ? nA : cA + (size_t)(t + 2) * kstep; const char* b2 = last ? nB : cB + (size_t)(t + 2) * kstep;
;             const char* a3 = a2 + kstep; const char* b3 = b2 + kstep;
;             PG8_LDB(B0, 0, 0); PG8_SCHED; PG8_LDA(At, 0, 0); PG8_STAGE(PG8_SA(1, 1), a1 + hstepA, voffA);
;             PG8_WAIT_L(8); PG8_BAR; PG8_WAIT_L(0); PG8_MMA(0, 0, At, B0); PG8_BAR; PG8_SCHED;
;             PG8_LDB(B1, 0, 1); PG8_STAGE(PG8_SB(0, 0), b2, voffB);
;             PG8_BAR; PG8_WAIT_L(0); PG8_MMA(0, 1, At, B1); PG8_BAR;
;             PG8_LDA(At, 0, 1); PG8_STAGE(PG8_SA(0, 0), a2, voffA);
;             PG8_BAR; PG8_WAIT_L(0); PG8_MMA(1, 0, At, B0); PG8_BAR; PG8_SCHED;
.LBB0_864:
	v_add_u32_e32 v36, s43, v172
	ds_read_b128 v[8:11], v36
	ds_read_b128 v[12:15], v36 offset:1024
	ds_read_b128 v[32:35], v36 offset:2048
	ds_read_b128 v[36:39], v36 offset:3072
	s_add_u32 s36, s34, 0xfff80080
	s_addc_u32 s37, s35, -1
	s_cmp_eq_u32 s31, 28
	s_cselect_b32 s39, s0, s37
	s_cselect_b32 s38, s1, s36
	s_cselect_b32 s37, s4, s29
	s_cselect_b32 s36, s21, s23
	v_lshl_add_u64 v[158:159], s[34:35], 0, v[150:151]
	s_add_i32 m0, s46, 0xc000
	ds_read_b128 v[154:157], v174
	ds_read_b128 v[176:179], v174 offset:1024
	ds_read_b128 v[180:183], v174 offset:2048
	ds_read_b128 v[196:199], v174 offset:3072
	ds_read_b128 v[208:211], v174 offset:4096
	ds_read_b128 v[212:215], v174 offset:5120
	ds_read_b128 v[216:219], v174 offset:6144
	ds_read_b128 v[220:223], v174 offset:7168
	global_load_lds_dwordx4 v[158:159], off
	s_add_i32 m0, s46, 0xe000
	v_lshl_add_u64 v[158:159], s[34:35], 0, v[152:153]
	global_load_lds_dwordx4 v[158:159], off
	s_waitcnt lgkmcnt(8)
	s_barrier
	s_waitcnt lgkmcnt(0)
	s_setprio 1
	v_mfma_f32_16x16x32_bf16 v[140:143], v[8:11], v[154:157], v[140:143]
	v_mfma_f32_16x16x32_bf16 v[136:139], v[32:35], v[154:157], v[136:139]
	v_mfma_f32_16x16x32_bf16 v[124:127], v[8:11], v[180:183], v[124:127]
	v_mfma_f32_16x16x32_bf16 v[120:123], v[32:35], v[180:183], v[120:123]
	v_mfma_f32_16x16x32_bf16 v[108:111], v[8:11], v[208:211], v[108:111]
	v_mfma_f32_16x16x32_bf16 v[104:107], v[32:35], v[208:211], v[104:107]
	v_mfma_f32_16x16x32_bf16 v[92:95], v[8:11], v[216:219], v[92:95]
	v_mfma_f32_16x16x32_bf16 v[88:91], v[32:35], v[216:219], v[88:91]
	v_mfma_f32_16x16x32_bf16 v[140:143], v[12:15], v[176:179], v[140:143]
	v_mfma_f32_16x16x32_bf16 v[136:139], v[36:39], v[176:179], v[136:139]
	v_mfma_f32_16x16x32_bf16 v[124:127], v[12:15], v[196:199], v[124:127]
	v_mfma_f32_16x16x32_bf16 v[120:123], v[36:39], v[196:199], v[120:123]
	v_mfma_f32_16x16x32_bf16 v[108:111], v[12:15], v[212:215], v[108:111]
	v_mfma_f32_16x16x32_bf16 v[104:107], v[36:39], v[212:215], v[104:107]
	v_mfma_f32_16x16x32_bf16 v[92:95], v[12:15], v[220:223], v[92:95]
	v_mfma_f32_16x16x32_bf16 v[88:91], v[36:39], v[220:223], v[88:91]
	s_setprio 0
	s_barrier
	v_add_u32_e32 v158, s48, v172
	s_mov_b32 m0, s44
	ds_read_b128 v[224:227], v158
	ds_read_b128 v[228:231], v158 offset:1024
	ds_read_b128 v[232:235], v158 offset:2048
	ds_read_b128 v[236:239], v158 offset:3072
	v_lshl_add_u64 v[158:159], s[36:37], 0, v[160:161]
	global_load_lds_dwordx4 v[158:159], off
	s_mov_b32 m0, s45
	v_lshl_add_u64 v[166:167], s[36:37], 0, v[148:149]
	global_load_lds_dwordx4 v[166:167], off
	s_barrier
	s_waitcnt lgkmcnt(0)
	s_setprio 1
	v_mfma_f32_16x16x32_bf16 v[132:135], v[224:227], v[154:157], v[132:135]
	v_mfma_f32_16x16x32_bf16 v[128:131], v[232:235], v[154:157], v[128:131]
	v_mfma_f32_16x16x32_bf16 v[116:119], v[224:227], v[180:183], v[116:119]
	v_mfma_f32_16x16x32_bf16 v[112:115], v[232:235], v[180:183], v[112:115]
	v_mfma_f32_16x16x32_bf16 v[100:103], v[224:227], v[208:211], v[100:103]
	v_mfma_f32_16x16x32_bf16 v[96:99], v[232:235], v[208:211], v[96:99]
	v_mfma_f32_16x16x32_bf16 v[84:87], v[224:227], v[216:219], v[84:87]
	v_mfma_f32_16x16x32_bf16 v[80:83], v[232:235], v[216:219], v[80:83]
	v_mfma_f32_16x16x32_bf16 v[132:135], v[228:231], v[176:179], v[132:135]
	v_mfma_f32_16x16x32_bf16 v[128:131], v[236:239], v[176:179], v[128:131]
	v_mfma_f32_16x16x32_bf16 v[116:119], v[228:231], v[196:199], v[116:119]
	v_mfma_f32_16x16x32_bf16 v[112:115], v[236:239], v[196:199], v[112:115]
	v_mfma_f32_16x16x32_bf16 v[100:103], v[228:231], v[212:215], v[100:103]
	v_mfma_f32_16x16x32_bf16 v[96:99], v[236:239], v[212:215], v[96:99]
	v_mfma_f32_16x16x32_bf16 v[84:87], v[228:231], v[220:223], v[84:87]
	v_mfma_f32_16x16x32_bf16 v[80:83], v[236:239], v[220:223], v[80:83]
	s_setprio 0
	s_mov_b32 m0, s46
	v_lshl_add_u64 v[170:171], s[38:39], 0, v[144:145]
	s_barrier
	ds_read_b128 v[154:157], v174 offset:16384
	ds_read_b128 v[176:179], v174 offset:17408
	ds_read_b128 v[180:183], v174 offset:18432
	ds_read_b128 v[196:199], v174 offset:19456
	ds_read_b128 v[208:211], v174 offset:20480
	ds_read_b128 v[212:215], v174 offset:21504
	ds_read_b128 v[216:219], v174 offset:22528
	ds_read_b128 v[220:223], v174 offset:23552
	global_load_lds_dwordx4 v[170:171], off
	s_mov_b32 m0, s47
	v_lshl_add_u64 v[184:185], s[38:39], 0, v[146:147]
	global_load_lds_dwordx4 v[184:185], off
	s_barrier
	s_waitcnt lgkmcnt(0)
	s_setprio 1
	v_mfma_f32_16x16x32_bf16 v[76:79], v[8:11], v[154:157], v[76:79]
	v_mfma_f32_16x16x32_bf16 v[72:75], v[32:35], v[154:157], v[72:75]
	v_mfma_f32_16x16x32_bf16 v[60:63], v[8:11], v[180:183], v[60:63]
	v_mfma_f32_16x16x32_bf16 v[56:59], v[32:35], v[180:183], v[56:59]
	v_mfma_f32_16x16x32_bf16 v[44:47], v[8:11], v[208:211], v[44:47]
	v_mfma_f32_16x16x32_bf16 v[40:43], v[32:35], v[208:211], v[40:43]
	v_mfma_f32_16x16x32_bf16 v[8:11], v[8:11], v[216:219], v[20:23]
	v_mfma_f32_16x16x32_bf16 v[76:79], v[12:15], v[176:179], v[76:79]
	v_mfma_f32_16x16x32_bf16 v[72:75], v[36:39], v[176:179], v[72:75]
	v_mfma_f32_16x16x32_bf16 v[60:63], v[12:15], v[196:199], v[60:63]
	v_mfma_f32_16x16x32_bf16 v[56:59], v[36:39], v[196:199], v[56:59]
	v_mfma_f32_16x16x32_bf16 v[44:47], v[12:15], v[212:215], v[44:47]
	v_mfma_f32_16x16x32_bf16 v[40:43], v[36:39], v[212:215], v[40:43]
	v_mfma_f32_16x16x32_bf16 v[8:11], v[12:15], v[220:223], v[8:11]
	v_mfma_f32_16x16x32_bf16 v[12:15], v[32:35], v[216:219], v[16:19]
	v_mfma_f32_16x16x32_bf16 v[12:15], v[36:39], v[220:223], v[12:15]
	s_setprio 0
	s_barrier
; #define PG8_STAGE(bufoff, gbase, voff) do { _Pragma("unroll") for (int _i = 0; _i < 2; ++_i) \
;         __builtin_amdgcn_global_load_lds((const unsigned*)((const char*)(gbase) + (voff)[_i]), (LAS unsigned*)(lds + (bufoff) + ldsw + _i * 8192), 16, 0, 0); } while (0)
; #define PG8_LDA(dst, b, h) do { _Pragma("unroll") for (int m = 0; m < 4; ++m) _Pragma("unroll") for (int k = 0; k < 2; ++k) dst[m][k] = *(const LAS bf16x8*)(lds + PG8_SA(b, h) + aoff + m * 2048 + k * 1024); } while (0)
; #define PG8_LDB(dst, b, h) do { _Pragma("unroll") for (int n = 0; n < 2; ++n) _Pragma("unroll") for (int k = 0; k < 2; ++k) dst[n][k] = *(const LAS bf16x8*)(lds + PG8_SB(b, h) + boff + n * 2048 + k * 1024); } while (0)
; #define PG8_MMA(ai, bj, At, Bt) do { __builtin_amdgcn_s_setprio(1); _Pragma("unroll") for (int m = 0; m < 4; ++m) _Pragma("unroll") for (int n = 0; n < 2; ++n) _Pragma("unroll") for (int k = 0; k < 2; ++k) \
;         acc[ai][bj][m][n] = __builtin_amdgcn_mfma_f32_16x16x32_bf16(Bt[n][k], At[m][k], acc[ai][bj][m][n], 0, 0, 0); __builtin_amdgcn_s_setprio(0); } while (0)
; #define PG8_WAIT_V(n) asm volatile("s_waitcnt vmcnt(" #n ")" ::: "memory")
; #define PG8_WAIT_L(n) asm volatile("s_waitcnt lgkmcnt(" #n ")" ::: "memory")
; #define PG8_BAR __builtin_amdgcn_s_barrier()
; #define PG8_SCHED __builtin_amdgcn_sched_barrier(0)
; template <class Epi>
; __device__ __forceinline__ void gemm_phase(const int TID, const int BID, LAS unsigned char* lds, const Gemm g, const StaticOrder& S, const Epi& E) {
;     ...
;             PG8_STAGE(PG8_SB(0, 1), b2 + hstepB, voffB);
;             PG8_WAIT_V(6); PG8_BAR; PG8_MMA(1, 1, At, B1); PG8_BAR;
;             PG8_LDB(B0, 1, 0); PG8_SCHED; PG8_LDA(At, 1, 0); PG8_STAGE(PG8_SA(0, 1), a2 + hstepA, voffA);
;             PG8_WAIT_L(8); PG8_BAR; PG8_WAIT_L(0); PG8_MMA(0, 0, At, B0); PG8_BAR; PG8_SCHED;
;             PG8_LDB(B1, 1, 1); PG8_STAGE(PG8_SB(1, 0), b3, voffB);
;             PG8_BAR; PG8_WAIT_L(0); PG8_MMA(0, 1, At, B1); PG8_BAR;
	s_add_u32 s66, s36, 0x80000
	s_addc_u32 s67, s37, 0
	s_mov_b32 m0, s49
	v_lshl_add_u64 v[16:17], s[66:67], 0, v[160:161]
	global_load_lds_dwordx4 v[16:17], off
	s_mov_b32 m0, s50
	v_lshl_add_u64 v[16:17], s[66:67], 0, v[148:149]
	global_load_lds_dwordx4 v[16:17], off
	s_waitcnt vmcnt(6)
	s_barrier
	s_setprio 1
	v_mfma_f32_16x16x32_bf16 v[16:19], v[224:227], v[154:157], v[68:71]
	v_mfma_f32_16x16x32_bf16 v[32:35], v[228:231], v[176:179], v[16:19]
	v_mfma_f32_16x16x32_bf16 v[16:19], v[232:235], v[154:157], v[64:67]
	v_mfma_f32_16x16x32_bf16 v[36:39], v[236:239], v[176:179], v[16:19]
	v_mfma_f32_16x16x32_bf16 v[16:19], v[224:227], v[180:183], v[52:55]
	v_mfma_f32_16x16x32_bf16 v[52:55], v[228:231], v[196:199], v[16:19]
	v_mfma_f32_16x16x32_bf16 v[16:19], v[232:235], v[180:183], v[48:51]
	v_mfma_f32_16x16x32_bf16 v[48:51], v[236:239], v[196:199], v[16:19]
	v_mfma_f32_16x16x32_bf16 v[16:19], v[224:227], v[208:211], v[28:31]
	v_mfma_f32_16x16x32_bf16 v[28:31], v[228:231], v[212:215], v[16:19]
	v_mfma_f32_16x16x32_bf16 v[16:19], v[232:235], v[208:211], v[24:27]
	v_mfma_f32_16x16x32_bf16 v[4:7], v[224:227], v[216:219], v[4:7]
	v_mfma_f32_16x16x32_bf16 v[0:3], v[232:235], v[216:219], v[0:3]
	v_mfma_f32_16x16x32_bf16 v[24:27], v[236:239], v[212:215], v[16:19]
	v_mfma_f32_16x16x32_bf16 v[4:7], v[228:231], v[220:223], v[4:7]
	v_mfma_f32_16x16x32_bf16 v[0:3], v[236:239], v[220:223], v[0:3]
	s_setprio 0
	v_add_u32_e32 v68, s53, v172
	s_barrier
	ds_read_b128 v[16:19], v68
	ds_read_b128 v[20:23], v68 offset:1024
	ds_read_b128 v[64:67], v68 offset:2048
	ds_read_b128 v[68:71], v68 offset:3072
	s_add_u32 s38, s38, 0x80000
	s_addc_u32 s39, s39, 0
	s_mov_b32 m0, s51
	v_lshl_add_u64 v[200:201], s[38:39], 0, v[144:145]
	ds_read_b128 v[154:157], v174 offset:32768
	ds_read_b128 v[176:179], v174 offset:33792
	ds_read_b128 v[180:183], v174 offset:34816
	ds_read_b128 v[196:199], v174 offset:35840
	ds_read_b128 v[208:211], v174 offset:36864
	ds_read_b128 v[212:215], v174 offset:37888
	ds_read_b128 v[216:219], v174 offset:38912
	ds_read_b128 v[220:223], v174 offset:39936
	global_load_lds_dwordx4 v[200:201], off
	s_mov_b32 m0, s52
	v_lshl_add_u64 v[200:201], s[38:39], 0, v[146:147]
	global_load_lds_dwordx4 v[200:201], off
	s_waitcnt lgkmcnt(8)
	s_barrier
	s_waitcnt lgkmcnt(0)
	s_setprio 1
	v_mfma_f32_16x16x32_bf16 v[140:143], v[16:19], v[154:157], v[140:143]
	v_mfma_f32_16x16x32_bf16 v[136:139], v[64:67], v[154:157], v[136:139]
	v_mfma_f32_16x16x32_bf16 v[124:127], v[16:19], v[180:183], v[124:127]
	v_mfma_f32_16x16x32_bf16 v[120:123], v[64:67], v[180:183], v[120:123]
	v_mfma_f32_16x16x32_bf16 v[108:111], v[16:19], v[208:211], v[108:111]
	v_mfma_f32_16x16x32_bf16 v[104:107], v[64:67], v[208:211], v[104:107]
	v_mfma_f32_16x16x32_bf16 v[92:95], v[16:19], v[216:219], v[92:95]
	v_mfma_f32_16x16x32_bf16 v[88:91], v[64:67], v[216:219], v[88:91]
	v_mfma_f32_16x16x32_bf16 v[140:143], v[20:23], v[176:179], v[140:143]
	v_mfma_f32_16x16x32_bf16 v[136:139], v[68:71], v[176:179], v[136:139]
	v_mfma_f32_16x16x32_bf16 v[124:127], v[20:23], v[196:199], v[124:127]
	v_mfma_f32_16x16x32_bf16 v[120:123], v[68:71], v[196:199], v[120:123]
	v_mfma_f32_16x16x32_bf16 v[108:111], v[20:23], v[212:215], v[108:111]
	v_mfma_f32_16x16x32_bf16 v[104:107], v[68:71], v[212:215], v[104:107]
	v_mfma_f32_16x16x32_bf16 v[92:95], v[20:23], v[220:223], v[92:95]
	v_mfma_f32_16x16x32_bf16 v[88:91], v[68:71], v[220:223], v[88:91]
	s_setprio 0
	s_barrier
	s_mov_b32 m0, s54
	v_add_u32_e32 v168, s58, v172
	v_lshl_add_u64 v[158:159], v[158:159], 0, s[90:91]
	ds_read_b128 v[224:227], v168
	ds_read_b128 v[228:231], v168 offset:1024
	ds_read_b128 v[232:235], v168 offset:2048
	ds_read_b128 v[236:239], v168 offset:3072
	global_load_lds_dwordx4 v[158:159], off
	s_mov_b32 m0, s55
	v_lshl_add_u64 v[158:159], v[166:167], 0, s[90:91]
	global_load_lds_dwordx4 v[158:159], off
	s_barrier
	s_waitcnt lgkmcnt(0)
	s_setprio 1
	v_mfma_f32_16x16x32_bf16 v[132:135], v[224:227], v[154:157], v[132:135]
	v_mfma_f32_16x16x32_bf16 v[128:131], v[232:235], v[154:157], v[128:131]
	v_mfma_f32_16x16x32_bf16 v[116:119], v[224:227], v[180:183], v[116:119]
	v_mfma_f32_16x16x32_bf16 v[112:115], v[232:235], v[180:183], v[112:115]
	v_mfma_f32_16x16x32_bf16 v[100:103], v[224:227], v[208:211], v[100:103]
	v_mfma_f32_16x16x32_bf16 v[96:99], v[232:235], v[208:211], v[96:99]
	v_mfma_f32_16x16x32_bf16 v[84:87], v[224:227], v[216:219], v[84:87]
	v_mfma_f32_16x16x32_bf16 v[80:83], v[232:235], v[216:219], v[80:83]
	v_mfma_f32_16x16x32_bf16 v[132:135], v[228:231], v[176:179], v[132:135]
	v_mfma_f32_16x16x32_bf16 v[128:131], v[236:239], v[176:179], v[128:131]
	v_mfma_f32_16x16x32_bf16 v[116:119], v[228:231], v[196:199], v[116:119]
	v_mfma_f32_16x16x32_bf16 v[112:115], v[236:239], v[196:199], v[112:115]
	v_mfma_f32_16x16x32_bf16 v[100:103], v[228:231], v[212:215], v[100:103]
	v_mfma_f32_16x16x32_bf16 v[96:99], v[236:239], v[212:215], v[96:99]
	v_mfma_f32_16x16x32_bf16 v[84:87], v[228:231], v[220:223], v[84:87]
	v_mfma_f32_16x16x32_bf16 v[80:83], v[236:239], v[220:223], v[80:83]
	s_setprio 0
	s_mov_b32 m0, s56
	v_lshl_add_u64 v[158:159], v[170:171], 0, s[90:91]
	s_barrier
	ds_read_b128 v[154:157], v174 offset:49152
	ds_read_b128 v[176:179], v174 offset:50176
	ds_read_b128 v[180:183], v174 offset:51200
	ds_read_b128 v[196:199], v174 offset:52224
	ds_read_b128 v[208:211], v174 offset:53248
	ds_read_b128 v[212:215], v174 offset:54272
	ds_read_b128 v[216:219], v174 offset:55296
	ds_read_b128 v[220:223], v174 offset:56320
	global_load_lds_dwordx4 v[158:159], off
	s_mov_b32 m0, s57
	v_lshl_add_u64 v[158:159], v[184:185], 0, s[90:91]
	global_load_lds_dwordx4 v[158:159], off
	s_barrier
; __device__ __forceinline__ float rinv_st(stat_t s, float invn) { return rsqrtf((float)((double)s * (1.0 / 4294967296.0)) * invn + 1e-6f); }
; #define PG8_STAGE(bufoff, gbase, voff) do { _Pragma("unroll") for (int _i = 0; _i < 2; ++_i) \
;         __builtin_amdgcn_global_load_lds((const unsigned*)((const char*)(gbase) + (voff)[_i]), (LAS unsigned*)(lds + (bufoff) + ldsw + _i * 8192), 16, 0, 0); } while (0)
; #define PG8_LDA(dst, b, h) do { _Pragma("unroll") for (int m = 0; m < 4; ++m) _Pragma("unroll") for (int k = 0; k < 2; ++k) dst[m][k] = *(const LAS bf16x8*)(lds + PG8_SA(b, h) + aoff + m * 2048 + k * 1024); } while (0)
; #define PG8_WAIT_V(n) asm volatile("s_waitcnt vmcnt(" #n ")" ::: "memory")
; template <class Epi>
; __device__ __forceinline__ void gemm_phase(const int TID, const int BID, LAS unsigned char* lds, const Gemm g, const StaticOrder& S, const Epi& E) {
;     ...
;             PG8_BAR; PG8_WAIT_L(0); PG8_MMA(0, 1, At, B1); PG8_BAR;
;             PG8_LDA(At, 1, 1); PG8_STAGE(PG8_SA(1, 0), a3, voffA);
;             PG8_BAR; PG8_WAIT_L(0); PG8_MMA(1, 0, At, B0); PG8_BAR; PG8_SCHED;
;             PG8_STAGE(PG8_SB(1, 1), b3 + hstepB, voffB);
;             PG8_WAIT_V(6); PG8_BAR; PG8_MMA(1, 1, At, B1); PG8_BAR;
;     __device__ __forceinline__ void operator()(const f32x4 (&acc)[2][2][4][2], const Unit& u, int wr, int wc, int fr, int fq) const {
;         const int row0 = u.pm * BM + wr * 64 + fr, col0 = u.pn * BM + wc * 32 + 8 * fq;
;         f32x4 bv[2][2];
; #pragma unroll
;         for (int bj = 0; bj < 2; ++bj)
; #pragma unroll
;             for (int n = 0; n < 2; ++n) bv[bj][n] = *(const f32x4*)(bias + col0 + bj * HALF + 4 * n);
;         const bool isv = u.pn >= 8;
; #pragma unroll
;         for (int ai = 0; ai < 2; ++ai)
; #pragma unroll
;             for (int m = 0; m < 4; ++m) {
;                 const int row = row0 + ai * HALF + m * 16; const float r = rinv_st(stats[row], 1.0f / 2048.0f);
;                 bf16_t* rowp = uv + (size_t)row * 4096 + col0; float ss = 0.f;
; #pragma unroll
;                 for (int bj = 0; bj < 2; ++bj) {
;                     const f32x4 v0 = acc[ai][bj][m][0] * r + bv[bj][0], v1 = acc[ai][bj][m][1] * r + bv[bj][1];
;                     const f32x2 a = gelu_pk((f32x2){v0[0], v0[1]}), b = gelu_pk((f32x2){v0[2], v0[3]}), c = gelu_pk((f32x2){v1[0], v1[1]}), d = gelu_pk((f32x2){v1[2], v1[3]});
	s_waitcnt lgkmcnt(0)
	s_setprio 1
	v_mfma_f32_16x16x32_bf16 v[76:79], v[16:19], v[154:157], v[76:79]
	v_mfma_f32_16x16x32_bf16 v[60:63], v[16:19], v[180:183], v[60:63]
	v_mfma_f32_16x16x32_bf16 v[44:47], v[16:19], v[208:211], v[44:47]
	v_mfma_f32_16x16x32_bf16 v[8:11], v[16:19], v[216:219], v[8:11]
	v_mfma_f32_16x16x32_bf16 v[76:79], v[20:23], v[176:179], v[76:79]
	v_mfma_f32_16x16x32_bf16 v[72:75], v[64:67], v[154:157], v[72:75]
	v_mfma_f32_16x16x32_bf16 v[60:63], v[20:23], v[196:199], v[60:63]
	v_mfma_f32_16x16x32_bf16 v[56:59], v[64:67], v[180:183], v[56:59]
	v_mfma_f32_16x16x32_bf16 v[44:47], v[20:23], v[212:215], v[44:47]
	v_mfma_f32_16x16x32_bf16 v[40:43], v[64:67], v[208:211], v[40:43]
	v_mfma_f32_16x16x32_bf16 v[20:23], v[20:23], v[220:223], v[8:11]
	v_mfma_f32_16x16x32_bf16 v[8:11], v[64:67], v[216:219], v[12:15]
	v_mfma_f32_16x16x32_bf16 v[72:75], v[68:71], v[176:179], v[72:75]
	v_mfma_f32_16x16x32_bf16 v[56:59], v[68:71], v[196:199], v[56:59]
	v_mfma_f32_16x16x32_bf16 v[40:43], v[68:71], v[212:215], v[40:43]
	v_mfma_f32_16x16x32_bf16 v[16:19], v[68:71], v[220:223], v[8:11]
	s_setprio 0
	s_barrier
	s_add_u32 s36, s36, 0x80080
	s_addc_u32 s37, s37, 0
	s_mov_b32 m0, s59
	v_lshl_add_u64 v[8:9], s[36:37], 0, v[160:161]
	global_load_lds_dwordx4 v[8:9], off
	s_mov_b32 m0, s60
	v_lshl_add_u64 v[8:9], s[36:37], 0, v[148:149]
	global_load_lds_dwordx4 v[8:9], off
	s_waitcnt vmcnt(6)
	s_barrier
	s_setprio 1
	v_mfma_f32_16x16x32_bf16 v[8:11], v[224:227], v[154:157], v[32:35]
	v_mfma_f32_16x16x32_bf16 v[68:71], v[228:231], v[176:179], v[8:11]
	v_mfma_f32_16x16x32_bf16 v[8:11], v[232:235], v[154:157], v[36:39]
	v_mfma_f32_16x16x32_bf16 v[64:67], v[236:239], v[176:179], v[8:11]
	v_mfma_f32_16x16x32_bf16 v[8:11], v[224:227], v[180:183], v[52:55]
	v_mfma_f32_16x16x32_bf16 v[52:55], v[228:231], v[196:199], v[8:11]
	v_mfma_f32_16x16x32_bf16 v[8:11], v[232:235], v[180:183], v[48:51]
	v_mfma_f32_16x16x32_bf16 v[48:51], v[236:239], v[196:199], v[8:11]
	v_mfma_f32_16x16x32_bf16 v[8:11], v[224:227], v[208:211], v[28:31]
	v_mfma_f32_16x16x32_bf16 v[28:31], v[228:231], v[212:215], v[8:11]
	v_mfma_f32_16x16x32_bf16 v[8:11], v[232:235], v[208:211], v[24:27]
	v_mfma_f32_16x16x32_bf16 v[4:7], v[224:227], v[216:219], v[4:7]
	v_mfma_f32_16x16x32_bf16 v[0:3], v[232:235], v[216:219], v[0:3]
	v_mfma_f32_16x16x32_bf16 v[24:27], v[236:239], v[212:215], v[8:11]
	v_mfma_f32_16x16x32_bf16 v[4:7], v[228:231], v[220:223], v[4:7]
	v_mfma_f32_16x16x32_bf16 v[0:3], v[236:239], v[220:223], v[0:3]
	s_setprio 0
	s_add_i32 s31, s31, 2
	s_add_u32 s34, s34, 0x100
	s_addc_u32 s35, s35, 0
	s_add_u32 s23, s23, 0x100
	s_addc_u32 s29, s29, 0
	s_cmp_gt_u32 s31, 29
	s_barrier
	s_cbranch_scc0 .LBB0_864
	v_readlane_b32 s0, v254, 32
	v_readlane_b32 s1, v254, 33
	s_load_dwordx2 s[0:1], s[0:1], 0x50
	v_lshl_or_b32 v154, s30, 8, v173
	v_lshl_add_u32 v156, s28, 8, v169
	v_ashrrev_i32_e32 v155, 31, v154
	v_ashrrev_i32_e32 v157, 31, v156
	s_waitcnt lgkmcnt(0)
	v_lshl_add_u64 v[12:13], v[154:155], 2, s[0:1]
	v_lshl_add_u64 v[158:159], v[156:157], 3, s[16:17]
	global_load_dwordx4 v[32:35], v[12:13], off offset:16
	global_load_dwordx4 v[36:39], v[12:13], off
	global_load_dwordx4 v[8:11], v[12:13], off offset:528
	s_nop 0
	global_load_dwordx4 v[12:15], v[12:13], off offset:512
	s_cmp_gt_i32 s30, 7
	global_load_dwordx2 v[166:167], v[158:159], off
	global_load_dwordx2 v[208:209], v[158:159], off offset:128
	global_load_dwordx2 v[210:211], v[158:159], off offset:256
	global_load_dwordx2 v[212:213], v[158:159], off offset:384
	global_load_dwordx2 v[214:215], v[158:159], off offset:1024
	global_load_dwordx2 v[216:217], v[158:159], off offset:1152
	global_load_dwordx2 v[218:219], v[158:159], off offset:1280
	global_load_dwordx2 v[220:221], v[158:159], off offset:1408
	s_mov_b32 s30, 0xbf38aa3b
	s_cselect_b64 s[0:1], -1, 0
	s_and_b64 s[28:29], s[8:9], s[0:1]
	s_mov_b32 s0, 0xbe11a98e
	s_mov_b32 s4, 0x3e027906
	s_waitcnt vmcnt(0)
	v_cvt_f64_u32_e32 v[170:171], v167
	v_ldexp_f64 v[170:171], v[170:171], 32
	v_cvt_f64_u32_e32 v[166:167], v166
	v_add_f64 v[166:167], v[170:171], v[166:167]
	v_ldexp_f64 v[166:167], v[166:167], s93
	v_cvt_f32_f64_e32 v166, v[166:167]
	v_fmamk_f32 v166, v166, 0x3a000000, v189
	v_cmp_gt_f32_e32 vcc, s78, v166
	v_mul_f32_e32 v167, 0x4b800000, v166
	s_nop 0
	v_cndmask_b32_e32 v166, v166, v167, vcc
	v_rsq_f32_e32 v166, v166
	s_nop 0
	v_mul_f32_e32 v167, 0x45800000, v166
	v_cndmask_b32_e32 v168, v166, v167, vcc
	v_pk_fma_f32 v[170:171], v[140:141], v[168:169], v[36:37] op_sel_hi:[1,0,1]
	v_pk_fma_f32 v[140:141], v[136:137], v[168:169], v[32:33] op_sel_hi:[1,0,1]
	v_and_b32_e32 v137, 0x7fffffff, v171
	v_and_b32_e32 v136, 0x7fffffff, v170
	v_pk_fma_f32 v[136:137], v[136:137], s[64:65], 1.0 op_sel_hi:[1,0,0]
	v_pk_mul_f32 v[180:181], v[170:171], v[170:171]
	v_rcp_f32_e32 v176, v136
	v_rcp_f32_e32 v177, v137
	v_mov_b64_e32 v[136:137], s[80:81]
	v_pk_mul_f32 v[180:181], v[180:181], s[30:31] op_sel_hi:[1,0]
	v_cmp_gt_f32_e32 vcc, 0, v170
	v_pk_fma_f32 v[178:179], v[176:177], s[74:75], v[136:137] op_sel_hi:[1,0,0]
	v_exp_f32_e32 v180, v180
	v_pk_fma_f32 v[178:179], v[176:177], v[178:179], s[86:87] op_sel_hi:[1,1,0]
	v_exp_f32_e32 v181, v181
	v_pk_fma_f32 v[178:179], v[176:177], v[178:179], s[0:1] op_sel_hi:[1,1,0]
	v_pk_fma_f32 v[142:143], v[142:143], v[168:169], v[38:39] op_sel_hi:[1,0,1]
	v_pk_fma_f32 v[178:179], v[176:177], v[178:179], s[4:5] op_sel_hi:[1,1,0]
	v_pk_fma_f32 v[138:139], v[138:139], v[168:169], v[34:35] op_sel_hi:[1,0,1]
	v_pk_mul_f32 v[176:177], v[176:177], v[178:179]
	v_pk_mul_f32 v[178:179], v[142:143], v[142:143]
	v_pk_mul_f32 v[176:177], v[180:181], v[176:177]
; __device__ __forceinline__ unsigned cvt_pk_bf16(float lo, float hi) { unsigned r; asm volatile("v_cvt_pk_bf16_f32 %0, %1, %2" : "=v"(r) : "v"(lo), "v"(hi)); return r; }
; __device__ __forceinline__ float rinv_st(stat_t s, float invn) { return rsqrtf((float)((double)s * (1.0 / 4294967296.0)) * invn + 1e-6f); }
;     __device__ __forceinline__ void operator()(const f32x4 (&acc)[2][2][4][2], const Unit& u, int wr, int wc, int fr, int fq) const {
;     ...
;                 const int row = row0 + ai * HALF + m * 16; const float r = rinv_st(stats[row], 1.0f / 2048.0f);
;                 bf16_t* rowp = uv + (size_t)row * 4096 + col0; float ss = 0.f;
; #pragma unroll
;                 for (int bj = 0; bj < 2; ++bj) {
;                     const f32x4 v0 = acc[ai][bj][m][0] * r + bv[bj][0], v1 = acc[ai][bj][m][1] * r + bv[bj][1];
;                     const f32x2 a = gelu_pk((f32x2){v0[0], v0[1]}), b = gelu_pk((f32x2){v0[2], v0[3]}), c = gelu_pk((f32x2){v1[0], v1[1]}), d = gelu_pk((f32x2){v1[2], v1[3]});
;                     ss += a.x * a.x + a.y * a.y + b.x * b.x + b.y * b.y + c.x * c.x + c.y * c.y + d.x * d.x + d.y * d.y;
;                     u32x4 w; w.x = cvt_pk_bf16(a.x, a.y); w.y = cvt_pk_bf16(b.x, b.y); w.z = cvt_pk_bf16(c.x, c.y); w.w = cvt_pk_bf16(d.x, d.y);
;                     *(u32x4*)(rowp + bj * HALF) = w;
	v_pk_mul_f32 v[178:179], v[178:179], s[30:31] op_sel_hi:[1,0]
	v_pk_mul_f32 v[180:181], v[170:171], v[176:177]
	v_pk_fma_f32 v[176:177], v[170:171], v[176:177], v[170:171] neg_lo:[1,0,0] neg_hi:[1,0,0]
	v_exp_f32_e32 v178, v178
	v_cndmask_b32_e32 v170, v176, v180, vcc
	v_cmp_gt_f32_e32 vcc, 0, v171
	v_and_b32_e32 v176, 0x7fffffff, v142
	v_exp_f32_e32 v179, v179
	v_cndmask_b32_e32 v171, v177, v181, vcc
	v_and_b32_e32 v177, 0x7fffffff, v143
	v_pk_fma_f32 v[176:177], v[176:177], s[64:65], 1.0 op_sel_hi:[1,0,0]
	v_cmp_gt_f32_e32 vcc, 0, v142
	v_rcp_f32_e32 v176, v176
	v_rcp_f32_e32 v177, v177
	v_lshlrev_b64 v[166:167], 13, v[156:157]
	v_lshl_add_u64 v[166:167], s[14:15], 0, v[166:167]
	v_lshl_add_u64 v[166:167], v[154:155], 1, v[166:167]
	v_pk_fma_f32 v[180:181], v[176:177], s[74:75], v[136:137] op_sel_hi:[1,0,0]
	v_pk_fma_f32 v[132:133], v[132:133], v[168:169], v[12:13] op_sel_hi:[1,0,1]
	v_pk_fma_f32 v[180:181], v[176:177], v[180:181], s[86:87] op_sel_hi:[1,1,0]
	v_pk_fma_f32 v[134:135], v[134:135], v[168:169], v[14:15] op_sel_hi:[1,0,1]
	v_pk_fma_f32 v[180:181], v[176:177], v[180:181], s[0:1] op_sel_hi:[1,1,0]
	v_pk_fma_f32 v[128:129], v[128:129], v[168:169], v[8:9] op_sel_hi:[1,0,1]
	v_pk_fma_f32 v[180:181], v[176:177], v[180:181], s[4:5] op_sel_hi:[1,1,0]
	v_pk_fma_f32 v[130:131], v[130:131], v[168:169], v[10:11] op_sel_hi:[1,0,1]
	v_pk_mul_f32 v[176:177], v[176:177], v[180:181]
	s_nop 0
	v_pk_mul_f32 v[176:177], v[178:179], v[176:177]
	s_nop 0
	v_pk_mul_f32 v[178:179], v[142:143], v[176:177]
	v_pk_fma_f32 v[176:177], v[142:143], v[176:177], v[142:143] neg_lo:[1,0,0] neg_hi:[1,0,0]
	v_and_b32_e32 v142, 0x7fffffff, v140
	v_cndmask_b32_e32 v175, v176, v178, vcc
	v_cmp_gt_f32_e32 vcc, 0, v143
	v_and_b32_e32 v143, 0x7fffffff, v141
	v_pk_fma_f32 v[142:143], v[142:143], s[64:65], 1.0 op_sel_hi:[1,0,0]
	v_cndmask_b32_e32 v180, v177, v179, vcc
	v_rcp_f32_e32 v142, v142
	v_rcp_f32_e32 v143, v143
	v_pk_mul_f32 v[178:179], v[140:141], v[140:141]
	v_cmp_gt_f32_e32 vcc, 0, v140
	v_pk_mul_f32 v[178:179], v[178:179], s[30:31] op_sel_hi:[1,0]
	v_pk_fma_f32 v[176:177], v[142:143], s[74:75], v[136:137] op_sel_hi:[1,0,0]
	v_exp_f32_e32 v178, v178
	v_pk_fma_f32 v[176:177], v[142:143], v[176:177], s[86:87] op_sel_hi:[1,1,0]
	v_exp_f32_e32 v179, v179
	v_pk_fma_f32 v[176:177], v[142:143], v[176:177], s[0:1] op_sel_hi:[1,1,0]
	s_nop 0
	v_pk_fma_f32 v[176:177], v[142:143], v[176:177], s[4:5] op_sel_hi:[1,1,0]
	s_nop 0
	v_pk_mul_f32 v[142:143], v[142:143], v[176:177]
	v_pk_mul_f32 v[176:177], v[138:139], v[138:139]
	v_pk_mul_f32 v[142:143], v[178:179], v[142:143]
	s_nop 0
	v_pk_mul_f32 v[178:179], v[140:141], v[142:143]
	v_pk_fma_f32 v[142:143], v[140:141], v[142:143], v[140:141] neg_lo:[1,0,0] neg_hi:[1,0,0]
	v_and_b32_e32 v140, 0x7fffffff, v138
	v_cndmask_b32_e32 v178, v142, v178, vcc
	v_cmp_gt_f32_e32 vcc, 0, v141
	v_and_b32_e32 v141, 0x7fffffff, v139
	v_pk_fma_f32 v[140:141], v[140:141], s[64:65], 1.0 op_sel_hi:[1,0,0]
	v_cndmask_b32_e32 v179, v143, v179, vcc
	v_rcp_f32_e32 v140, v140
	v_rcp_f32_e32 v141, v141
	v_cmp_gt_f32_e32 vcc, 0, v138
	v_pk_fma_f32 v[142:143], v[140:141], s[74:75], v[136:137] op_sel_hi:[1,0,0]
	s_nop 0
	v_pk_fma_f32 v[142:143], v[140:141], v[142:143], s[86:87] op_sel_hi:[1,1,0]
	s_nop 0
	v_pk_fma_f32 v[142:143], v[140:141], v[142:143], s[0:1] op_sel_hi:[1,1,0]
	s_nop 0
	v_pk_fma_f32 v[142:143], v[140:141], v[142:143], s[4:5] op_sel_hi:[1,1,0]
	s_nop 0
	v_pk_mul_f32 v[140:141], v[140:141], v[142:143]
	v_pk_mul_f32 v[142:143], v[176:177], s[30:31] op_sel_hi:[1,0]
	v_mul_f32_e32 v176, v171, v171
	v_exp_f32_e32 v142, v142
	v_exp_f32_e32 v143, v143
	v_fmac_f32_e32 v176, v170, v170
	v_fmac_f32_e32 v176, v175, v175
	v_fmac_f32_e32 v176, v180, v180
	v_pk_mul_f32 v[140:141], v[142:143], v[140:141]
	v_fmac_f32_e32 v176, v178, v178
	v_pk_mul_f32 v[142:143], v[138:139], v[140:141]
	v_pk_fma_f32 v[140:141], v[138:139], v[140:141], v[138:139] neg_lo:[1,0,0] neg_hi:[1,0,0]
	v_fmac_f32_e32 v176, v179, v179
	v_cndmask_b32_e32 v142, v140, v142, vcc
	v_cmp_gt_f32_e32 vcc, 0, v139
	v_fmac_f32_e32 v176, v142, v142
	v_cvt_pk_bf16_f32 v138, v170, v171
	v_cvt_pk_bf16_f32 v139, v175, v180
	v_cvt_pk_bf16_f32 v140, v178, v179
	s_nop 0
	v_cndmask_b32_e32 v141, v141, v143, vcc
	v_fmac_f32_e32 v176, v141, v141
	v_cvt_pk_bf16_f32 v141, v142, v141
	global_store_dwordx4 v[166:167], v[138:141], off
	v_pk_mul_f32 v[142:143], v[132:133], v[132:133]
	v_cmp_gt_f32_e32 vcc, 0, v132
	v_and_b32_e32 v139, 0x7fffffff, v133
	v_and_b32_e32 v138, 0x7fffffff, v132
	v_pk_fma_f32 v[138:139], v[138:139], s[64:65], 1.0 op_sel_hi:[1,0,0]
	v_pk_mul_f32 v[142:143], v[142:143], s[30:31] op_sel_hi:[1,0]
	v_rcp_f32_e32 v138, v138
	v_rcp_f32_e32 v139, v139
	v_exp_f32_e32 v142, v142
	v_exp_f32_e32 v143, v143
	v_pk_fma_f32 v[140:141], v[138:139], s[74:75], v[136:137] op_sel_hi:[1,0,0]
	s_nop 0
	v_pk_fma_f32 v[140:141], v[138:139], v[140:141], s[86:87] op_sel_hi:[1,1,0]
	s_nop 0
	v_pk_fma_f32 v[140:141], v[138:139], v[140:141], s[0:1] op_sel_hi:[1,1,0]
	s_nop 0
	v_pk_fma_f32 v[140:141], v[138:139], v[140:141], s[4:5] op_sel_hi:[1,1,0]
	s_nop 0
	v_pk_mul_f32 v[138:139], v[138:139], v[140:141]
; __device__ __forceinline__ unsigned cvt_pk_bf16(float lo, float hi) { unsigned r; asm volatile("v_cvt_pk_bf16_f32 %0, %1, %2" : "=v"(r) : "v"(lo), "v"(hi)); return r; }
; __device__ __forceinline__ void stat_add(stat_t* p, float ss) { __hip_atomic_fetch_add(p, (stat_t)((double)ss * 4294967296.0), __ATOMIC_RELAXED, __HIP_MEMORY_SCOPE_AGENT); }
;     __device__ __forceinline__ void operator()(const f32x4 (&acc)[2][2][4][2], const Unit& u, int wr, int wc, int fr, int fq) const {
;     ...
;                     const f32x4 v0 = acc[ai][bj][m][0] * r + bv[bj][0], v1 = acc[ai][bj][m][1] * r + bv[bj][1];
;                     const f32x2 a = gelu_pk((f32x2){v0[0], v0[1]}), b = gelu_pk((f32x2){v0[2], v0[3]}), c = gelu_pk((f32x2){v1[0], v1[1]}), d = gelu_pk((f32x2){v1[2], v1[3]});
;                     ss += a.x * a.x + a.y * a.y + b.x * b.x + b.y * b.y + c.x * c.x + c.y * c.y + d.x * d.x + d.y * d.y;
;                     u32x4 w; w.x = cvt_pk_bf16(a.x, a.y); w.y = cvt_pk_bf16(b.x, b.y); w.z = cvt_pk_bf16(c.x, c.y); w.w = cvt_pk_bf16(d.x, d.y);
;                     *(u32x4*)(rowp + bj * HALF) = w;
;                 }
;                 ss += __shfl_xor(ss, 16); ss += __shfl_xor(ss, 32);
;                 if (isv && fq == 0) stat_add(stats_v + row, ss);
	v_pk_mul_f32 v[140:141], v[134:135], v[134:135]
	v_pk_mul_f32 v[138:139], v[142:143], v[138:139]
	s_nop 0
	v_pk_mul_f32 v[142:143], v[132:133], v[138:139]
	v_pk_fma_f32 v[138:139], v[132:133], v[138:139], v[132:133] neg_lo:[1,0,0] neg_hi:[1,0,0]
	v_and_b32_e32 v132, 0x7fffffff, v134
	v_cndmask_b32_e32 v142, v138, v142, vcc
	v_cmp_gt_f32_e32 vcc, 0, v133
	v_and_b32_e32 v133, 0x7fffffff, v135
	v_pk_fma_f32 v[132:133], v[132:133], s[64:65], 1.0 op_sel_hi:[1,0,0]
	v_cndmask_b32_e32 v143, v139, v143, vcc
	v_rcp_f32_e32 v132, v132
	v_rcp_f32_e32 v133, v133
	v_cmp_gt_f32_e32 vcc, 0, v134
	v_pk_fma_f32 v[138:139], v[132:133], s[74:75], v[136:137] op_sel_hi:[1,0,0]
	s_nop 0
	v_pk_fma_f32 v[138:139], v[132:133], v[138:139], s[86:87] op_sel_hi:[1,1,0]
	s_nop 0
	v_pk_fma_f32 v[138:139], v[132:133], v[138:139], s[0:1] op_sel_hi:[1,1,0]
	s_nop 0
	v_pk_fma_f32 v[138:139], v[132:133], v[138:139], s[4:5] op_sel_hi:[1,1,0]
	s_nop 0
	v_pk_mul_f32 v[132:133], v[132:133], v[138:139]
	v_pk_mul_f32 v[138:139], v[140:141], s[30:31] op_sel_hi:[1,0]
	s_nop 0
	v_exp_f32_e32 v138, v138
	v_exp_f32_e32 v139, v139
	s_nop 0
	v_pk_mul_f32 v[132:133], v[138:139], v[132:133]
	s_nop 0
	v_pk_mul_f32 v[138:139], v[134:135], v[132:133]
	v_pk_fma_f32 v[132:133], v[134:135], v[132:133], v[134:135] neg_lo:[1,0,0] neg_hi:[1,0,0]
	s_nop 0
	v_cndmask_b32_e32 v140, v132, v138, vcc
	v_cmp_gt_f32_e32 vcc, 0, v135
	v_and_b32_e32 v132, 0x7fffffff, v128
	s_nop 0
	v_cndmask_b32_e32 v141, v133, v139, vcc
	v_and_b32_e32 v133, 0x7fffffff, v129
	v_pk_fma_f32 v[132:133], v[132:133], s[64:65], 1.0 op_sel_hi:[1,0,0]
	v_pk_mul_f32 v[138:139], v[128:129], v[128:129]
	v_rcp_f32_e32 v132, v132
	v_rcp_f32_e32 v133, v133
	v_pk_mul_f32 v[138:139], v[138:139], s[30:31] op_sel_hi:[1,0]
	v_cmp_gt_f32_e32 vcc, 0, v128
	v_exp_f32_e32 v138, v138
	v_pk_fma_f32 v[134:135], v[132:133], s[74:75], v[136:137] op_sel_hi:[1,0,0]
	v_exp_f32_e32 v139, v139
	v_pk_fma_f32 v[134:135], v[132:133], v[134:135], s[86:87] op_sel_hi:[1,1,0]
	s_nop 0
	v_pk_fma_f32 v[134:135], v[132:133], v[134:135], s[0:1] op_sel_hi:[1,1,0]
	s_nop 0
	v_pk_fma_f32 v[134:135], v[132:133], v[134:135], s[4:5] op_sel_hi:[1,1,0]
	s_nop 0
	v_pk_mul_f32 v[132:133], v[132:133], v[134:135]
	v_pk_mul_f32 v[134:135], v[130:131], v[130:131]
	v_pk_mul_f32 v[132:133], v[138:139], v[132:133]
	s_nop 0
	v_pk_mul_f32 v[138:139], v[128:129], v[132:133]
	v_pk_fma_f32 v[132:133], v[128:129], v[132:133], v[128:129] neg_lo:[1,0,0] neg_hi:[1,0,0]
	v_and_b32_e32 v128, 0x7fffffff, v130
	v_cndmask_b32_e32 v138, v132, v138, vcc
	v_cmp_gt_f32_e32 vcc, 0, v129
	v_and_b32_e32 v129, 0x7fffffff, v131
	v_pk_fma_f32 v[128:129], v[128:129], s[64:65], 1.0 op_sel_hi:[1,0,0]
	v_cndmask_b32_e32 v139, v133, v139, vcc
	v_rcp_f32_e32 v128, v128
	v_rcp_f32_e32 v129, v129
	v_cmp_gt_f32_e32 vcc, 0, v130
	v_pk_fma_f32 v[132:133], v[128:129], s[74:75], v[136:137] op_sel_hi:[1,0,0]
	s_nop 0
	v_pk_fma_f32 v[132:133], v[128:129], v[132:133], s[86:87] op_sel_hi:[1,1,0]
	s_nop 0
	v_pk_fma_f32 v[132:133], v[128:129], v[132:133], s[0:1] op_sel_hi:[1,1,0]
	s_nop 0
	v_pk_fma_f32 v[132:133], v[128:129], v[132:133], s[4:5] op_sel_hi:[1,1,0]
	s_nop 0
	v_pk_mul_f32 v[128:129], v[128:129], v[132:133]
	v_pk_mul_f32 v[132:133], v[134:135], s[30:31] op_sel_hi:[1,0]
	s_nop 0
	v_exp_f32_e32 v132, v132
	v_exp_f32_e32 v133, v133
	s_nop 0
	v_pk_mul_f32 v[128:129], v[132:133], v[128:129]
	s_nop 0
	v_pk_mul_f32 v[132:133], v[130:131], v[128:129]
	v_pk_fma_f32 v[128:129], v[130:131], v[128:129], v[130:131] neg_lo:[1,0,0] neg_hi:[1,0,0]
	s_nop 0
	v_cndmask_b32_e32 v132, v128, v132, vcc
	v_mul_f32_e32 v128, v143, v143
	v_fmac_f32_e32 v128, v142, v142
	v_fmac_f32_e32 v128, v140, v140
	v_fmac_f32_e32 v128, v141, v141
	v_fmac_f32_e32 v128, v138, v138
	v_cmp_gt_f32_e32 vcc, 0, v131
	v_fmac_f32_e32 v128, v139, v139
	v_fmac_f32_e32 v128, v132, v132
	v_cndmask_b32_e32 v131, v129, v133, vcc
	v_fmac_f32_e32 v128, v131, v131
	v_add_f32_e32 v134, v176, v128
	v_cvt_pk_bf16_f32 v128, v142, v143
	v_cvt_pk_bf16_f32 v129, v140, v141
	v_cvt_pk_bf16_f32 v130, v138, v139
	v_cvt_pk_bf16_f32 v131, v132, v131
	global_store_dwordx4 v[166:167], v[128:131], off offset:256
	s_nop 1
	v_and_b32_e32 v129, 64, v190
	v_xor_b32_e32 v128, 16, v190
	v_add_u32_e32 v129, 64, v129
	v_cmp_lt_i32_e32 vcc, v128, v129
	v_xor_b32_e32 v130, 32, v190
	s_nop 0
	v_cndmask_b32_e32 v128, v190, v128, vcc
	v_lshlrev_b32_e32 v133, 2, v128
	ds_bpermute_b32 v128, v133, v134
	v_cmp_lt_i32_e32 vcc, v130, v129
	s_waitcnt lgkmcnt(0)
	v_add_f32_e32 v128, v134, v128
	v_cndmask_b32_e32 v129, v190, v130, vcc
	v_lshlrev_b32_e32 v134, 2, v129
	ds_bpermute_b32 v129, v134, v128
	s_and_saveexec_b64 s[30:31], s[28:29]
	s_cbranch_execz .LBB0_867
	s_waitcnt lgkmcnt(0)
	v_add_f32_e32 v128, v128, v129
	v_cvt_f64_f32_e32 v[128:129], v128
	v_ldexp_f64 v[128:129], v[128:129], 32
	v_trunc_f64_e32 v[128:129], v[128:129]
	v_ldexp_f64 v[136:137], v[128:129], s93
	v_floor_f64_e32 v[136:137], v[136:137]
	v_fmac_f64_e32 v[128:129], 0xc1f00000, v[136:137]
	v_lshl_add_u64 v[130:131], v[156:157], 3, s[18:19]
	v_cvt_u32_f64_e32 v128, v[128:129]
	v_cvt_u32_f64_e32 v129, v[136:137]
	global_atomic_add_x2 v[130:131], v[128:129], off

; #define PG8_STAGE(bufoff, gbase, voff) do { _Pragma("unroll") for (int _i = 0; _i < 2; ++_i) \
;         __builtin_amdgcn_global_load_lds((const unsigned*)((const char*)(gbase) + (voff)[_i]), (LAS unsigned*)(lds + (bufoff) + ldsw + _i * 8192), 16, 0, 0); } while (0)
; #define PG8_LDA(dst, b, h) do { _Pragma("unroll") for (int m = 0; m < 4; ++m) _Pragma("unroll") for (int k = 0; k < 2; ++k) dst[m][k] = *(const LAS bf16x8*)(lds + PG8_SA(b, h) + aoff + m * 2048 + k * 1024); } while (0)
; #define PG8_LDB(dst, b, h) do { _Pragma("unroll") for (int n = 0; n < 2; ++n) _Pragma("unroll") for (int k = 0; k < 2; ++k) dst[n][k] = *(const LAS bf16x8*)(lds + PG8_SB(b, h) + boff + n * 2048 + k * 1024); } while (0)
; #define PG8_MMA(ai, bj, At, Bt) do { __builtin_amdgcn_s_setprio(1); _Pragma("unroll") for (int m = 0; m < 4; ++m) _Pragma("unroll") for (int n = 0; n < 2; ++n) _Pragma("unroll") for (int k = 0; k < 2; ++k) \
;         acc[ai][bj][m][n] = __builtin_amdgcn_mfma_f32_16x16x32_bf16(Bt[n][k], At[m][k], acc[ai][bj][m][n], 0, 0, 0); __builtin_amdgcn_s_setprio(0); } while (0)
; #define PG8_WAIT_L(n) asm volatile("s_waitcnt lgkmcnt(" #n ")" ::: "memory")
; #define PG8_BAR __builtin_amdgcn_s_barrier()
; #define PG8_SCHED __builtin_amdgcn_sched_barrier(0)
; template <class Epi>
; __device__ __forceinline__ void gemm_phase(const int TID, const int BID, LAS unsigned char* lds, const Gemm g, const StaticOrder& S, const Epi& E) {
;     ...
;         for (int t = 0; t < nt; t += 2) {
;             const bool last = (t == nt - 2);
;             const char* a1 = cA + (size_t)(t + 1) * kstep;
;             const char* a2 = last ? nA : cA + (size_t)(t + 2) * kstep; const char* b2 = last ? nB : cB + (size_t)(t + 2) * kstep;
;             const char* a3 = a2 + kstep; const char* b3 = b2 + kstep;
;             PG8_LDB(B0, 0, 0); PG8_SCHED; PG8_LDA(At, 0, 0); PG8_STAGE(PG8_SA(1, 1), a1 + hstepA, voffA);
;             PG8_WAIT_L(8); PG8_BAR; PG8_WAIT_L(0); PG8_MMA(0, 0, At, B0); PG8_BAR; PG8_SCHED;
;             PG8_LDB(B1, 0, 1); PG8_STAGE(PG8_SB(0, 0), b2, voffB);
;             PG8_BAR; PG8_WAIT_L(0); PG8_MMA(0, 1, At, B1); PG8_BAR;
;             PG8_LDA(At, 0, 1); PG8_STAGE(PG8_SA(0, 0), a2, voffA);
;             PG8_BAR; PG8_WAIT_L(0); PG8_MMA(1, 0, At, B0); PG8_BAR; PG8_SCHED;
.LBB0_925:
	v_add_u32_e32 v154, s31, v147
	ds_read_b128 v[138:141], v154
	ds_read_b128 v[142:145], v154 offset:1024
	ds_read_b128 v[150:153], v154 offset:2048
	ds_read_b128 v[154:157], v154 offset:3072
	s_add_u32 s36, s34, 0xfff80080
	s_addc_u32 s37, s35, -1
	s_cmp_eq_u32 s64, 28
	s_cselect_b32 s39, s1, s37
	s_cselect_b32 s38, s4, s36
	s_cselect_b32 s37, s17, s23
	s_cselect_b32 s36, s19, s22
	v_lshl_add_u64 v[158:159], s[34:35], 0, v[134:135]
	s_add_i32 m0, s48, 0xc000
	ds_read_b128 v[166:169], v149
	ds_read_b128 v[170:173], v149 offset:1024
	ds_read_b128 v[174:177], v149 offset:2048
	ds_read_b128 v[178:181], v149 offset:3072
	ds_read_b128 v[182:185], v149 offset:4096
	ds_read_b128 v[196:199], v149 offset:5120
	ds_read_b128 v[208:211], v149 offset:6144
	ds_read_b128 v[212:215], v149 offset:7168
	global_load_lds_dwordx4 v[158:159], off
	s_add_i32 m0, s48, 0xe000
	v_lshl_add_u64 v[158:159], s[34:35], 0, v[136:137]
	global_load_lds_dwordx4 v[158:159], off
	s_waitcnt lgkmcnt(8)
	s_barrier
	s_waitcnt lgkmcnt(0)
	s_setprio 1
	v_mfma_f32_16x16x32_bf16 v[124:127], v[138:141], v[166:169], v[124:127]
	v_mfma_f32_16x16x32_bf16 v[120:123], v[150:153], v[166:169], v[120:123]
	v_mfma_f32_16x16x32_bf16 v[108:111], v[138:141], v[174:177], v[108:111]
	v_mfma_f32_16x16x32_bf16 v[104:107], v[150:153], v[174:177], v[104:107]
	v_mfma_f32_16x16x32_bf16 v[92:95], v[138:141], v[182:185], v[92:95]
	v_mfma_f32_16x16x32_bf16 v[88:91], v[150:153], v[182:185], v[88:91]
	v_mfma_f32_16x16x32_bf16 v[76:79], v[138:141], v[208:211], v[76:79]
	v_mfma_f32_16x16x32_bf16 v[72:75], v[150:153], v[208:211], v[72:75]
	v_mfma_f32_16x16x32_bf16 v[124:127], v[142:145], v[170:173], v[124:127]
	v_mfma_f32_16x16x32_bf16 v[120:123], v[154:157], v[170:173], v[120:123]
	v_mfma_f32_16x16x32_bf16 v[108:111], v[142:145], v[178:181], v[108:111]
	v_mfma_f32_16x16x32_bf16 v[104:107], v[154:157], v[178:181], v[104:107]
	v_mfma_f32_16x16x32_bf16 v[92:95], v[142:145], v[196:199], v[92:95]
	v_mfma_f32_16x16x32_bf16 v[88:91], v[154:157], v[196:199], v[88:91]
	v_mfma_f32_16x16x32_bf16 v[76:79], v[142:145], v[212:215], v[76:79]
	v_mfma_f32_16x16x32_bf16 v[72:75], v[154:157], v[212:215], v[72:75]
	s_setprio 0
	s_barrier
	v_add_u32_e32 v158, s50, v147
	s_mov_b32 m0, s46
	ds_read_b128 v[216:219], v158
	ds_read_b128 v[220:223], v158 offset:1024
	ds_read_b128 v[224:227], v158 offset:2048
	ds_read_b128 v[228:231], v158 offset:3072
	v_lshl_add_u64 v[158:159], s[36:37], 0, v[160:161]
	global_load_lds_dwordx4 v[158:159], off
	s_mov_b32 m0, s47
	v_lshl_add_u64 v[200:201], s[36:37], 0, v[132:133]
	global_load_lds_dwordx4 v[200:201], off
	s_barrier
	s_waitcnt lgkmcnt(0)
	s_setprio 1
	v_mfma_f32_16x16x32_bf16 v[116:119], v[216:219], v[166:169], v[116:119]
	v_mfma_f32_16x16x32_bf16 v[112:115], v[224:227], v[166:169], v[112:115]
	v_mfma_f32_16x16x32_bf16 v[100:103], v[216:219], v[174:177], v[100:103]
	v_mfma_f32_16x16x32_bf16 v[96:99], v[224:227], v[174:177], v[96:99]
	v_mfma_f32_16x16x32_bf16 v[84:87], v[216:219], v[182:185], v[84:87]
	v_mfma_f32_16x16x32_bf16 v[80:83], v[224:227], v[182:185], v[80:83]
	v_mfma_f32_16x16x32_bf16 v[68:71], v[216:219], v[208:211], v[68:71]
	v_mfma_f32_16x16x32_bf16 v[64:67], v[224:227], v[208:211], v[64:67]
	v_mfma_f32_16x16x32_bf16 v[116:119], v[220:223], v[170:173], v[116:119]
	v_mfma_f32_16x16x32_bf16 v[112:115], v[228:231], v[170:173], v[112:115]
	v_mfma_f32_16x16x32_bf16 v[100:103], v[220:223], v[178:181], v[100:103]
	v_mfma_f32_16x16x32_bf16 v[96:99], v[228:231], v[178:181], v[96:99]
	v_mfma_f32_16x16x32_bf16 v[84:87], v[220:223], v[196:199], v[84:87]
	v_mfma_f32_16x16x32_bf16 v[80:83], v[228:231], v[196:199], v[80:83]
	v_mfma_f32_16x16x32_bf16 v[68:71], v[220:223], v[212:215], v[68:71]
	v_mfma_f32_16x16x32_bf16 v[64:67], v[228:231], v[212:215], v[64:67]
	s_setprio 0
	s_mov_b32 m0, s48
	v_lshl_add_u64 v[232:233], s[38:39], 0, v[128:129]
	s_barrier
	ds_read_b128 v[166:169], v149 offset:16384
	ds_read_b128 v[170:173], v149 offset:17408
	ds_read_b128 v[174:177], v149 offset:18432
	ds_read_b128 v[178:181], v149 offset:19456
	ds_read_b128 v[182:185], v149 offset:20480
	ds_read_b128 v[196:199], v149 offset:21504
	ds_read_b128 v[208:211], v149 offset:22528
	ds_read_b128 v[212:215], v149 offset:23552
	global_load_lds_dwordx4 v[232:233], off
	s_mov_b32 m0, s49
	v_lshl_add_u64 v[234:235], s[38:39], 0, v[130:131]
	global_load_lds_dwordx4 v[234:235], off
	s_barrier
	s_waitcnt lgkmcnt(0)
	s_setprio 1
	v_mfma_f32_16x16x32_bf16 v[60:63], v[138:141], v[166:169], v[60:63]
	v_mfma_f32_16x16x32_bf16 v[56:59], v[150:153], v[166:169], v[56:59]
	v_mfma_f32_16x16x32_bf16 v[44:47], v[138:141], v[174:177], v[44:47]
	v_mfma_f32_16x16x32_bf16 v[40:43], v[150:153], v[174:177], v[40:43]
	v_mfma_f32_16x16x32_bf16 v[28:31], v[138:141], v[182:185], v[28:31]
	v_mfma_f32_16x16x32_bf16 v[24:27], v[150:153], v[182:185], v[24:27]
	v_mfma_f32_16x16x32_bf16 v[12:15], v[138:141], v[208:211], v[12:15]
	v_mfma_f32_16x16x32_bf16 v[8:11], v[150:153], v[208:211], v[8:11]
	v_mfma_f32_16x16x32_bf16 v[60:63], v[142:145], v[170:173], v[60:63]
	v_mfma_f32_16x16x32_bf16 v[56:59], v[154:157], v[170:173], v[56:59]
	v_mfma_f32_16x16x32_bf16 v[44:47], v[142:145], v[178:181], v[44:47]
	v_mfma_f32_16x16x32_bf16 v[40:43], v[154:157], v[178:181], v[40:43]
	v_mfma_f32_16x16x32_bf16 v[28:31], v[142:145], v[196:199], v[28:31]
	v_mfma_f32_16x16x32_bf16 v[24:27], v[154:157], v[196:199], v[24:27]
	v_mfma_f32_16x16x32_bf16 v[12:15], v[142:145], v[212:215], v[12:15]
	v_mfma_f32_16x16x32_bf16 v[8:11], v[154:157], v[212:215], v[8:11]
	s_setprio 0
	s_barrier
; #define PG8_STAGE(bufoff, gbase, voff) do { _Pragma("unroll") for (int _i = 0; _i < 2; ++_i) \
;         __builtin_amdgcn_global_load_lds((const unsigned*)((const char*)(gbase) + (voff)[_i]), (LAS unsigned*)(lds + (bufoff) + ldsw + _i * 8192), 16, 0, 0); } while (0)
; #define PG8_LDA(dst, b, h) do { _Pragma("unroll") for (int m = 0; m < 4; ++m) _Pragma("unroll") for (int k = 0; k < 2; ++k) dst[m][k] = *(const LAS bf16x8*)(lds + PG8_SA(b, h) + aoff + m * 2048 + k * 1024); } while (0)
; #define PG8_LDB(dst, b, h) do { _Pragma("unroll") for (int n = 0; n < 2; ++n) _Pragma("unroll") for (int k = 0; k < 2; ++k) dst[n][k] = *(const LAS bf16x8*)(lds + PG8_SB(b, h) + boff + n * 2048 + k * 1024); } while (0)
; #define PG8_MMA(ai, bj, At, Bt) do { __builtin_amdgcn_s_setprio(1); _Pragma("unroll") for (int m = 0; m < 4; ++m) _Pragma("unroll") for (int n = 0; n < 2; ++n) _Pragma("unroll") for (int k = 0; k < 2; ++k) \
;         acc[ai][bj][m][n] = __builtin_amdgcn_mfma_f32_16x16x32_bf16(Bt[n][k], At[m][k], acc[ai][bj][m][n], 0, 0, 0); __builtin_amdgcn_s_setprio(0); } while (0)
; #define PG8_WAIT_V(n) asm volatile("s_waitcnt vmcnt(" #n ")" ::: "memory")
; #define PG8_WAIT_L(n) asm volatile("s_waitcnt lgkmcnt(" #n ")" ::: "memory")
; #define PG8_BAR __builtin_amdgcn_s_barrier()
; #define PG8_SCHED __builtin_amdgcn_sched_barrier(0)
; template <class Epi>
; __device__ __forceinline__ void gemm_phase(const int TID, const int BID, LAS unsigned char* lds, const Gemm g, const StaticOrder& S, const Epi& E) {
;     ...
;             PG8_STAGE(PG8_SB(0, 1), b2 + hstepB, voffB);
;             PG8_WAIT_V(6); PG8_BAR; PG8_MMA(1, 1, At, B1); PG8_BAR;
;             PG8_LDB(B0, 1, 0); PG8_SCHED; PG8_LDA(At, 1, 0); PG8_STAGE(PG8_SA(0, 1), a2 + hstepA, voffA);
;             PG8_WAIT_L(8); PG8_BAR; PG8_WAIT_L(0); PG8_MMA(0, 0, At, B0); PG8_BAR; PG8_SCHED;
;             PG8_LDB(B1, 1, 1); PG8_STAGE(PG8_SB(1, 0), b3, voffB);
;             PG8_BAR; PG8_WAIT_L(0); PG8_MMA(0, 1, At, B1); PG8_BAR;
	s_add_u32 s66, s36, 0x80000
	s_addc_u32 s67, s37, 0
	s_mov_b32 m0, s51
	v_lshl_add_u64 v[138:139], s[66:67], 0, v[160:161]
	global_load_lds_dwordx4 v[138:139], off
	s_mov_b32 m0, s52
	v_lshl_add_u64 v[138:139], s[66:67], 0, v[132:133]
	global_load_lds_dwordx4 v[138:139], off
	s_waitcnt vmcnt(6)
	s_barrier
	s_setprio 1
	v_mfma_f32_16x16x32_bf16 v[52:55], v[216:219], v[166:169], v[52:55]
	v_mfma_f32_16x16x32_bf16 v[48:51], v[224:227], v[166:169], v[48:51]
	v_mfma_f32_16x16x32_bf16 v[36:39], v[216:219], v[174:177], v[36:39]
	v_mfma_f32_16x16x32_bf16 v[32:35], v[224:227], v[174:177], v[32:35]
	v_mfma_f32_16x16x32_bf16 v[20:23], v[216:219], v[182:185], v[20:23]
	v_mfma_f32_16x16x32_bf16 v[16:19], v[224:227], v[182:185], v[16:19]
	v_mfma_f32_16x16x32_bf16 v[4:7], v[216:219], v[208:211], v[4:7]
	v_mfma_f32_16x16x32_bf16 v[0:3], v[224:227], v[208:211], v[0:3]
	v_mfma_f32_16x16x32_bf16 v[52:55], v[220:223], v[170:173], v[52:55]
	v_mfma_f32_16x16x32_bf16 v[48:51], v[228:231], v[170:173], v[48:51]
	v_mfma_f32_16x16x32_bf16 v[36:39], v[220:223], v[178:181], v[36:39]
	v_mfma_f32_16x16x32_bf16 v[32:35], v[228:231], v[178:181], v[32:35]
	v_mfma_f32_16x16x32_bf16 v[20:23], v[220:223], v[196:199], v[20:23]
	v_mfma_f32_16x16x32_bf16 v[16:19], v[228:231], v[196:199], v[16:19]
	v_mfma_f32_16x16x32_bf16 v[4:7], v[220:223], v[212:215], v[4:7]
	v_mfma_f32_16x16x32_bf16 v[0:3], v[228:231], v[212:215], v[0:3]
	s_setprio 0
	v_add_u32_e32 v154, s55, v147
	s_barrier
	ds_read_b128 v[138:141], v154
	ds_read_b128 v[142:145], v154 offset:1024
	ds_read_b128 v[150:153], v154 offset:2048
	ds_read_b128 v[154:157], v154 offset:3072
	s_add_u32 s38, s38, 0x80000
	s_addc_u32 s39, s39, 0
	s_mov_b32 m0, s53
	v_lshl_add_u64 v[216:217], s[38:39], 0, v[128:129]
	ds_read_b128 v[166:169], v149 offset:32768
	ds_read_b128 v[170:173], v149 offset:33792
	ds_read_b128 v[174:177], v149 offset:34816
	ds_read_b128 v[178:181], v149 offset:35840
	ds_read_b128 v[182:185], v149 offset:36864
	ds_read_b128 v[196:199], v149 offset:37888
	ds_read_b128 v[208:211], v149 offset:38912
	ds_read_b128 v[212:215], v149 offset:39936
	global_load_lds_dwordx4 v[216:217], off
	s_mov_b32 m0, s54
	v_lshl_add_u64 v[216:217], s[38:39], 0, v[130:131]
	global_load_lds_dwordx4 v[216:217], off
	s_waitcnt lgkmcnt(8)
	s_barrier
	s_waitcnt lgkmcnt(0)
	s_setprio 1
	v_mfma_f32_16x16x32_bf16 v[124:127], v[138:141], v[166:169], v[124:127]
	v_mfma_f32_16x16x32_bf16 v[120:123], v[150:153], v[166:169], v[120:123]
	v_mfma_f32_16x16x32_bf16 v[108:111], v[138:141], v[174:177], v[108:111]
	v_mfma_f32_16x16x32_bf16 v[104:107], v[150:153], v[174:177], v[104:107]
	v_mfma_f32_16x16x32_bf16 v[92:95], v[138:141], v[182:185], v[92:95]
	v_mfma_f32_16x16x32_bf16 v[88:91], v[150:153], v[182:185], v[88:91]
	v_mfma_f32_16x16x32_bf16 v[76:79], v[138:141], v[208:211], v[76:79]
	v_mfma_f32_16x16x32_bf16 v[72:75], v[150:153], v[208:211], v[72:75]
	v_mfma_f32_16x16x32_bf16 v[124:127], v[142:145], v[170:173], v[124:127]
	v_mfma_f32_16x16x32_bf16 v[120:123], v[154:157], v[170:173], v[120:123]
	v_mfma_f32_16x16x32_bf16 v[108:111], v[142:145], v[178:181], v[108:111]
	v_mfma_f32_16x16x32_bf16 v[104:107], v[154:157], v[178:181], v[104:107]
	v_mfma_f32_16x16x32_bf16 v[92:95], v[142:145], v[196:199], v[92:95]
	v_mfma_f32_16x16x32_bf16 v[88:91], v[154:157], v[196:199], v[88:91]
	v_mfma_f32_16x16x32_bf16 v[76:79], v[142:145], v[212:215], v[76:79]
	v_mfma_f32_16x16x32_bf16 v[72:75], v[154:157], v[212:215], v[72:75]
	s_setprio 0
	s_barrier
	s_mov_b32 m0, s56
	v_add_u32_e32 v228, s60, v147
	v_lshl_add_u64 v[158:159], v[158:159], 0, s[90:91]
	ds_read_b128 v[216:219], v228
	ds_read_b128 v[220:223], v228 offset:1024
	ds_read_b128 v[224:227], v228 offset:2048
	ds_read_b128 v[228:231], v228 offset:3072
	global_load_lds_dwordx4 v[158:159], off
	s_mov_b32 m0, s57
	v_lshl_add_u64 v[158:159], v[200:201], 0, s[90:91]
	global_load_lds_dwordx4 v[158:159], off
	s_barrier
	s_waitcnt lgkmcnt(0)
	s_setprio 1
	v_mfma_f32_16x16x32_bf16 v[116:119], v[216:219], v[166:169], v[116:119]
	v_mfma_f32_16x16x32_bf16 v[112:115], v[224:227], v[166:169], v[112:115]
	v_mfma_f32_16x16x32_bf16 v[100:103], v[216:219], v[174:177], v[100:103]
	v_mfma_f32_16x16x32_bf16 v[96:99], v[224:227], v[174:177], v[96:99]
	v_mfma_f32_16x16x32_bf16 v[84:87], v[216:219], v[182:185], v[84:87]
	v_mfma_f32_16x16x32_bf16 v[80:83], v[224:227], v[182:185], v[80:83]
	v_mfma_f32_16x16x32_bf16 v[68:71], v[216:219], v[208:211], v[68:71]
	v_mfma_f32_16x16x32_bf16 v[64:67], v[224:227], v[208:211], v[64:67]
	v_mfma_f32_16x16x32_bf16 v[116:119], v[220:223], v[170:173], v[116:119]
	v_mfma_f32_16x16x32_bf16 v[112:115], v[228:231], v[170:173], v[112:115]
	v_mfma_f32_16x16x32_bf16 v[100:103], v[220:223], v[178:181], v[100:103]
	v_mfma_f32_16x16x32_bf16 v[96:99], v[228:231], v[178:181], v[96:99]
	v_mfma_f32_16x16x32_bf16 v[84:87], v[220:223], v[196:199], v[84:87]
	v_mfma_f32_16x16x32_bf16 v[80:83], v[228:231], v[196:199], v[80:83]
	v_mfma_f32_16x16x32_bf16 v[68:71], v[220:223], v[212:215], v[68:71]
	v_mfma_f32_16x16x32_bf16 v[64:67], v[228:231], v[212:215], v[64:67]
	s_setprio 0
	s_mov_b32 m0, s58
	v_lshl_add_u64 v[158:159], v[232:233], 0, s[90:91]
	s_barrier
	ds_read_b128 v[166:169], v149 offset:49152
	ds_read_b128 v[170:173], v149 offset:50176
	ds_read_b128 v[174:177], v149 offset:51200
	ds_read_b128 v[178:181], v149 offset:52224
	ds_read_b128 v[182:185], v149 offset:53248
	ds_read_b128 v[196:199], v149 offset:54272
	ds_read_b128 v[208:211], v149 offset:55296
	ds_read_b128 v[212:215], v149 offset:56320
	global_load_lds_dwordx4 v[158:159], off
	s_mov_b32 m0, s59
	v_lshl_add_u64 v[158:159], v[234:235], 0, s[90:91]
	global_load_lds_dwordx4 v[158:159], off
	s_barrier
; __device__ __forceinline__ unsigned cvt_pk_bf16(float lo, float hi) { unsigned r; asm volatile("v_cvt_pk_bf16_f32 %0, %1, %2" : "=v"(r) : "v"(lo), "v"(hi)); return r; }
; __device__ __forceinline__ float rinv_st(stat_t s, float invn) { return rsqrtf((float)((double)s * (1.0 / 4294967296.0)) * invn + 1e-6f); }
; #define PG8_STAGE(bufoff, gbase, voff) do { _Pragma("unroll") for (int _i = 0; _i < 2; ++_i) \
;         __builtin_amdgcn_global_load_lds((const unsigned*)((const char*)(gbase) + (voff)[_i]), (LAS unsigned*)(lds + (bufoff) + ldsw + _i * 8192), 16, 0, 0); } while (0)
; #define PG8_LDA(dst, b, h) do { _Pragma("unroll") for (int m = 0; m < 4; ++m) _Pragma("unroll") for (int k = 0; k < 2; ++k) dst[m][k] = *(const LAS bf16x8*)(lds + PG8_SA(b, h) + aoff + m * 2048 + k * 1024); } while (0)
; template <class Epi>
; __device__ __forceinline__ void gemm_phase(const int TID, const int BID, LAS unsigned char* lds, const Gemm g, const StaticOrder& S, const Epi& E) {
;     ...
;             PG8_BAR; PG8_WAIT_L(0); PG8_MMA(0, 1, At, B1); PG8_BAR;
;             PG8_LDA(At, 1, 1); PG8_STAGE(PG8_SA(1, 0), a3, voffA);
;             PG8_BAR; PG8_WAIT_L(0); PG8_MMA(1, 0, At, B0); PG8_BAR; PG8_SCHED;
;             PG8_STAGE(PG8_SB(1, 1), b3 + hstepB, voffB);
;             PG8_WAIT_V(6); PG8_BAR; PG8_MMA(1, 1, At, B1); PG8_BAR;
;     __device__ __forceinline__ void operator()(const f32x4 (&acc)[2][2][4][2], const Unit& u, int wr, int wc, int fr, int fq) const {
;         const int row0 = u.pm * BM + wr * 64 + fr, col0 = u.pn * BM + wc * 32 + 8 * fq;
; #pragma unroll
;         for (int ai = 0; ai < 2; ++ai)
; #pragma unroll
;             for (int m = 0; m < 4; ++m) {
;                 const int row = row0 + ai * HALF + m * 16; const float r = rinv_st(stats[row], 1.0f / 2048.0f);
;                 bf16_t* rowp = U + (size_t)row * FF + col0;
; #pragma unroll
;                 for (int bj = 0; bj < 2; ++bj) {
;                     f32x4 v0 = acc[ai][bj][m][0] * r, v1 = acc[ai][bj][m][1] * r;
; #pragma unroll
;                     for (int j = 0; j < 4; ++j) { const float a = fmaxf(v0[j], 0.f), b = fmaxf(v1[j], 0.f); v0[j] = a * a; v1[j] = b * b; }
;                     u32x4 w; w.x = cvt_pk_bf16(v0[0], v0[1]); w.y = cvt_pk_bf16(v0[2], v0[3]); w.z = cvt_pk_bf16(v1[0], v1[1]); w.w = cvt_pk_bf16(v1[2], v1[3]);
;                     *(u32x4*)(rowp + bj * HALF) = w;
	s_waitcnt lgkmcnt(0)
	s_setprio 1
	v_mfma_f32_16x16x32_bf16 v[60:63], v[138:141], v[166:169], v[60:63]
	v_mfma_f32_16x16x32_bf16 v[56:59], v[150:153], v[166:169], v[56:59]
	v_mfma_f32_16x16x32_bf16 v[44:47], v[138:141], v[174:177], v[44:47]
	v_mfma_f32_16x16x32_bf16 v[40:43], v[150:153], v[174:177], v[40:43]
	v_mfma_f32_16x16x32_bf16 v[28:31], v[138:141], v[182:185], v[28:31]
	v_mfma_f32_16x16x32_bf16 v[24:27], v[150:153], v[182:185], v[24:27]
	v_mfma_f32_16x16x32_bf16 v[12:15], v[138:141], v[208:211], v[12:15]
	v_mfma_f32_16x16x32_bf16 v[8:11], v[150:153], v[208:211], v[8:11]
	v_mfma_f32_16x16x32_bf16 v[60:63], v[142:145], v[170:173], v[60:63]
	v_mfma_f32_16x16x32_bf16 v[56:59], v[154:157], v[170:173], v[56:59]
	v_mfma_f32_16x16x32_bf16 v[44:47], v[142:145], v[178:181], v[44:47]
	v_mfma_f32_16x16x32_bf16 v[40:43], v[154:157], v[178:181], v[40:43]
	v_mfma_f32_16x16x32_bf16 v[28:31], v[142:145], v[196:199], v[28:31]
	v_mfma_f32_16x16x32_bf16 v[24:27], v[154:157], v[196:199], v[24:27]
	v_mfma_f32_16x16x32_bf16 v[12:15], v[142:145], v[212:215], v[12:15]
	v_mfma_f32_16x16x32_bf16 v[8:11], v[154:157], v[212:215], v[8:11]
	s_setprio 0
	s_barrier
	s_add_u32 s36, s36, 0x80080
	s_addc_u32 s37, s37, 0
	s_mov_b32 m0, s61
	v_lshl_add_u64 v[138:139], s[36:37], 0, v[160:161]
	global_load_lds_dwordx4 v[138:139], off
	s_mov_b32 m0, s62
	v_lshl_add_u64 v[138:139], s[36:37], 0, v[132:133]
	global_load_lds_dwordx4 v[138:139], off
	s_waitcnt vmcnt(6)
	s_barrier
	s_setprio 1
	v_mfma_f32_16x16x32_bf16 v[52:55], v[216:219], v[166:169], v[52:55]
	v_mfma_f32_16x16x32_bf16 v[48:51], v[224:227], v[166:169], v[48:51]
	v_mfma_f32_16x16x32_bf16 v[36:39], v[216:219], v[174:177], v[36:39]
	v_mfma_f32_16x16x32_bf16 v[32:35], v[224:227], v[174:177], v[32:35]
	v_mfma_f32_16x16x32_bf16 v[20:23], v[216:219], v[182:185], v[20:23]
	v_mfma_f32_16x16x32_bf16 v[16:19], v[224:227], v[182:185], v[16:19]
	v_mfma_f32_16x16x32_bf16 v[4:7], v[216:219], v[208:211], v[4:7]
	v_mfma_f32_16x16x32_bf16 v[0:3], v[224:227], v[208:211], v[0:3]
	v_mfma_f32_16x16x32_bf16 v[52:55], v[220:223], v[170:173], v[52:55]
	v_mfma_f32_16x16x32_bf16 v[48:51], v[228:231], v[170:173], v[48:51]
	v_mfma_f32_16x16x32_bf16 v[36:39], v[220:223], v[178:181], v[36:39]
	v_mfma_f32_16x16x32_bf16 v[32:35], v[228:231], v[178:181], v[32:35]
	v_mfma_f32_16x16x32_bf16 v[20:23], v[220:223], v[196:199], v[20:23]
	v_mfma_f32_16x16x32_bf16 v[16:19], v[228:231], v[196:199], v[16:19]
	v_mfma_f32_16x16x32_bf16 v[4:7], v[220:223], v[212:215], v[4:7]
	v_mfma_f32_16x16x32_bf16 v[0:3], v[228:231], v[212:215], v[0:3]
	s_setprio 0
	s_add_i32 s64, s64, 2
	s_add_u32 s34, s34, 0x100
	s_addc_u32 s35, s35, 0
	s_add_u32 s22, s22, 0x100
	s_addc_u32 s23, s23, 0
	s_cmp_gt_u32 s64, 29
	s_barrier
	s_cbranch_scc0 .LBB0_925
	v_lshl_add_u32 v142, s30, 8, v146
	v_ashrrev_i32_e32 v143, 31, v142
	v_lshl_add_u64 v[138:139], v[142:143], 3, s[10:11]
	v_lshl_or_b32 v140, s0, 8, v148
	v_ashrrev_i32_e32 v141, 31, v140
	s_mov_b64 s[0:1], 0x200000
	s_mov_b32 s30, s18
	s_mov_b64 s[36:37], s[28:29]
	s_mov_b64 s[34:35], s[26:27]
	v_mov_b64_e32 v[144:145], v[236:237]
	v_cvt_f64_u32_e32 v[150:151], v145
	v_ldexp_f64 v[150:151], v[150:151], 32
	v_cvt_f64_u32_e32 v[144:145], v144
	v_add_f64 v[144:145], v[150:151], v[144:145]
	v_ldexp_f64 v[144:145], v[144:145], s93
	v_cvt_f32_f64_e32 v144, v[144:145]
	v_fmamk_f32 v144, v144, 0x3a000000, v189
	v_cmp_gt_f32_e32 vcc, s78, v144
	v_mul_f32_e32 v145, 0x4b800000, v144
	s_nop 0
	v_cndmask_b32_e32 v144, v144, v145, vcc
	v_rsq_f32_e32 v144, v144
	s_nop 0
	v_mul_f32_e32 v145, 0x45800000, v144
	v_cndmask_b32_e32 v150, v144, v145, vcc
	v_pk_mul_f32 v[120:121], v[120:121], v[150:151] op_sel_hi:[1,0]
	v_pk_mul_f32 v[124:125], v[124:125], v[150:151] op_sel_hi:[1,0]
	v_pk_mul_f32 v[122:123], v[122:123], v[150:151] op_sel_hi:[1,0]
	v_max_f32_e32 v120, 0, v120
	v_lshlrev_b64 v[144:145], 14, v[142:143]
	v_pk_mul_f32 v[126:127], v[126:127], v[150:151] op_sel_hi:[1,0]
	v_mul_f32_e32 v143, v120, v120
	v_max_f32_e32 v120, 0, v125
	v_max_f32_e32 v121, 0, v121
	v_max_f32_e32 v122, 0, v122
	v_lshl_add_u64 v[152:153], s[14:15], 0, v[144:145]
	v_lshlrev_b64 v[144:145], 1, v[140:141]
	v_max_f32_e32 v124, 0, v124
	v_mul_f32_e32 v120, v120, v120
	v_mul_f32_e32 v125, v121, v121
	v_max_f32_e32 v121, 0, v126
	v_mul_f32_e32 v126, v122, v122
	v_max_f32_e32 v122, 0, v127
	v_max_f32_e32 v123, 0, v123
	v_pk_mul_f32 v[114:115], v[114:115], v[150:151] op_sel_hi:[1,0]
	v_pk_mul_f32 v[112:113], v[112:113], v[150:151] op_sel_hi:[1,0]
	v_lshl_add_u64 v[140:141], v[152:153], 0, v[144:145]
	v_mul_f32_e32 v124, v124, v124
	v_mul_f32_e32 v121, v121, v121
	v_mul_f32_e32 v122, v122, v122
	v_mul_f32_e32 v123, v123, v123
	v_cvt_pk_bf16_f32 v120, v124, v120
	v_pk_mul_f32 v[118:119], v[118:119], v[150:151] op_sel_hi:[1,0]
	v_pk_mul_f32 v[116:117], v[116:117], v[150:151] op_sel_hi:[1,0]
	v_max_f32_e32 v112, 0, v112
	v_max_f32_e32 v113, 0, v113
	v_max_f32_e32 v114, 0, v114
	v_cvt_pk_bf16_f32 v121, v121, v122
	v_cvt_pk_bf16_f32 v122, v143, v125
	v_cvt_pk_bf16_f32 v123, v126, v123
	global_store_dwordx4 v[140:141], v[120:123], off
	v_max_f32_e32 v115, 0, v115
	v_max_f32_e32 v116, 0, v116
	v_mul_f32_e32 v120, v112, v112
	v_max_f32_e32 v112, 0, v117
	v_mul_f32_e32 v117, v113, v113
	v_max_f32_e32 v113, 0, v118
	v_mul_f32_e32 v118, v114, v114
	v_max_f32_e32 v114, 0, v119
	v_mul_f32_e32 v112, v112, v112
	v_mul_f32_e32 v113, v113, v113
	v_mul_f32_e32 v114, v114, v114
	v_mul_f32_e32 v115, v115, v115
	v_mul_f32_e32 v116, v116, v116
	v_cvt_pk_bf16_f32 v112, v116, v112
	v_cvt_pk_bf16_f32 v113, v113, v114
	v_cvt_pk_bf16_f32 v114, v120, v117
	v_cvt_pk_bf16_f32 v115, v118, v115
; __device__ __forceinline__ unsigned cvt_pk_bf16(float lo, float hi) { unsigned r; asm volatile("v_cvt_pk_bf16_f32 %0, %1, %2" : "=v"(r) : "v"(lo), "v"(hi)); return r; }
; __device__ __forceinline__ float rinv_st(stat_t s, float invn) { return rsqrtf((float)((double)s * (1.0 / 4294967296.0)) * invn + 1e-6f); }
;     __device__ __forceinline__ void operator()(const f32x4 (&acc)[2][2][4][2], const Unit& u, int wr, int wc, int fr, int fq) const {
;     ...
;                 const int row = row0 + ai * HALF + m * 16; const float r = rinv_st(stats[row], 1.0f / 2048.0f);
;                 bf16_t* rowp = U + (size_t)row * FF + col0;
; #pragma unroll
;                 for (int bj = 0; bj < 2; ++bj) {
;                     f32x4 v0 = acc[ai][bj][m][0] * r, v1 = acc[ai][bj][m][1] * r;
; #pragma unroll
;                     for (int j = 0; j < 4; ++j) { const float a = fmaxf(v0[j], 0.f), b = fmaxf(v1[j], 0.f); v0[j] = a * a; v1[j] = b * b; }
;                     u32x4 w; w.x = cvt_pk_bf16(v0[0], v0[1]); w.y = cvt_pk_bf16(v0[2], v0[3]); w.z = cvt_pk_bf16(v1[0], v1[1]); w.w = cvt_pk_bf16(v1[2], v1[3]);
;                     *(u32x4*)(rowp + bj * HALF) = w;
	global_store_dwordx4 v[140:141], v[112:115], off offset:256
	s_nop 1
	v_mov_b64_e32 v[114:115], v[238:239]
	v_cvt_f64_u32_e32 v[116:117], v115
	v_ldexp_f64 v[116:117], v[116:117], 32
	v_cvt_f64_u32_e32 v[114:115], v114
	v_add_f64 v[114:115], v[116:117], v[114:115]
	v_ldexp_f64 v[114:115], v[114:115], s93
	v_cvt_f32_f64_e32 v114, v[114:115]
	v_fmamk_f32 v114, v114, 0x3a000000, v189
	v_cmp_gt_f32_e32 vcc, s78, v114
	v_mul_f32_e32 v115, 0x4b800000, v114
	v_or_b32_e32 v112, 16, v142
	v_cndmask_b32_e32 v114, v114, v115, vcc
	v_rsq_f32_e32 v114, v114
	v_ashrrev_i32_e32 v113, 31, v112
	v_lshlrev_b64 v[112:113], 14, v[112:113]
	v_lshl_add_u64 v[112:113], s[14:15], 0, v[112:113]
	v_mul_f32_e32 v115, 0x45800000, v114
	v_cndmask_b32_e32 v114, v114, v115, vcc
	v_pk_mul_f32 v[104:105], v[104:105], v[114:115] op_sel_hi:[1,0]
	v_pk_mul_f32 v[108:109], v[108:109], v[114:115] op_sel_hi:[1,0]
	v_pk_mul_f32 v[106:107], v[106:107], v[114:115] op_sel_hi:[1,0]
	v_max_f32_e32 v104, 0, v104
	v_pk_mul_f32 v[110:111], v[110:111], v[114:115] op_sel_hi:[1,0]
	v_mul_f32_e32 v115, v104, v104
	v_max_f32_e32 v104, 0, v109
	v_max_f32_e32 v105, 0, v105
	v_max_f32_e32 v106, 0, v106
	v_max_f32_e32 v108, 0, v108
	v_mul_f32_e32 v104, v104, v104
	v_mul_f32_e32 v109, v105, v105
	v_max_f32_e32 v105, 0, v110
	v_mul_f32_e32 v110, v106, v106
	v_max_f32_e32 v106, 0, v111
	v_max_f32_e32 v107, 0, v107
	v_pk_mul_f32 v[98:99], v[98:99], v[114:115] op_sel_hi:[1,0]
	v_pk_mul_f32 v[96:97], v[96:97], v[114:115] op_sel_hi:[1,0]
	v_lshl_add_u64 v[112:113], v[112:113], 0, v[144:145]
	v_mul_f32_e32 v108, v108, v108
	v_mul_f32_e32 v105, v105, v105
	v_mul_f32_e32 v106, v106, v106
	v_mul_f32_e32 v107, v107, v107
	v_cvt_pk_bf16_f32 v104, v108, v104
	v_pk_mul_f32 v[102:103], v[102:103], v[114:115] op_sel_hi:[1,0]
	v_pk_mul_f32 v[100:101], v[100:101], v[114:115] op_sel_hi:[1,0]
	v_max_f32_e32 v96, 0, v96
	v_max_f32_e32 v97, 0, v97
	v_max_f32_e32 v98, 0, v98
	v_cvt_pk_bf16_f32 v105, v105, v106
	v_cvt_pk_bf16_f32 v106, v115, v109
	v_cvt_pk_bf16_f32 v107, v110, v107
	global_store_dwordx4 v[112:113], v[104:107], off
	v_max_f32_e32 v99, 0, v99
	v_max_f32_e32 v100, 0, v100
	v_mul_f32_e32 v104, v96, v96
	v_max_f32_e32 v96, 0, v101
	v_mul_f32_e32 v101, v97, v97
	v_max_f32_e32 v97, 0, v102
	v_mul_f32_e32 v102, v98, v98
	v_max_f32_e32 v98, 0, v103
	v_mul_f32_e32 v96, v96, v96
	v_mul_f32_e32 v97, v97, v97
	v_mul_f32_e32 v98, v98, v98
	v_mul_f32_e32 v99, v99, v99
	v_mul_f32_e32 v100, v100, v100
	v_cvt_pk_bf16_f32 v96, v100, v96
	v_cvt_pk_bf16_f32 v97, v97, v98
	v_cvt_pk_bf16_f32 v98, v104, v101
	v_cvt_pk_bf16_f32 v99, v102, v99
	global_store_dwordx4 v[112:113], v[96:99], off offset:256
	s_nop 1
	v_mov_b64_e32 v[98:99], v[240:241]
	v_cvt_f64_u32_e32 v[100:101], v99
	v_ldexp_f64 v[100:101], v[100:101], 32
	v_cvt_f64_u32_e32 v[98:99], v98
	v_add_f64 v[98:99], v[100:101], v[98:99]
	v_ldexp_f64 v[98:99], v[98:99], s93
	v_cvt_f32_f64_e32 v98, v[98:99]
	v_fmamk_f32 v98, v98, 0x3a000000, v189
	v_cmp_gt_f32_e32 vcc, s78, v98
	v_mul_f32_e32 v99, 0x4b800000, v98
	v_or_b32_e32 v96, 32, v142
	v_cndmask_b32_e32 v98, v98, v99, vcc
	v_rsq_f32_e32 v98, v98
	v_ashrrev_i32_e32 v97, 31, v96
	v_lshlrev_b64 v[96:97], 14, v[96:97]
	v_lshl_add_u64 v[96:97], s[14:15], 0, v[96:97]
	v_mul_f32_e32 v99, 0x45800000, v98
	v_cndmask_b32_e32 v98, v98, v99, vcc
	v_pk_mul_f32 v[88:89], v[88:89], v[98:99] op_sel_hi:[1,0]
	v_pk_mul_f32 v[92:93], v[92:93], v[98:99] op_sel_hi:[1,0]
	v_pk_mul_f32 v[90:91], v[90:91], v[98:99] op_sel_hi:[1,0]
	v_max_f32_e32 v88, 0, v88
	v_pk_mul_f32 v[94:95], v[94:95], v[98:99] op_sel_hi:[1,0]
	v_mul_f32_e32 v99, v88, v88
	v_max_f32_e32 v88, 0, v93
	v_max_f32_e32 v89, 0, v89
	v_max_f32_e32 v90, 0, v90
	v_max_f32_e32 v92, 0, v92
	v_mul_f32_e32 v88, v88, v88
	v_mul_f32_e32 v93, v89, v89
	v_max_f32_e32 v89, 0, v94
	v_mul_f32_e32 v94, v90, v90
	v_max_f32_e32 v90, 0, v95
	v_max_f32_e32 v91, 0, v91
	v_pk_mul_f32 v[82:83], v[82:83], v[98:99] op_sel_hi:[1,0]
	v_pk_mul_f32 v[80:81], v[80:81], v[98:99] op_sel_hi:[1,0]
	v_lshl_add_u64 v[96:97], v[96:97], 0, v[144:145]
	v_mul_f32_e32 v92, v92, v92
	v_mul_f32_e32 v89, v89, v89
	v_mul_f32_e32 v90, v90, v90
	v_mul_f32_e32 v91, v91, v91
	v_cvt_pk_bf16_f32 v88, v92, v88
	v_pk_mul_f32 v[86:87], v[86:87], v[98:99] op_sel_hi:[1,0]
	v_pk_mul_f32 v[84:85], v[84:85], v[98:99] op_sel_hi:[1,0]
	v_max_f32_e32 v80, 0, v80
	v_max_f32_e32 v81, 0, v81
	v_max_f32_e32 v82, 0, v82
	v_cvt_pk_bf16_f32 v89, v89, v90
	v_cvt_pk_bf16_f32 v90, v99, v93
	v_cvt_pk_bf16_f32 v91, v94, v91
	global_store_dwordx4 v[96:97], v[88:91], off
	v_max_f32_e32 v83, 0, v83
	v_max_f32_e32 v84, 0, v84
	v_mul_f32_e32 v88, v80, v80
	v_max_f32_e32 v80, 0, v85
	v_mul_f32_e32 v85, v81, v81
	v_max_f32_e32 v81, 0, v86
	v_mul_f32_e32 v86, v82, v82
	v_max_f32_e32 v82, 0, v87
	v_mul_f32_e32 v80, v80, v80
	v_mul_f32_e32 v81, v81, v81
	v_mul_f32_e32 v82, v82, v82
	v_mul_f32_e32 v83, v83, v83
	v_mul_f32_e32 v84, v84, v84
	v_cvt_pk_bf16_f32 v80, v84, v80
	v_cvt_pk_bf16_f32 v81, v81, v82
	v_cvt_pk_bf16_f32 v82, v88, v85
	v_cvt_pk_bf16_f32 v83, v86, v83
	global_store_dwordx4 v[96:97], v[80:83], off offset:256
	s_nop 1
	v_mov_b64_e32 v[82:83], v[242:243]
	v_cvt_f64_u32_e32 v[84:85], v83
	v_ldexp_f64 v[84:85], v[84:85], 32
	v_cvt_f64_u32_e32 v[82:83], v82
	v_add_f64 v[82:83], v[84:85], v[82:83]
	v_ldexp_f64 v[82:83], v[82:83], s93
	v_cvt_f32_f64_e32 v82, v[82:83]
	v_fmamk_f32 v82, v82, 0x3a000000, v189
	v_cmp_gt_f32_e32 vcc, s78, v82
	v_mul_f32_e32 v83, 0x4b800000, v82
	v_or_b32_e32 v80, 48, v142
	v_cndmask_b32_e32 v82, v82, v83, vcc
	v_rsq_f32_e32 v82, v82
	v_ashrrev_i32_e32 v81, 31, v80
	v_lshlrev_b64 v[80:81], 14, v[80:81]
; __device__ __forceinline__ unsigned cvt_pk_bf16(float lo, float hi) { unsigned r; asm volatile("v_cvt_pk_bf16_f32 %0, %1, %2" : "=v"(r) : "v"(lo), "v"(hi)); return r; }
; __device__ __forceinline__ float rinv_st(stat_t s, float invn) { return rsqrtf((float)((double)s * (1.0 / 4294967296.0)) * invn + 1e-6f); }
;     __device__ __forceinline__ void operator()(const f32x4 (&acc)[2][2][4][2], const Unit& u, int wr, int wc, int fr, int fq) const {
;     ...
;                 const int row = row0 + ai * HALF + m * 16; const float r = rinv_st(stats[row], 1.0f / 2048.0f);
;                 bf16_t* rowp = U + (size_t)row * FF + col0;
; #pragma unroll
;                 for (int bj = 0; bj < 2; ++bj) {
;                     f32x4 v0 = acc[ai][bj][m][0] * r, v1 = acc[ai][bj][m][1] * r;
; #pragma unroll
;                     for (int j = 0; j < 4; ++j) { const float a = fmaxf(v0[j], 0.f), b = fmaxf(v1[j], 0.f); v0[j] = a * a; v1[j] = b * b; }
;                     u32x4 w; w.x = cvt_pk_bf16(v0[0], v0[1]); w.y = cvt_pk_bf16(v0[2], v0[3]); w.z = cvt_pk_bf16(v1[0], v1[1]); w.w = cvt_pk_bf16(v1[2], v1[3]);
;                     *(u32x4*)(rowp + bj * HALF) = w;
;                 }
	v_lshl_add_u64 v[80:81], s[14:15], 0, v[80:81]
	v_mul_f32_e32 v83, 0x45800000, v82
	v_cndmask_b32_e32 v82, v82, v83, vcc
	v_pk_mul_f32 v[72:73], v[72:73], v[82:83] op_sel_hi:[1,0]
	v_pk_mul_f32 v[76:77], v[76:77], v[82:83] op_sel_hi:[1,0]
	v_pk_mul_f32 v[74:75], v[74:75], v[82:83] op_sel_hi:[1,0]
	v_max_f32_e32 v72, 0, v72
	v_pk_mul_f32 v[78:79], v[78:79], v[82:83] op_sel_hi:[1,0]
	v_mul_f32_e32 v83, v72, v72
	v_max_f32_e32 v72, 0, v77
	v_max_f32_e32 v73, 0, v73
	v_max_f32_e32 v74, 0, v74
	v_max_f32_e32 v76, 0, v76
	v_mul_f32_e32 v72, v72, v72
	v_mul_f32_e32 v77, v73, v73
	v_max_f32_e32 v73, 0, v78
	v_mul_f32_e32 v78, v74, v74
	v_max_f32_e32 v74, 0, v79
	v_max_f32_e32 v75, 0, v75
	v_pk_mul_f32 v[66:67], v[66:67], v[82:83] op_sel_hi:[1,0]
	v_pk_mul_f32 v[64:65], v[64:65], v[82:83] op_sel_hi:[1,0]
	v_lshl_add_u64 v[80:81], v[80:81], 0, v[144:145]
	v_mul_f32_e32 v76, v76, v76
	v_mul_f32_e32 v73, v73, v73
	v_mul_f32_e32 v74, v74, v74
	v_mul_f32_e32 v75, v75, v75
	v_cvt_pk_bf16_f32 v72, v76, v72
	v_pk_mul_f32 v[70:71], v[70:71], v[82:83] op_sel_hi:[1,0]
	v_pk_mul_f32 v[68:69], v[68:69], v[82:83] op_sel_hi:[1,0]
	v_max_f32_e32 v64, 0, v64
	v_max_f32_e32 v65, 0, v65
	v_max_f32_e32 v66, 0, v66
	v_cvt_pk_bf16_f32 v73, v73, v74
	v_cvt_pk_bf16_f32 v74, v83, v77
	v_cvt_pk_bf16_f32 v75, v78, v75
	global_store_dwordx4 v[80:81], v[72:75], off
	v_max_f32_e32 v67, 0, v67
	v_max_f32_e32 v68, 0, v68
	v_mul_f32_e32 v72, v64, v64
	v_max_f32_e32 v64, 0, v69
	v_mul_f32_e32 v69, v65, v65
	v_max_f32_e32 v65, 0, v70
	v_mul_f32_e32 v70, v66, v66
	v_max_f32_e32 v66, 0, v71
	v_mul_f32_e32 v64, v64, v64
	v_mul_f32_e32 v65, v65, v65
	v_mul_f32_e32 v66, v66, v66
	v_mul_f32_e32 v67, v67, v67
	v_mul_f32_e32 v68, v68, v68
	v_cvt_pk_bf16_f32 v64, v68, v64
	v_cvt_pk_bf16_f32 v65, v65, v66
	v_cvt_pk_bf16_f32 v66, v72, v69
	v_cvt_pk_bf16_f32 v67, v70, v67
	global_store_dwordx4 v[80:81], v[64:67], off offset:256
	s_nop 1
	v_mov_b64_e32 v[64:65], v[244:245]
	v_cvt_f64_u32_e32 v[66:67], v65
	v_ldexp_f64 v[66:67], v[66:67], 32
	v_cvt_f64_u32_e32 v[64:65], v64
	v_add_f64 v[64:65], v[66:67], v[64:65]
	v_ldexp_f64 v[64:65], v[64:65], s93
	v_cvt_f32_f64_e32 v64, v[64:65]
	v_fmamk_f32 v64, v64, 0x3a000000, v189
	v_cmp_gt_f32_e32 vcc, s78, v64
	v_mul_f32_e32 v65, 0x4b800000, v64
	s_nop 0
	v_cndmask_b32_e32 v64, v64, v65, vcc
	v_rsq_f32_e32 v64, v64
	s_nop 0
	v_mul_f32_e32 v65, 0x45800000, v64
	v_cndmask_b32_e32 v66, v64, v65, vcc
	v_pk_mul_f32 v[56:57], v[56:57], v[66:67] op_sel_hi:[1,0]
	v_pk_mul_f32 v[60:61], v[60:61], v[66:67] op_sel_hi:[1,0]
	v_pk_mul_f32 v[58:59], v[58:59], v[66:67] op_sel_hi:[1,0]
	v_max_f32_e32 v56, 0, v56
	v_pk_mul_f32 v[62:63], v[62:63], v[66:67] op_sel_hi:[1,0]
	v_max_f32_e32 v60, 0, v60
	v_mul_f32_e32 v67, v56, v56
	v_max_f32_e32 v56, 0, v61
	v_max_f32_e32 v57, 0, v57
	v_max_f32_e32 v58, 0, v58
	v_lshl_add_u64 v[64:65], v[140:141], 0, s[0:1]
	v_mul_f32_e32 v60, v60, v60
	v_mul_f32_e32 v56, v56, v56
	v_mul_f32_e32 v61, v57, v57
	v_max_f32_e32 v57, 0, v62
	v_mul_f32_e32 v62, v58, v58
	v_max_f32_e32 v58, 0, v63
	s_mov_b32 s0, 0x200000
	v_mul_f32_e32 v57, v57, v57
	v_max_f32_e32 v59, 0, v59
	v_mul_f32_e32 v58, v58, v58
	v_cvt_pk_bf16_f32 v56, v60, v56
	v_add_co_u32_e32 v60, vcc, s0, v140
	v_pk_mul_f32 v[50:51], v[50:51], v[66:67] op_sel_hi:[1,0]
	v_pk_mul_f32 v[48:49], v[48:49], v[66:67] op_sel_hi:[1,0]
	v_mul_f32_e32 v59, v59, v59
	v_cvt_pk_bf16_f32 v57, v57, v58
	v_cvt_pk_bf16_f32 v58, v67, v61
	v_addc_co_u32_e32 v61, vcc, 0, v141, vcc
	v_pk_mul_f32 v[54:55], v[54:55], v[66:67] op_sel_hi:[1,0]
	v_pk_mul_f32 v[52:53], v[52:53], v[66:67] op_sel_hi:[1,0]
	v_max_f32_e32 v48, 0, v48
	v_max_f32_e32 v49, 0, v49
	v_max_f32_e32 v50, 0, v50
	v_cvt_pk_bf16_f32 v59, v62, v59
	global_store_dwordx4 v[60:61], v[56:59], off
	v_max_f32_e32 v51, 0, v51
	v_max_f32_e32 v52, 0, v52
	v_mul_f32_e32 v56, v48, v48
	v_max_f32_e32 v48, 0, v53
	v_mul_f32_e32 v53, v49, v49
	v_max_f32_e32 v49, 0, v54
	v_mul_f32_e32 v54, v50, v50
	v_max_f32_e32 v50, 0, v55
	v_mul_f32_e32 v48, v48, v48
	v_mul_f32_e32 v49, v49, v49
	v_mul_f32_e32 v50, v50, v50
	v_mul_f32_e32 v51, v51, v51
	v_mul_f32_e32 v52, v52, v52
	v_cvt_pk_bf16_f32 v48, v52, v48
	v_cvt_pk_bf16_f32 v49, v49, v50
	v_cvt_pk_bf16_f32 v50, v56, v53
	v_cvt_pk_bf16_f32 v51, v54, v51
	global_store_dwordx4 v[64:65], v[48:51], off offset:256
	s_nop 1
	v_mov_b64_e32 v[48:49], v[246:247]
	s_mov_b64 s[0:1], 0x240000
	v_cvt_f64_u32_e32 v[50:51], v49
	v_ldexp_f64 v[50:51], v[50:51], 32
	v_cvt_f64_u32_e32 v[48:49], v48
	v_add_f64 v[48:49], v[50:51], v[48:49]
	v_ldexp_f64 v[48:49], v[48:49], s93
	v_cvt_f32_f64_e32 v48, v[48:49]
	v_fmamk_f32 v48, v48, 0x3a000000, v189
	v_cmp_gt_f32_e32 vcc, s78, v48
	v_mul_f32_e32 v49, 0x4b800000, v48
	s_nop 0
	v_cndmask_b32_e32 v48, v48, v49, vcc
	v_rsq_f32_e32 v48, v48
	s_nop 0
	v_mul_f32_e32 v49, 0x45800000, v48
	v_cndmask_b32_e32 v50, v48, v49, vcc
	v_pk_mul_f32 v[40:41], v[40:41], v[50:51] op_sel_hi:[1,0]
	v_pk_mul_f32 v[44:45], v[44:45], v[50:51] op_sel_hi:[1,0]
	v_pk_mul_f32 v[42:43], v[42:43], v[50:51] op_sel_hi:[1,0]
	v_max_f32_e32 v40, 0, v40
	v_pk_mul_f32 v[46:47], v[46:47], v[50:51] op_sel_hi:[1,0]
	v_max_f32_e32 v44, 0, v44
	v_mul_f32_e32 v51, v40, v40
	v_max_f32_e32 v40, 0, v45
	v_max_f32_e32 v41, 0, v41
	v_max_f32_e32 v42, 0, v42
	v_lshl_add_u64 v[48:49], v[140:141], 0, s[0:1]
	v_mul_f32_e32 v44, v44, v44
	v_mul_f32_e32 v40, v40, v40
	v_mul_f32_e32 v45, v41, v41
	v_max_f32_e32 v41, 0, v46
	v_mul_f32_e32 v46, v42, v42
	v_max_f32_e32 v42, 0, v47
	s_mov_b32 s0, 0x240000
	v_mul_f32_e32 v41, v41, v41
	v_max_f32_e32 v43, 0, v43
	v_mul_f32_e32 v42, v42, v42
	v_cvt_pk_bf16_f32 v40, v44, v40
	v_add_co_u32_e32 v44, vcc, s0, v140
; __device__ __forceinline__ unsigned cvt_pk_bf16(float lo, float hi) { unsigned r; asm volatile("v_cvt_pk_bf16_f32 %0, %1, %2" : "=v"(r) : "v"(lo), "v"(hi)); return r; }
; __device__ __forceinline__ float rinv_st(stat_t s, float invn) { return rsqrtf((float)((double)s * (1.0 / 4294967296.0)) * invn + 1e-6f); }
; #define PG8_WAIT_V(n) asm volatile("s_waitcnt vmcnt(" #n ")" ::: "memory")
; #define PG8_BAR __builtin_amdgcn_s_barrier()
; template <class Epi>
; __device__ __forceinline__ void gemm_phase(const int TID, const int BID, LAS unsigned char* lds, const Gemm g, const StaticOrder& S, const Epi& E) {
;     ...
;         if (!has_next) break;
; #pragma unroll
;         for (int a = 0; a < 2; ++a)
; #pragma unroll
;             for (int b = 0; b < 2; ++b)
; #pragma unroll
;                 for (int m = 0; m < 4; ++m)
; #pragma unroll
;                     for (int n = 0; n < 2; ++n) acc[a][b][m][n] = (f32x4){0.f, 0.f, 0.f, 0.f};
;         cur = nxt; cA = nA; cB = nB; ++ui;
;     }
;     PG8_WAIT_V(0);
;     if (wr == 0) PG8_BAR;
;     PG8_BAR;
;     __device__ __forceinline__ void operator()(const f32x4 (&acc)[2][2][4][2], const Unit& u, int wr, int wc, int fr, int fq) const {
;     ...
;                 const int row = row0 + ai * HALF + m * 16; const float r = rinv_st(stats[row], 1.0f / 2048.0f);
;                 bf16_t* rowp = U + (size_t)row * FF + col0;
; #pragma unroll
;                 for (int bj = 0; bj < 2; ++bj) {
;                     f32x4 v0 = acc[ai][bj][m][0] * r, v1 = acc[ai][bj][m][1] * r;
; #pragma unroll
;                     for (int j = 0; j < 4; ++j) { const float a = fmaxf(v0[j], 0.f), b = fmaxf(v1[j], 0.f); v0[j] = a * a; v1[j] = b * b; }
;                     u32x4 w; w.x = cvt_pk_bf16(v0[0], v0[1]); w.y = cvt_pk_bf16(v0[2], v0[3]); w.z = cvt_pk_bf16(v1[0], v1[1]); w.w = cvt_pk_bf16(v1[2], v1[3]);
;                     *(u32x4*)(rowp + bj * HALF) = w;
;                 }
	v_pk_mul_f32 v[34:35], v[34:35], v[50:51] op_sel_hi:[1,0]
	v_pk_mul_f32 v[32:33], v[32:33], v[50:51] op_sel_hi:[1,0]
	v_mul_f32_e32 v43, v43, v43
	v_cvt_pk_bf16_f32 v41, v41, v42
	v_cvt_pk_bf16_f32 v42, v51, v45
	v_addc_co_u32_e32 v45, vcc, 0, v141, vcc
	v_pk_mul_f32 v[38:39], v[38:39], v[50:51] op_sel_hi:[1,0]
	v_pk_mul_f32 v[36:37], v[36:37], v[50:51] op_sel_hi:[1,0]
	v_max_f32_e32 v32, 0, v32
	v_max_f32_e32 v33, 0, v33
	v_max_f32_e32 v34, 0, v34
	v_cvt_pk_bf16_f32 v43, v46, v43
	global_store_dwordx4 v[44:45], v[40:43], off
	v_max_f32_e32 v35, 0, v35
	v_max_f32_e32 v36, 0, v36
	v_mul_f32_e32 v40, v32, v32
	v_max_f32_e32 v32, 0, v37
	v_mul_f32_e32 v37, v33, v33
	v_max_f32_e32 v33, 0, v38
	v_mul_f32_e32 v38, v34, v34
	v_max_f32_e32 v34, 0, v39
	v_mul_f32_e32 v32, v32, v32
	v_mul_f32_e32 v33, v33, v33
	v_mul_f32_e32 v34, v34, v34
	v_mul_f32_e32 v35, v35, v35
	v_mul_f32_e32 v36, v36, v36
	v_cvt_pk_bf16_f32 v32, v36, v32
	v_cvt_pk_bf16_f32 v33, v33, v34
	v_cvt_pk_bf16_f32 v34, v40, v37
	v_cvt_pk_bf16_f32 v35, v38, v35
	global_store_dwordx4 v[48:49], v[32:35], off offset:256
	s_nop 1
	v_mov_b64_e32 v[32:33], v[248:249]
	s_mov_b64 s[0:1], 0x280000
	v_cvt_f64_u32_e32 v[34:35], v33
	v_ldexp_f64 v[34:35], v[34:35], 32
	v_cvt_f64_u32_e32 v[32:33], v32
	v_add_f64 v[32:33], v[34:35], v[32:33]
	v_ldexp_f64 v[32:33], v[32:33], s93
	v_cvt_f32_f64_e32 v32, v[32:33]
	v_fmamk_f32 v32, v32, 0x3a000000, v189
	v_cmp_gt_f32_e32 vcc, s78, v32
	v_mul_f32_e32 v33, 0x4b800000, v32
	s_nop 0
	v_cndmask_b32_e32 v32, v32, v33, vcc
	v_rsq_f32_e32 v32, v32
	s_nop 0
	v_mul_f32_e32 v33, 0x45800000, v32
	v_cndmask_b32_e32 v34, v32, v33, vcc
	v_pk_mul_f32 v[24:25], v[24:25], v[34:35] op_sel_hi:[1,0]
	v_pk_mul_f32 v[28:29], v[28:29], v[34:35] op_sel_hi:[1,0]
	v_pk_mul_f32 v[26:27], v[26:27], v[34:35] op_sel_hi:[1,0]
	v_max_f32_e32 v24, 0, v24
	v_pk_mul_f32 v[30:31], v[30:31], v[34:35] op_sel_hi:[1,0]
	v_max_f32_e32 v28, 0, v28
	v_mul_f32_e32 v35, v24, v24
	v_max_f32_e32 v24, 0, v29
	v_max_f32_e32 v25, 0, v25
	v_max_f32_e32 v26, 0, v26
	v_lshl_add_u64 v[32:33], v[140:141], 0, s[0:1]
	v_mul_f32_e32 v28, v28, v28
	v_mul_f32_e32 v24, v24, v24
	v_mul_f32_e32 v29, v25, v25
	v_max_f32_e32 v25, 0, v30
	v_mul_f32_e32 v30, v26, v26
	v_max_f32_e32 v26, 0, v31
	s_mov_b32 s0, 0x280000
	v_mul_f32_e32 v25, v25, v25
	v_max_f32_e32 v27, 0, v27
	v_mul_f32_e32 v26, v26, v26
	v_cvt_pk_bf16_f32 v24, v28, v24
	v_add_co_u32_e32 v28, vcc, s0, v140
	v_pk_mul_f32 v[18:19], v[18:19], v[34:35] op_sel_hi:[1,0]
	v_pk_mul_f32 v[16:17], v[16:17], v[34:35] op_sel_hi:[1,0]
	v_mul_f32_e32 v27, v27, v27
	v_cvt_pk_bf16_f32 v25, v25, v26
	v_cvt_pk_bf16_f32 v26, v35, v29
	v_addc_co_u32_e32 v29, vcc, 0, v141, vcc
	v_pk_mul_f32 v[22:23], v[22:23], v[34:35] op_sel_hi:[1,0]
	v_pk_mul_f32 v[20:21], v[20:21], v[34:35] op_sel_hi:[1,0]
	v_max_f32_e32 v16, 0, v16
	v_max_f32_e32 v17, 0, v17
	v_max_f32_e32 v18, 0, v18
	v_cvt_pk_bf16_f32 v27, v30, v27
	global_store_dwordx4 v[28:29], v[24:27], off
	v_max_f32_e32 v19, 0, v19
	v_max_f32_e32 v20, 0, v20
	v_mul_f32_e32 v24, v16, v16
	v_max_f32_e32 v16, 0, v21
	v_mul_f32_e32 v21, v17, v17
	v_max_f32_e32 v17, 0, v22
	v_mul_f32_e32 v22, v18, v18
	v_max_f32_e32 v18, 0, v23
	v_mul_f32_e32 v16, v16, v16
	v_mul_f32_e32 v17, v17, v17
	v_mul_f32_e32 v18, v18, v18
	v_mul_f32_e32 v19, v19, v19
	v_mul_f32_e32 v20, v20, v20
	v_cvt_pk_bf16_f32 v16, v20, v16
	v_cvt_pk_bf16_f32 v17, v17, v18
	v_cvt_pk_bf16_f32 v18, v24, v21
	v_cvt_pk_bf16_f32 v19, v22, v19
	global_store_dwordx4 v[32:33], v[16:19], off offset:256
	s_nop 1
	v_mov_b64_e32 v[16:17], v[250:251]
	s_mov_b64 s[0:1], 0x2c0000
	v_cvt_f64_u32_e32 v[18:19], v17
	v_ldexp_f64 v[18:19], v[18:19], 32
	v_cvt_f64_u32_e32 v[16:17], v16
	v_add_f64 v[16:17], v[18:19], v[16:17]
	v_ldexp_f64 v[16:17], v[16:17], s93
	v_cvt_f32_f64_e32 v16, v[16:17]
	v_fmamk_f32 v16, v16, 0x3a000000, v189
	v_cmp_gt_f32_e32 vcc, s78, v16
	v_mul_f32_e32 v17, 0x4b800000, v16
	v_lshl_add_u64 v[18:19], v[140:141], 0, s[0:1]
	v_cndmask_b32_e32 v16, v16, v17, vcc
	v_rsq_f32_e32 v16, v16
	s_mov_b32 s0, 0x2c0000
	v_mul_f32_e32 v17, 0x45800000, v16
	v_cndmask_b32_e32 v16, v16, v17, vcc
	v_pk_mul_f32 v[8:9], v[8:9], v[16:17] op_sel_hi:[1,0]
	v_pk_mul_f32 v[12:13], v[12:13], v[16:17] op_sel_hi:[1,0]
	v_pk_mul_f32 v[10:11], v[10:11], v[16:17] op_sel_hi:[1,0]
	v_max_f32_e32 v8, 0, v8
	v_pk_mul_f32 v[14:15], v[14:15], v[16:17] op_sel_hi:[1,0]
	v_max_f32_e32 v12, 0, v12
	v_mul_f32_e32 v17, v8, v8
	v_max_f32_e32 v8, 0, v13
	v_max_f32_e32 v9, 0, v9
	v_max_f32_e32 v10, 0, v10
	v_mul_f32_e32 v12, v12, v12
	v_mul_f32_e32 v8, v8, v8
	v_mul_f32_e32 v13, v9, v9
	v_max_f32_e32 v9, 0, v14
	v_mul_f32_e32 v14, v10, v10
	v_max_f32_e32 v10, 0, v15
	v_mul_f32_e32 v9, v9, v9
	v_max_f32_e32 v11, 0, v11
	v_mul_f32_e32 v10, v10, v10
	v_cvt_pk_bf16_f32 v8, v12, v8
	v_add_co_u32_e32 v12, vcc, s0, v140
	v_pk_mul_f32 v[2:3], v[2:3], v[16:17] op_sel_hi:[1,0]
	v_pk_mul_f32 v[0:1], v[0:1], v[16:17] op_sel_hi:[1,0]
	v_mul_f32_e32 v11, v11, v11
	v_cvt_pk_bf16_f32 v9, v9, v10
	v_cvt_pk_bf16_f32 v10, v17, v13
	v_addc_co_u32_e32 v13, vcc, 0, v141, vcc
	v_pk_mul_f32 v[6:7], v[6:7], v[16:17] op_sel_hi:[1,0]
	v_pk_mul_f32 v[4:5], v[4:5], v[16:17] op_sel_hi:[1,0]
	v_max_f32_e32 v0, 0, v0
	v_max_f32_e32 v1, 0, v1
	v_max_f32_e32 v2, 0, v2
	v_cvt_pk_bf16_f32 v11, v14, v11
	global_store_dwordx4 v[12:13], v[8:11], off
	v_max_f32_e32 v3, 0, v3
	v_max_f32_e32 v4, 0, v4
	v_mul_f32_e32 v8, v0, v0
	v_max_f32_e32 v0, 0, v5
	v_mul_f32_e32 v5, v1, v1
	v_max_f32_e32 v1, 0, v6
	v_mul_f32_e32 v6, v2, v2
	v_max_f32_e32 v2, 0, v7
	v_mul_f32_e32 v0, v0, v0
	v_mul_f32_e32 v1, v1, v1
	v_mul_f32_e32 v2, v2, v2
	v_mul_f32_e32 v3, v3, v3
	s_and_b64 vcc, exec, s[8:9]
	s_mov_b32 s0, s16
	v_mul_f32_e32 v4, v4, v4
	v_cvt_pk_bf16_f32 v0, v4, v0
	v_cvt_pk_bf16_f32 v1, v1, v2
	v_cvt_pk_bf16_f32 v2, v8, v5
	v_cvt_pk_bf16_f32 v3, v6, v3
	global_store_dwordx4 v[18:19], v[0:3], off offset:256
	s_cbranch_vccz .LBB0_918
	s_waitcnt vmcnt(0)
	s_cmpk_gt_u32 s42, 0xff
	s_cbranch_scc1 .LBB0_929
	s_barrier

; #define PG8_STAGE(bufoff, gbase, voff) do { _Pragma("unroll") for (int _i = 0; _i < 2; ++_i) \
;         __builtin_amdgcn_global_load_lds((const unsigned*)((const char*)(gbase) + (voff)[_i]), (LAS unsigned*)(lds + (bufoff) + ldsw + _i * 8192), 16, 0, 0); } while (0)
; #define PG8_LDA(dst, b, h) do { _Pragma("unroll") for (int m = 0; m < 4; ++m) _Pragma("unroll") for (int k = 0; k < 2; ++k) dst[m][k] = *(const LAS bf16x8*)(lds + PG8_SA(b, h) + aoff + m * 2048 + k * 1024); } while (0)
; #define PG8_LDB(dst, b, h) do { _Pragma("unroll") for (int n = 0; n < 2; ++n) _Pragma("unroll") for (int k = 0; k < 2; ++k) dst[n][k] = *(const LAS bf16x8*)(lds + PG8_SB(b, h) + boff + n * 2048 + k * 1024); } while (0)
; #define PG8_MMA(ai, bj, At, Bt) do { __builtin_amdgcn_s_setprio(1); _Pragma("unroll") for (int m = 0; m < 4; ++m) _Pragma("unroll") for (int n = 0; n < 2; ++n) _Pragma("unroll") for (int k = 0; k < 2; ++k) \
;         acc[ai][bj][m][n] = __builtin_amdgcn_mfma_f32_16x16x32_bf16(Bt[n][k], At[m][k], acc[ai][bj][m][n], 0, 0, 0); __builtin_amdgcn_s_setprio(0); } while (0)
; #define PG8_WAIT_V(n) asm volatile("s_waitcnt vmcnt(" #n ")" ::: "memory")
; #define PG8_WAIT_L(n) asm volatile("s_waitcnt lgkmcnt(" #n ")" ::: "memory")
; #define PG8_BAR __builtin_amdgcn_s_barrier()
; #define PG8_SCHED __builtin_amdgcn_sched_barrier(0)
; template <class Epi>
; __device__ __forceinline__ void gemm_phase(const int TID, const int BID, LAS unsigned char* lds, const Gemm g, const StaticOrder& S, const Epi& E) {
;     ...
;             PG8_LDB(B0, 0, 0); PG8_SCHED; PG8_LDA(At, 0, 0); PG8_STAGE(PG8_SA(1, 1), a1 + hstepA, voffA);
;             PG8_WAIT_L(8); PG8_BAR; PG8_WAIT_L(0); PG8_MMA(0, 0, At, B0); PG8_BAR; PG8_SCHED;
;             PG8_LDB(B1, 0, 1); PG8_STAGE(PG8_SB(0, 0), b2, voffB);
;             PG8_BAR; PG8_WAIT_L(0); PG8_MMA(0, 1, At, B1); PG8_BAR;
;             PG8_LDA(At, 0, 1); PG8_STAGE(PG8_SA(0, 0), a2, voffA);
;             PG8_BAR; PG8_WAIT_L(0); PG8_MMA(1, 0, At, B0); PG8_BAR; PG8_SCHED;
;             PG8_STAGE(PG8_SB(0, 1), b2 + hstepB, voffB);
;             PG8_WAIT_V(6); PG8_BAR; PG8_MMA(1, 1, At, B1); PG8_BAR;
.LBB0_955:
	v_add_u32_e32 v68, s63, v198
	ds_read_b128 v[48:51], v68
	ds_read_b128 v[52:55], v68 offset:1024
	ds_read_b128 v[60:63], v68 offset:2048
	ds_read_b128 v[68:71], v68 offset:3072
	s_add_i32 vcc_lo, s14, 2
	s_add_u32 s16, s12, 0x80
	s_addc_u32 s15, s13, 0
	s_cmp_eq_u32 s88, s14
	s_cselect_b32 s14, s50, s16
	s_cselect_b32 s15, s51, s15
	s_cselect_b32 s17, s53, s19
	s_cselect_b32 s16, s52, s18
	v_lshl_add_u64 v[182:183], s[12:13], 0, v[166:167]
	s_add_i32 m0, s76, 0xc000
	ds_read_b128 v[144:147], v200
	ds_read_b128 v[148:151], v200 offset:1024
	ds_read_b128 v[170:173], v200 offset:2048
	ds_read_b128 v[174:177], v200 offset:3072
	ds_read_b128 v[178:181], v200 offset:4096
	ds_read_b128 v[208:211], v200 offset:5120
	ds_read_b128 v[212:215], v200 offset:6144
	ds_read_b128 v[216:219], v200 offset:7168
	global_load_lds_dwordx4 v[182:183], off
	s_add_i32 m0, s76, 0xe000
	v_lshl_add_u64 v[182:183], s[12:13], 0, v[168:169]
	global_load_lds_dwordx4 v[182:183], off
	s_waitcnt lgkmcnt(8)
	s_barrier
	s_waitcnt lgkmcnt(0)
	s_setprio 1
	v_mfma_f32_16x16x32_bf16 v[140:143], v[48:51], v[144:147], v[140:143]
	v_mfma_f32_16x16x32_bf16 v[136:139], v[60:63], v[144:147], v[136:139]
	v_mfma_f32_16x16x32_bf16 v[124:127], v[48:51], v[170:173], v[124:127]
	v_mfma_f32_16x16x32_bf16 v[120:123], v[60:63], v[170:173], v[120:123]
	v_mfma_f32_16x16x32_bf16 v[108:111], v[48:51], v[178:181], v[108:111]
	v_mfma_f32_16x16x32_bf16 v[104:107], v[60:63], v[178:181], v[104:107]
	v_mfma_f32_16x16x32_bf16 v[92:95], v[48:51], v[212:215], v[92:95]
	v_mfma_f32_16x16x32_bf16 v[88:91], v[60:63], v[212:215], v[88:91]
	v_mfma_f32_16x16x32_bf16 v[140:143], v[52:55], v[148:151], v[140:143]
	v_mfma_f32_16x16x32_bf16 v[136:139], v[68:71], v[148:151], v[136:139]
	v_mfma_f32_16x16x32_bf16 v[124:127], v[52:55], v[174:177], v[124:127]
	v_mfma_f32_16x16x32_bf16 v[120:123], v[68:71], v[174:177], v[120:123]
	v_mfma_f32_16x16x32_bf16 v[108:111], v[52:55], v[208:211], v[108:111]
	v_mfma_f32_16x16x32_bf16 v[104:107], v[68:71], v[208:211], v[104:107]
	v_mfma_f32_16x16x32_bf16 v[92:95], v[52:55], v[216:219], v[92:95]
	v_mfma_f32_16x16x32_bf16 v[88:91], v[68:71], v[216:219], v[88:91]
	s_setprio 0
	s_barrier
	v_add_u32_e32 v182, s80, v198
	s_mov_b32 m0, s0
	ds_read_b128 v[220:223], v182
	ds_read_b128 v[224:227], v182 offset:1024
	ds_read_b128 v[228:231], v182 offset:2048
	ds_read_b128 v[232:235], v182 offset:3072
	v_lshl_add_u64 v[182:183], s[16:17], 0, v[160:161]
	global_load_lds_dwordx4 v[182:183], off
	s_mov_b32 m0, s1
	v_lshl_add_u64 v[236:237], s[16:17], 0, v[158:159]
	global_load_lds_dwordx4 v[236:237], off
	s_barrier
	s_waitcnt lgkmcnt(0)
	s_setprio 1
	v_mfma_f32_16x16x32_bf16 v[132:135], v[220:223], v[144:147], v[132:135]
	v_mfma_f32_16x16x32_bf16 v[128:131], v[228:231], v[144:147], v[128:131]
	v_mfma_f32_16x16x32_bf16 v[116:119], v[220:223], v[170:173], v[116:119]
	v_mfma_f32_16x16x32_bf16 v[112:115], v[228:231], v[170:173], v[112:115]
	v_mfma_f32_16x16x32_bf16 v[100:103], v[220:223], v[178:181], v[100:103]
	v_mfma_f32_16x16x32_bf16 v[96:99], v[228:231], v[178:181], v[96:99]
	v_mfma_f32_16x16x32_bf16 v[84:87], v[220:223], v[212:215], v[84:87]
	v_mfma_f32_16x16x32_bf16 v[80:83], v[228:231], v[212:215], v[80:83]
	v_mfma_f32_16x16x32_bf16 v[132:135], v[224:227], v[148:151], v[132:135]
	v_mfma_f32_16x16x32_bf16 v[128:131], v[232:235], v[148:151], v[128:131]
	v_mfma_f32_16x16x32_bf16 v[116:119], v[224:227], v[174:177], v[116:119]
	v_mfma_f32_16x16x32_bf16 v[112:115], v[232:235], v[174:177], v[112:115]
	v_mfma_f32_16x16x32_bf16 v[100:103], v[224:227], v[208:211], v[100:103]
	v_mfma_f32_16x16x32_bf16 v[96:99], v[232:235], v[208:211], v[96:99]
	v_mfma_f32_16x16x32_bf16 v[84:87], v[224:227], v[216:219], v[84:87]
	v_mfma_f32_16x16x32_bf16 v[80:83], v[232:235], v[216:219], v[80:83]
	s_setprio 0
	s_mov_b32 m0, s76
	v_lshl_add_u64 v[238:239], s[14:15], 0, v[154:155]
	s_barrier
	ds_read_b128 v[144:147], v200 offset:16384
	ds_read_b128 v[148:151], v200 offset:17408
	ds_read_b128 v[170:173], v200 offset:18432
	ds_read_b128 v[174:177], v200 offset:19456
	ds_read_b128 v[178:181], v200 offset:20480
	ds_read_b128 v[208:211], v200 offset:21504
	ds_read_b128 v[212:215], v200 offset:22528
	ds_read_b128 v[216:219], v200 offset:23552
	global_load_lds_dwordx4 v[238:239], off
	s_mov_b32 m0, s22
	v_lshl_add_u64 v[240:241], s[14:15], 0, v[156:157]
	global_load_lds_dwordx4 v[240:241], off
	s_barrier
	s_waitcnt lgkmcnt(0)
	s_setprio 1
	v_mfma_f32_16x16x32_bf16 v[76:79], v[48:51], v[144:147], v[76:79]
	v_mfma_f32_16x16x32_bf16 v[72:75], v[60:63], v[144:147], v[72:75]
	v_mfma_f32_16x16x32_bf16 v[44:47], v[48:51], v[170:173], v[44:47]
	v_mfma_f32_16x16x32_bf16 v[40:43], v[60:63], v[170:173], v[40:43]
	v_mfma_f32_16x16x32_bf16 v[28:31], v[48:51], v[178:181], v[28:31]
	v_mfma_f32_16x16x32_bf16 v[24:27], v[60:63], v[178:181], v[24:27]
	v_mfma_f32_16x16x32_bf16 v[12:15], v[48:51], v[212:215], v[12:15]
	v_mfma_f32_16x16x32_bf16 v[8:11], v[60:63], v[212:215], v[8:11]
	v_mfma_f32_16x16x32_bf16 v[76:79], v[52:55], v[148:151], v[76:79]
	v_mfma_f32_16x16x32_bf16 v[72:75], v[68:71], v[148:151], v[72:75]
	v_mfma_f32_16x16x32_bf16 v[44:47], v[52:55], v[174:177], v[44:47]
	v_mfma_f32_16x16x32_bf16 v[40:43], v[68:71], v[174:177], v[40:43]
	v_mfma_f32_16x16x32_bf16 v[28:31], v[52:55], v[208:211], v[28:31]
	v_mfma_f32_16x16x32_bf16 v[24:27], v[68:71], v[208:211], v[24:27]
	v_mfma_f32_16x16x32_bf16 v[12:15], v[52:55], v[216:219], v[12:15]
	v_mfma_f32_16x16x32_bf16 v[8:11], v[68:71], v[216:219], v[8:11]
	s_setprio 0
	s_barrier
; #define PG8_STAGE(bufoff, gbase, voff) do { _Pragma("unroll") for (int _i = 0; _i < 2; ++_i) \
;         __builtin_amdgcn_global_load_lds((const unsigned*)((const char*)(gbase) + (voff)[_i]), (LAS unsigned*)(lds + (bufoff) + ldsw + _i * 8192), 16, 0, 0); } while (0)
; #define PG8_LDA(dst, b, h) do { _Pragma("unroll") for (int m = 0; m < 4; ++m) _Pragma("unroll") for (int k = 0; k < 2; ++k) dst[m][k] = *(const LAS bf16x8*)(lds + PG8_SA(b, h) + aoff + m * 2048 + k * 1024); } while (0)
; #define PG8_LDB(dst, b, h) do { _Pragma("unroll") for (int n = 0; n < 2; ++n) _Pragma("unroll") for (int k = 0; k < 2; ++k) dst[n][k] = *(const LAS bf16x8*)(lds + PG8_SB(b, h) + boff + n * 2048 + k * 1024); } while (0)
; #define PG8_MMA(ai, bj, At, Bt) do { __builtin_amdgcn_s_setprio(1); _Pragma("unroll") for (int m = 0; m < 4; ++m) _Pragma("unroll") for (int n = 0; n < 2; ++n) _Pragma("unroll") for (int k = 0; k < 2; ++k) \
;         acc[ai][bj][m][n] = __builtin_amdgcn_mfma_f32_16x16x32_bf16(Bt[n][k], At[m][k], acc[ai][bj][m][n], 0, 0, 0); __builtin_amdgcn_s_setprio(0); } while (0)
; #define PG8_WAIT_V(n) asm volatile("s_waitcnt vmcnt(" #n ")" ::: "memory")
; #define PG8_WAIT_L(n) asm volatile("s_waitcnt lgkmcnt(" #n ")" ::: "memory")
; #define PG8_BAR __builtin_amdgcn_s_barrier()
; #define PG8_SCHED __builtin_amdgcn_sched_barrier(0)
; template <class Epi>
; __device__ __forceinline__ void gemm_phase(const int TID, const int BID, LAS unsigned char* lds, const Gemm g, const StaticOrder& S, const Epi& E) {
;     ...
;             PG8_WAIT_V(6); PG8_BAR; PG8_MMA(1, 1, At, B1); PG8_BAR;
;             PG8_LDB(B0, 1, 0); PG8_SCHED; PG8_LDA(At, 1, 0); PG8_STAGE(PG8_SA(0, 1), a2 + hstepA, voffA);
;             PG8_WAIT_L(8); PG8_BAR; PG8_WAIT_L(0); PG8_MMA(0, 0, At, B0); PG8_BAR; PG8_SCHED;
;             PG8_LDB(B1, 1, 1); PG8_STAGE(PG8_SB(1, 0), b3, voffB);
;             PG8_BAR; PG8_WAIT_L(0); PG8_MMA(0, 1, At, B1); PG8_BAR;
;             PG8_LDA(At, 1, 1); PG8_STAGE(PG8_SA(1, 0), a3, voffA);
	s_add_u32 s16, s16, s58
	s_addc_u32 s17, s17, 0
	s_mov_b32 m0, s71
	v_lshl_add_u64 v[242:243], s[16:17], 0, v[160:161]
	global_load_lds_dwordx4 v[242:243], off
	s_mov_b32 m0, s23
	v_lshl_add_u64 v[244:245], s[16:17], 0, v[158:159]
	global_load_lds_dwordx4 v[244:245], off
	s_waitcnt vmcnt(6)
	s_barrier
	s_setprio 1
	v_mfma_f32_16x16x32_bf16 v[36:39], v[220:223], v[170:173], v[36:39]
	v_mfma_f32_16x16x32_bf16 v[32:35], v[228:231], v[170:173], v[32:35]
	v_mfma_f32_16x16x32_bf16 v[20:23], v[220:223], v[178:181], v[20:23]
	v_mfma_f32_16x16x32_bf16 v[16:19], v[228:231], v[178:181], v[16:19]
	v_mfma_f32_16x16x32_bf16 v[4:7], v[220:223], v[212:215], v[4:7]
	v_mfma_f32_16x16x32_bf16 v[0:3], v[228:231], v[212:215], v[0:3]
	v_mfma_f32_16x16x32_bf16 v[48:51], v[220:223], v[144:147], v[64:67]
	v_mfma_f32_16x16x32_bf16 v[52:55], v[228:231], v[144:147], v[56:59]
	v_mfma_f32_16x16x32_bf16 v[36:39], v[224:227], v[174:177], v[36:39]
	v_mfma_f32_16x16x32_bf16 v[32:35], v[232:235], v[174:177], v[32:35]
	v_mfma_f32_16x16x32_bf16 v[20:23], v[224:227], v[208:211], v[20:23]
	v_mfma_f32_16x16x32_bf16 v[16:19], v[232:235], v[208:211], v[16:19]
	v_mfma_f32_16x16x32_bf16 v[4:7], v[224:227], v[216:219], v[4:7]
	v_mfma_f32_16x16x32_bf16 v[0:3], v[232:235], v[216:219], v[0:3]
	v_mfma_f32_16x16x32_bf16 v[48:51], v[224:227], v[148:151], v[48:51]
	v_mfma_f32_16x16x32_bf16 v[52:55], v[232:235], v[148:151], v[52:55]
	s_setprio 0
	v_add_u32_e32 v68, s81, v198
	s_barrier
	ds_read_b128 v[56:59], v68
	ds_read_b128 v[60:63], v68 offset:1024
	ds_read_b128 v[64:67], v68 offset:2048
	ds_read_b128 v[68:71], v68 offset:3072
	s_add_u32 s14, s14, s36
	s_addc_u32 s15, s15, 0
	s_mov_b32 m0, s96
	v_lshl_add_u64 v[220:221], s[14:15], 0, v[154:155]
	ds_read_b128 v[144:147], v200 offset:32768
	ds_read_b128 v[148:151], v200 offset:33792
	ds_read_b128 v[170:173], v200 offset:34816
	ds_read_b128 v[174:177], v200 offset:35840
	ds_read_b128 v[178:181], v200 offset:36864
	ds_read_b128 v[208:211], v200 offset:37888
	ds_read_b128 v[212:215], v200 offset:38912
	ds_read_b128 v[216:219], v200 offset:39936
	global_load_lds_dwordx4 v[220:221], off
	s_mov_b32 m0, s97
	v_lshl_add_u64 v[220:221], s[14:15], 0, v[156:157]
	global_load_lds_dwordx4 v[220:221], off
	s_waitcnt lgkmcnt(8)
	s_barrier
	s_waitcnt lgkmcnt(0)
	s_setprio 1
	v_mfma_f32_16x16x32_bf16 v[140:143], v[56:59], v[144:147], v[140:143]
	v_mfma_f32_16x16x32_bf16 v[136:139], v[64:67], v[144:147], v[136:139]
	v_mfma_f32_16x16x32_bf16 v[124:127], v[56:59], v[170:173], v[124:127]
	v_mfma_f32_16x16x32_bf16 v[120:123], v[64:67], v[170:173], v[120:123]
	v_mfma_f32_16x16x32_bf16 v[108:111], v[56:59], v[178:181], v[108:111]
	v_mfma_f32_16x16x32_bf16 v[104:107], v[64:67], v[178:181], v[104:107]
	v_mfma_f32_16x16x32_bf16 v[92:95], v[56:59], v[212:215], v[92:95]
	v_mfma_f32_16x16x32_bf16 v[88:91], v[64:67], v[212:215], v[88:91]
	v_mfma_f32_16x16x32_bf16 v[140:143], v[60:63], v[148:151], v[140:143]
	v_mfma_f32_16x16x32_bf16 v[136:139], v[68:71], v[148:151], v[136:139]
	v_mfma_f32_16x16x32_bf16 v[124:127], v[60:63], v[174:177], v[124:127]
	v_mfma_f32_16x16x32_bf16 v[120:123], v[68:71], v[174:177], v[120:123]
	v_mfma_f32_16x16x32_bf16 v[108:111], v[60:63], v[208:211], v[108:111]
	v_mfma_f32_16x16x32_bf16 v[104:107], v[68:71], v[208:211], v[104:107]
	v_mfma_f32_16x16x32_bf16 v[92:95], v[60:63], v[216:219], v[92:95]
	v_mfma_f32_16x16x32_bf16 v[88:91], v[68:71], v[216:219], v[88:91]
	s_setprio 0
	s_barrier
	s_mov_b32 m0, s66
	v_add_u32_e32 v201, s87, v198
	v_lshl_add_u64 v[182:183], v[182:183], 0, s[90:91]
	ds_read_b128 v[220:223], v201
	ds_read_b128 v[224:227], v201 offset:1024
	ds_read_b128 v[228:231], v201 offset:2048
	ds_read_b128 v[232:235], v201 offset:3072
	global_load_lds_dwordx4 v[182:183], off
	s_mov_b32 m0, s92
	v_lshl_add_u64 v[182:183], v[236:237], 0, s[90:91]
	global_load_lds_dwordx4 v[182:183], off
	s_barrier
; #define PG8_STAGE(bufoff, gbase, voff) do { _Pragma("unroll") for (int _i = 0; _i < 2; ++_i) \
;         __builtin_amdgcn_global_load_lds((const unsigned*)((const char*)(gbase) + (voff)[_i]), (LAS unsigned*)(lds + (bufoff) + ldsw + _i * 8192), 16, 0, 0); } while (0)
; #define PG8_LDA(dst, b, h) do { _Pragma("unroll") for (int m = 0; m < 4; ++m) _Pragma("unroll") for (int k = 0; k < 2; ++k) dst[m][k] = *(const LAS bf16x8*)(lds + PG8_SA(b, h) + aoff + m * 2048 + k * 1024); } while (0)
; #define PG8_MMA(ai, bj, At, Bt) do { __builtin_amdgcn_s_setprio(1); _Pragma("unroll") for (int m = 0; m < 4; ++m) _Pragma("unroll") for (int n = 0; n < 2; ++n) _Pragma("unroll") for (int k = 0; k < 2; ++k) \
;         acc[ai][bj][m][n] = __builtin_amdgcn_mfma_f32_16x16x32_bf16(Bt[n][k], At[m][k], acc[ai][bj][m][n], 0, 0, 0); __builtin_amdgcn_s_setprio(0); } while (0)
; #define PG8_WAIT_V(n) asm volatile("s_waitcnt vmcnt(" #n ")" ::: "memory")
; #define PG8_WAIT_L(n) asm volatile("s_waitcnt lgkmcnt(" #n ")" ::: "memory")
; #define PG8_BAR __builtin_amdgcn_s_barrier()
; #define PG8_SCHED __builtin_amdgcn_sched_barrier(0)
; template <class Epi>
; __device__ __forceinline__ void gemm_phase(const int TID, const int BID, LAS unsigned char* lds, const Gemm g, const StaticOrder& S, const Epi& E) {
;     ...
;             PG8_LDA(At, 1, 1); PG8_STAGE(PG8_SA(1, 0), a3, voffA);
;             PG8_BAR; PG8_WAIT_L(0); PG8_MMA(1, 0, At, B0); PG8_BAR; PG8_SCHED;
;             PG8_STAGE(PG8_SB(1, 1), b3 + hstepB, voffB);
;             PG8_WAIT_V(6); PG8_BAR; PG8_MMA(1, 1, At, B1); PG8_BAR;
;         }
;     __device__ __forceinline__ void operator()(const f32x4 (&acc)[2][2][4][2], const Unit& u, int wr, int wc, int fr, int fq) const {
;         const int row0 = u.pm * BM + wr * 64 + fr, col0 = col_off + u.pn * BM + wc * 32 + 8 * fq;
;         f32x4 cs[2][2];
; #pragma unroll
;         for (int bj = 0; bj < 2; ++bj)
; #pragma unroll
;             for (int n = 0; n < 2; ++n) cs[bj][n] = colscale ? *(const f32x4*)(colscale + col0 + bj * HALF + 4 * n) : (f32x4){1.f, 1.f, 1.f, 1.f};
	s_waitcnt lgkmcnt(0)
	s_setprio 1
	v_mfma_f32_16x16x32_bf16 v[132:135], v[220:223], v[144:147], v[132:135]
	v_mfma_f32_16x16x32_bf16 v[128:131], v[228:231], v[144:147], v[128:131]
	v_mfma_f32_16x16x32_bf16 v[116:119], v[220:223], v[170:173], v[116:119]
	v_mfma_f32_16x16x32_bf16 v[112:115], v[228:231], v[170:173], v[112:115]
	v_mfma_f32_16x16x32_bf16 v[100:103], v[220:223], v[178:181], v[100:103]
	v_mfma_f32_16x16x32_bf16 v[96:99], v[228:231], v[178:181], v[96:99]
	v_mfma_f32_16x16x32_bf16 v[84:87], v[220:223], v[212:215], v[84:87]
	v_mfma_f32_16x16x32_bf16 v[80:83], v[228:231], v[212:215], v[80:83]
	v_mfma_f32_16x16x32_bf16 v[132:135], v[224:227], v[148:151], v[132:135]
	v_mfma_f32_16x16x32_bf16 v[128:131], v[232:235], v[148:151], v[128:131]
	v_mfma_f32_16x16x32_bf16 v[116:119], v[224:227], v[174:177], v[116:119]
	v_mfma_f32_16x16x32_bf16 v[112:115], v[232:235], v[174:177], v[112:115]
	v_mfma_f32_16x16x32_bf16 v[100:103], v[224:227], v[208:211], v[100:103]
	v_mfma_f32_16x16x32_bf16 v[96:99], v[232:235], v[208:211], v[96:99]
	v_mfma_f32_16x16x32_bf16 v[84:87], v[224:227], v[216:219], v[84:87]
	v_mfma_f32_16x16x32_bf16 v[80:83], v[232:235], v[216:219], v[80:83]
	s_setprio 0
	s_mov_b32 m0, s4
	v_lshl_add_u64 v[182:183], v[238:239], 0, s[90:91]
	s_barrier
	ds_read_b128 v[144:147], v200 offset:49152
	ds_read_b128 v[148:151], v200 offset:50176
	ds_read_b128 v[170:173], v200 offset:51200
	ds_read_b128 v[174:177], v200 offset:52224
	ds_read_b128 v[178:181], v200 offset:53248
	ds_read_b128 v[208:211], v200 offset:54272
	ds_read_b128 v[212:215], v200 offset:55296
	ds_read_b128 v[216:219], v200 offset:56320
	global_load_lds_dwordx4 v[182:183], off
	s_mov_b32 m0, s64
	v_lshl_add_u64 v[182:183], v[240:241], 0, s[90:91]
	global_load_lds_dwordx4 v[182:183], off
	s_barrier
	s_waitcnt lgkmcnt(0)
	s_setprio 1
	v_mfma_f32_16x16x32_bf16 v[76:79], v[56:59], v[144:147], v[76:79]
	v_mfma_f32_16x16x32_bf16 v[72:75], v[64:67], v[144:147], v[72:75]
	v_mfma_f32_16x16x32_bf16 v[44:47], v[56:59], v[170:173], v[44:47]
	v_mfma_f32_16x16x32_bf16 v[40:43], v[64:67], v[170:173], v[40:43]
	v_mfma_f32_16x16x32_bf16 v[28:31], v[56:59], v[178:181], v[28:31]
	v_mfma_f32_16x16x32_bf16 v[24:27], v[64:67], v[178:181], v[24:27]
	v_mfma_f32_16x16x32_bf16 v[12:15], v[56:59], v[212:215], v[12:15]
	v_mfma_f32_16x16x32_bf16 v[8:11], v[64:67], v[212:215], v[8:11]
	v_mfma_f32_16x16x32_bf16 v[76:79], v[60:63], v[148:151], v[76:79]
	v_mfma_f32_16x16x32_bf16 v[72:75], v[68:71], v[148:151], v[72:75]
	v_mfma_f32_16x16x32_bf16 v[44:47], v[60:63], v[174:177], v[44:47]
	v_mfma_f32_16x16x32_bf16 v[40:43], v[68:71], v[174:177], v[40:43]
	v_mfma_f32_16x16x32_bf16 v[28:31], v[60:63], v[208:211], v[28:31]
	v_mfma_f32_16x16x32_bf16 v[24:27], v[68:71], v[208:211], v[24:27]
	v_mfma_f32_16x16x32_bf16 v[12:15], v[60:63], v[216:219], v[12:15]
	v_mfma_f32_16x16x32_bf16 v[8:11], v[68:71], v[216:219], v[8:11]
	s_setprio 0
	s_barrier
	s_mov_b32 m0, s74
	v_lshl_add_u64 v[56:57], v[242:243], 0, s[90:91]
	global_load_lds_dwordx4 v[56:57], off
	s_mov_b32 m0, s95
	v_lshl_add_u64 v[56:57], v[244:245], 0, s[90:91]
	global_load_lds_dwordx4 v[56:57], off
	s_waitcnt vmcnt(6)
	s_barrier
	s_setprio 1
	v_mfma_f32_16x16x32_bf16 v[48:51], v[220:223], v[144:147], v[48:51]
	v_mfma_f32_16x16x32_bf16 v[64:67], v[224:227], v[148:151], v[48:51]
	v_mfma_f32_16x16x32_bf16 v[48:51], v[228:231], v[144:147], v[52:55]
	v_mfma_f32_16x16x32_bf16 v[36:39], v[220:223], v[170:173], v[36:39]
	v_mfma_f32_16x16x32_bf16 v[32:35], v[228:231], v[170:173], v[32:35]
	v_mfma_f32_16x16x32_bf16 v[20:23], v[220:223], v[178:181], v[20:23]
	v_mfma_f32_16x16x32_bf16 v[16:19], v[228:231], v[178:181], v[16:19]
	v_mfma_f32_16x16x32_bf16 v[4:7], v[220:223], v[212:215], v[4:7]
	v_mfma_f32_16x16x32_bf16 v[0:3], v[228:231], v[212:215], v[0:3]
	v_mfma_f32_16x16x32_bf16 v[56:59], v[232:235], v[148:151], v[48:51]
	v_mfma_f32_16x16x32_bf16 v[36:39], v[224:227], v[174:177], v[36:39]
	v_mfma_f32_16x16x32_bf16 v[32:35], v[232:235], v[174:177], v[32:35]
	v_mfma_f32_16x16x32_bf16 v[20:23], v[224:227], v[208:211], v[20:23]
	v_mfma_f32_16x16x32_bf16 v[16:19], v[232:235], v[208:211], v[16:19]
	v_mfma_f32_16x16x32_bf16 v[4:7], v[224:227], v[216:219], v[4:7]
	v_mfma_f32_16x16x32_bf16 v[0:3], v[232:235], v[216:219], v[0:3]
	s_setprio 0
	s_add_u32 s12, s12, 0x100
	s_addc_u32 s13, s13, 0
	s_add_u32 s18, s18, 0x100
	s_addc_u32 s19, s19, 0
	s_cmp_ge_u32 vcc_lo, s57
	s_mov_b32 s14, vcc_lo
	s_barrier
	s_cbranch_scc0 .LBB0_955
	v_lshl_add_u32 v174, s55, 8, v199
	v_ashrrev_i32_e32 v175, 31, v174
	v_mov_b32_e32 v60, 1.0
	v_cndmask_b32_e64 v48, 0, 1, s[40:41]
	v_lshl_add_u64 v[144:145], v[174:175], 2, s[26:27]
	v_cmp_ne_u32_e64 s[12:13], 1, v48
	s_andn2_b64 vcc, exec, s[40:41]
	v_mov_b32_e32 v68, 1.0
	v_mov_b32_e32 v69, v60
	v_mov_b32_e32 v70, 1.0
	v_mov_b32_e32 v71, 1.0
	s_cbranch_vccnz .LBB0_958
	global_load_dwordx4 v[68:71], v[144:145], off
